# merged 4-phase GEMM K-loops (reads-first order, own VGPR for the second A-fragment LDS base, 1 wait state after every M0 write) + prologue fix: first 8 tile DMAs retired by every wave before the first
# baseline (speedup 1.0000x reference)
; #define PG8_STAGE(bufoff, gbase, voff) do { _Pragma("unroll") for (int _i = 0; _i < 2; ++_i) \
;         __builtin_amdgcn_global_load_lds((const unsigned*)((const char*)(gbase) + (voff)[_i]), (LAS unsigned*)(lds + (bufoff) + ldsw + _i * 8192), 16, 0, 0); } while (0)
; #define PG8_WAIT_V(n) asm volatile("s_waitcnt vmcnt(" #n ")" ::: "memory")
; #define PG8_BAR __builtin_amdgcn_s_barrier()
; template <class Epi>
; __device__ __forceinline__ void gemm_phase(LAS unsigned char* lds, const Gemm g, const StaticOrder& S, const Epi& E) {
;     ...
;     for (int i = 0; i < 2; ++i) { int R, C; stage_rc(tid * 16 + i * 8192, R, C); const int Rb = Epi::PERM ? ((R & ~31) + perm32(R & 31)) : R;
;         voffA[i] = (unsigned)(R * lda + C) * 2u; voffB[i] = (unsigned)(Rb * K + C) * 2u; }
;     const size_t kstep = (size_t)(BK * 2);
;     const size_t hstepA = (size_t)HALF * lda * 2, hstepB = (size_t)HALF * K * 2;
;     const size_t tstepA = 2 * hstepA, tstepB = 2 * hstepB;
;     const unsigned ldsw = (unsigned)wid * 1024u;
;     const int aoff = lds_byte(wr * 64 + fr, fq * 8), boff = lds_byte(wc * 32 + fr, fq * 8);
;     ...
;     Unit cur, nxt; int ui = 0;
;     if (!S.next(0, cur)) return;
;     f32x4 acc[2][2][4][2];
; #pragma unroll
;     for (int a = 0; a < 2; ++a)
; #pragma unroll
;         for (int b = 0; b < 2; ++b)
; #pragma unroll
;             for (int m = 0; m < 4; ++m)
; #pragma unroll
;                 for (int n = 0; n < 2; ++n) acc[a][b][m][n] = (f32x4){0.f, 0.f, 0.f, 0.f};
;     bf16x8 At[4][2], B0[2][2], B1[2][2];
;     const char* cA = (const char*)g.A + (size_t)cur.pm * tstepA + (size_t)cur.kt0 * kstep; const char* cB = (const char*)g.Bt + (size_t)cur.pn * tstepB + (size_t)cur.kt0 * kstep;
;     PG8_STAGE(PG8_SB(0, 0), cB, voffB); PG8_STAGE(PG8_SA(0, 0), cA, voffA); PG8_STAGE(PG8_SB(0, 1), cB + hstepB, voffB); PG8_STAGE(PG8_SA(0, 1), cA + hstepA, voffA);
;     if (wr == 1) PG8_BAR;
;     PG8_WAIT_V(4); PG8_BAR;
;     PG8_STAGE(PG8_SB(1, 0), cB + kstep, voffB); PG8_STAGE(PG8_SA(1, 0), cA + kstep, voffA); PG8_STAGE(PG8_SB(1, 1), cB + hstepB + kstep, voffB);
;     PG8_WAIT_V(6); PG8_BAR;
.LBB0_110:
	s_lshl_b32 s7, s7, 5
	s_mov_b64 s[28:29], 0x80
	s_and_b32 s7, s7, 0x60
	s_add_i32 m0, s68, 0x18000
	v_lshl_add_u64 v[6:7], v[6:7], 0, s[28:29]
	s_lshl_b32 s9, s6, 13
	s_lshl_b32 s33, s7, 7
	s_waitcnt vmcnt(0)
	s_barrier
	global_load_lds_dwordx4 v[6:7], off
	v_lshl_add_u64 v[4:5], v[4:5], 0, s[28:29]
	s_add_i32 m0, s68, 0x1a000
	s_add_i32 s73, s68, 0x8000
	s_add_i32 s74, s68, 0xa000
	global_load_lds_dwordx4 v[4:5], off
	v_lshl_add_u64 v[2:3], v[2:3], 0, s[28:29]
	s_mov_b32 m0, s73
	s_add_u32 s30, s64, 0x40080
	global_load_lds_dwordx4 v[2:3], off
	v_lshl_add_u64 v[0:1], v[0:1], 0, s[28:29]
	s_mov_b32 m0, s74
	s_addc_u32 s31, s65, 0
	global_load_lds_dwordx4 v[0:1], off
	s_add_i32 m0, s68, 0x1c000
	v_lshl_add_u64 v[0:1], s[30:31], 0, v[132:133]
	global_load_lds_dwordx4 v[0:1], off
	v_lshl_add_u64 v[0:1], s[30:31], 0, v[136:137]
	s_add_i32 m0, s68, 0x1e000
	v_lshlrev_b32_e32 v2, 2, v129
	global_load_lds_dwordx4 v[0:1], off
	v_and_b32_e32 v0, 15, v129
	v_lshl_or_b32 v151, s6, 6, v0
	v_lshlrev_b32_e32 v1, 1, v11
	v_lshlrev_b32_e32 v3, 6, v129
	s_movk_i32 s6, 0x3c0
	v_lshl_or_b32 v0, v0, 6, v1
	v_and_b32_e32 v2, 32, v2
	v_and_or_b32 v1, v3, s6, v1
	v_bitop3_b32 v152, s33, v1, v2 bitop3:0xf6
	v_lshlrev_b32_e32 v1, 8, v129
	v_bitop3_b32 v0, v0, s9, v2 bitop3:0xde
	v_and_b32_e32 v1, 0x38000, v1
	v_lshlrev_b32_e32 v2, 11, v10
	v_or3_b32 v1, v8, v1, v2
	v_add_u32_e32 v138, v1, v9
	v_lshlrev_b32_e32 v1, 4, v12
	s_waitcnt vmcnt(6)
	v_and_b32_e32 v1, 0x78000, v1
	v_or3_b32 v1, v8, v1, v2
	s_add_i32 s78, 0, 0x10000
	s_add_i32 s79, 0, 0x14000
	s_ashr_i32 s75, s14, 31
	s_mov_b32 s76, s14
	s_ashr_i32 s77, s2, 31
	v_or_b32_e32 v153, s7, v11
	v_mov_b32_e32 v139, v133
	v_add_u32_e32 v140, v1, v9
	v_mov_b32_e32 v141, v133
	v_mov_b64_e32 v[142:143], 0x2d6
	v_mov_b64_e32 v[144:145], 0x2d5
	v_add_u32_e32 v154, s78, v152
	v_add_u32_e32 v155, 0, v0
	v_add_u32_e32 v156, s79, v152
	s_movk_i32 s80, 0x60f
	s_movk_i32 s81, 0x1600
	s_barrier
	s_branch .LBB0_112

; #define PG8_STAGE(bufoff, gbase, voff) do { _Pragma("unroll") for (int _i = 0; _i < 2; ++_i) \
;         __builtin_amdgcn_global_load_lds((const unsigned*)((const char*)(gbase) + (voff)[_i]), (LAS unsigned*)(lds + (bufoff) + ldsw + _i * 8192), 16, 0, 0); } while (0)
; #define PG8_LDA(dst, b, h) do { _Pragma("unroll") for (int m = 0; m < 4; ++m) _Pragma("unroll") for (int k = 0; k < 2; ++k) dst[m][k] = *(const LAS bf16x8*)(lds + PG8_SA(b, h) + aoff + m * 2048 + k * 1024); } while (0)
; #define PG8_LDB(dst, b, h) do { _Pragma("unroll") for (int n = 0; n < 2; ++n) _Pragma("unroll") for (int k = 0; k < 2; ++k) dst[n][k] = *(const LAS bf16x8*)(lds + PG8_SB(b, h) + boff + n * 2048 + k * 1024); } while (0)
; #define PG8_MMA(ai, bj, At, Bt) do { __builtin_amdgcn_s_setprio(1); _Pragma("unroll") for (int m = 0; m < 4; ++m) _Pragma("unroll") for (int n = 0; n < 2; ++n) _Pragma("unroll") for (int k = 0; k < 2; ++k) \
;         acc[ai][bj][m][n] = __builtin_amdgcn_mfma_f32_16x16x32_bf16(Bt[n][k], At[m][k], acc[ai][bj][m][n], 0, 0, 0); __builtin_amdgcn_s_setprio(0); } while (0)
; #define PG8_WAIT_V(n) asm volatile("s_waitcnt vmcnt(" #n ")" ::: "memory")
; #define PG8_WAIT_L(n) asm volatile("s_waitcnt lgkmcnt(" #n ")" ::: "memory")
; template <class Epi>
; __device__ __forceinline__ void gemm_phase(LAS unsigned char* lds, const Gemm g, const StaticOrder& S, const Epi& E) {
;     ...
;         for (int t = 0; t < nt; t += 2) {
;             const bool last = (t == nt - 2);
;             const char* a1 = cA + (size_t)(t + 1) * kstep;
;             const char* a2 = last ? nA : cA + (size_t)(t + 2) * kstep; const char* b2 = last ? nB : cB + (size_t)(t + 2) * kstep;
;             const char* a3 = a2 + kstep; const char* b3 = b2 + kstep;
;             PG8_LDB(B0, 0, 0); PG8_SCHED; PG8_LDA(At, 0, 0); PG8_STAGE(PG8_SA(1, 1), a1 + hstepA, voffA);
;             PG8_WAIT_L(8); PG8_BAR; PG8_WAIT_L(0); PG8_MMA(0, 0, At, B0); PG8_BAR; PG8_SCHED;
;             PG8_LDB(B1, 0, 1); PG8_STAGE(PG8_SB(0, 0), b2, voffB);
;             PG8_BAR; PG8_WAIT_L(0); PG8_MMA(0, 1, At, B1); PG8_BAR;
;             PG8_LDA(At, 0, 1); PG8_STAGE(PG8_SA(0, 0), a2, voffA);
;             PG8_BAR; PG8_WAIT_L(0); PG8_MMA(1, 0, At, B0); PG8_BAR; PG8_SCHED;
;             PG8_STAGE(PG8_SB(0, 1), b2 + hstepB, voffB);
;             PG8_WAIT_V(6); PG8_BAR; PG8_MMA(1, 1, At, B1); PG8_BAR;
.LBB0_119:
	s_add_u32 s55, s62, 0xfffc0080
	s_addc_u32 s61, s63, -1
	s_cmp_eq_u32 s33, 12
	s_cselect_b32 s67, s57, s61
	s_cselect_b32 s66, s56, s55
	s_cselect_b32 s65, s59, s31
	s_cselect_b32 s64, s58, s9
	ds_read_b128 v[146:149], v154
	ds_read_b128 v[158:161], v154 offset:1024
	ds_read_b128 v[162:165], v154 offset:2048
	ds_read_b128 v[166:169], v154 offset:3072
	ds_read_b128 v[170:173], v155
	ds_read_b128 v[174:177], v155 offset:1024
	ds_read_b128 v[178:181], v155 offset:2048
	ds_read_b128 v[182:185], v155 offset:3072
	ds_read_b128 v[186:189], v155 offset:4096
	ds_read_b128 v[190:193], v155 offset:5120
	ds_read_b128 v[194:197], v155 offset:6144
	ds_read_b128 v[198:201], v155 offset:7168
	ds_read_b128 v[202:205], v156
	ds_read_b128 v[206:209], v156 offset:1024
	ds_read_b128 v[210:213], v156 offset:2048
	ds_read_b128 v[214:217], v156 offset:3072
	v_lshl_add_u64 v[242:243], s[62:63], 0, v[138:139]
	s_add_i32 m0, s68, 0xc000
	s_nop 0
	global_load_lds_dwordx4 v[242:243], off
	v_lshl_add_u64 v[242:243], s[62:63], 0, v[140:141]
	s_add_i32 m0, s68, 0xe000
	s_nop 0
	global_load_lds_dwordx4 v[242:243], off
	s_waitcnt vmcnt(8) lgkmcnt(0)
	s_barrier
	v_mfma_f32_16x16x32_bf16 v[124:127], v[146:149], v[170:173], v[124:127]
	v_mfma_f32_16x16x32_bf16 v[120:123], v[162:165], v[170:173], v[120:123]
	v_mfma_f32_16x16x32_bf16 v[108:111], v[146:149], v[178:181], v[108:111]
	v_mfma_f32_16x16x32_bf16 v[104:107], v[162:165], v[178:181], v[104:107]
	v_mfma_f32_16x16x32_bf16 v[92:95], v[146:149], v[186:189], v[92:95]
	v_mfma_f32_16x16x32_bf16 v[88:91], v[162:165], v[186:189], v[88:91]
	v_mfma_f32_16x16x32_bf16 v[76:79], v[146:149], v[194:197], v[76:79]
	v_mfma_f32_16x16x32_bf16 v[72:75], v[162:165], v[194:197], v[72:75]
	v_mfma_f32_16x16x32_bf16 v[124:127], v[158:161], v[174:177], v[124:127]
	v_mfma_f32_16x16x32_bf16 v[120:123], v[166:169], v[174:177], v[120:123]
	v_mfma_f32_16x16x32_bf16 v[108:111], v[158:161], v[182:185], v[108:111]
	v_mfma_f32_16x16x32_bf16 v[104:107], v[166:169], v[182:185], v[104:107]
	v_mfma_f32_16x16x32_bf16 v[92:95], v[158:161], v[190:193], v[92:95]
	v_mfma_f32_16x16x32_bf16 v[88:91], v[166:169], v[190:193], v[88:91]
	v_mfma_f32_16x16x32_bf16 v[76:79], v[158:161], v[198:201], v[76:79]
	v_mfma_f32_16x16x32_bf16 v[72:75], v[166:169], v[198:201], v[72:75]
	v_mfma_f32_16x16x32_bf16 v[116:119], v[202:205], v[170:173], v[116:119]
	v_mfma_f32_16x16x32_bf16 v[112:115], v[210:213], v[170:173], v[112:115]
	v_mfma_f32_16x16x32_bf16 v[100:103], v[202:205], v[178:181], v[100:103]
	v_mfma_f32_16x16x32_bf16 v[96:99], v[210:213], v[178:181], v[96:99]
	v_mfma_f32_16x16x32_bf16 v[84:87], v[202:205], v[186:189], v[84:87]
	v_mfma_f32_16x16x32_bf16 v[80:83], v[210:213], v[186:189], v[80:83]
	v_mfma_f32_16x16x32_bf16 v[68:71], v[202:205], v[194:197], v[68:71]
	v_mfma_f32_16x16x32_bf16 v[64:67], v[210:213], v[194:197], v[64:67]
	v_mfma_f32_16x16x32_bf16 v[116:119], v[206:209], v[174:177], v[116:119]
	v_mfma_f32_16x16x32_bf16 v[112:115], v[214:217], v[174:177], v[112:115]
	v_mfma_f32_16x16x32_bf16 v[100:103], v[206:209], v[182:185], v[100:103]
	v_mfma_f32_16x16x32_bf16 v[96:99], v[214:217], v[182:185], v[96:99]
	v_mfma_f32_16x16x32_bf16 v[84:87], v[206:209], v[190:193], v[84:87]
	v_mfma_f32_16x16x32_bf16 v[80:83], v[214:217], v[190:193], v[80:83]
	v_mfma_f32_16x16x32_bf16 v[68:71], v[206:209], v[198:201], v[68:71]
	v_mfma_f32_16x16x32_bf16 v[64:67], v[214:217], v[198:201], v[64:67]
	s_barrier
	ds_read_b128 v[170:173], v155 offset:16384
	ds_read_b128 v[174:177], v155 offset:17408
	ds_read_b128 v[178:181], v155 offset:18432
	ds_read_b128 v[182:185], v155 offset:19456
	ds_read_b128 v[186:189], v155 offset:20480
	ds_read_b128 v[190:193], v155 offset:21504
	ds_read_b128 v[194:197], v155 offset:22528
	ds_read_b128 v[198:201], v155 offset:23552
	s_add_i32 s55, s78, s35
	v_lshl_add_u64 v[218:219], s[64:65], 0, v[132:133]
	s_mov_b32 m0, s55
	s_nop 0
	global_load_lds_dwordx4 v[218:219], off
	v_lshl_add_u64 v[220:221], s[64:65], 0, v[136:137]
	s_add_i32 m0, s55, 0x2000
	s_nop 0
	global_load_lds_dwordx4 v[220:221], off
	s_mov_b32 m0, s68
	v_lshl_add_u64 v[222:223], s[66:67], 0, v[130:131]
	global_load_lds_dwordx4 v[222:223], off
	v_lshl_add_u64 v[224:225], s[66:67], 0, v[134:135]
	s_mov_b32 m0, s69
	s_nop 0
	global_load_lds_dwordx4 v[224:225], off
	s_add_u32 s82, s64, 0x40000
	s_addc_u32 s83, s65, 0
	s_add_i32 s55, s79, s35
	v_lshl_add_u64 v[240:241], s[82:83], 0, v[132:133]
	s_mov_b32 m0, s55
	s_nop 0
	global_load_lds_dwordx4 v[240:241], off
	v_lshl_add_u64 v[240:241], s[82:83], 0, v[136:137]
	s_add_i32 m0, s55, 0x2000
	s_nop 0
	global_load_lds_dwordx4 v[240:241], off
	s_waitcnt vmcnt(8) lgkmcnt(0)
	s_barrier
; #define PG8_STAGE(bufoff, gbase, voff) do { _Pragma("unroll") for (int _i = 0; _i < 2; ++_i) \
;         __builtin_amdgcn_global_load_lds((const unsigned*)((const char*)(gbase) + (voff)[_i]), (LAS unsigned*)(lds + (bufoff) + ldsw + _i * 8192), 16, 0, 0); } while (0)
; #define PG8_LDA(dst, b, h) do { _Pragma("unroll") for (int m = 0; m < 4; ++m) _Pragma("unroll") for (int k = 0; k < 2; ++k) dst[m][k] = *(const LAS bf16x8*)(lds + PG8_SA(b, h) + aoff + m * 2048 + k * 1024); } while (0)
; #define PG8_LDB(dst, b, h) do { _Pragma("unroll") for (int n = 0; n < 2; ++n) _Pragma("unroll") for (int k = 0; k < 2; ++k) dst[n][k] = *(const LAS bf16x8*)(lds + PG8_SB(b, h) + boff + n * 2048 + k * 1024); } while (0)
; #define PG8_MMA(ai, bj, At, Bt) do { __builtin_amdgcn_s_setprio(1); _Pragma("unroll") for (int m = 0; m < 4; ++m) _Pragma("unroll") for (int n = 0; n < 2; ++n) _Pragma("unroll") for (int k = 0; k < 2; ++k) \
;         acc[ai][bj][m][n] = __builtin_amdgcn_mfma_f32_16x16x32_bf16(Bt[n][k], At[m][k], acc[ai][bj][m][n], 0, 0, 0); __builtin_amdgcn_s_setprio(0); } while (0)
; #define PG8_WAIT_V(n) asm volatile("s_waitcnt vmcnt(" #n ")" ::: "memory")
; #define PG8_WAIT_L(n) asm volatile("s_waitcnt lgkmcnt(" #n ")" ::: "memory")
; #define PG8_BAR __builtin_amdgcn_s_barrier()
; #define PG8_SCHED __builtin_amdgcn_sched_barrier(0)
; template <class Epi>
; __device__ __forceinline__ void gemm_phase(LAS unsigned char* lds, const Gemm g, const StaticOrder& S, const Epi& E) {
;     ...
;             PG8_BAR; PG8_WAIT_L(0); PG8_MMA(1, 0, At, B0); PG8_BAR; PG8_SCHED;
;             PG8_STAGE(PG8_SB(0, 1), b2 + hstepB, voffB);
;             PG8_WAIT_V(6); PG8_BAR; PG8_MMA(1, 1, At, B1); PG8_BAR;
;             PG8_LDB(B0, 1, 0); PG8_SCHED; PG8_LDA(At, 1, 0); PG8_STAGE(PG8_SA(0, 1), a2 + hstepA, voffA);
;             PG8_WAIT_L(8); PG8_BAR; PG8_WAIT_L(0); PG8_MMA(0, 0, At, B0); PG8_BAR; PG8_SCHED;
;             PG8_LDB(B1, 1, 1); PG8_STAGE(PG8_SB(1, 0), b3, voffB);
;             PG8_BAR; PG8_WAIT_L(0); PG8_MMA(0, 1, At, B1); PG8_BAR;
	v_mfma_f32_16x16x32_bf16 v[60:63], v[146:149], v[170:173], v[60:63]
	v_mfma_f32_16x16x32_bf16 v[56:59], v[162:165], v[170:173], v[56:59]
	v_mfma_f32_16x16x32_bf16 v[44:47], v[146:149], v[178:181], v[44:47]
	v_mfma_f32_16x16x32_bf16 v[40:43], v[162:165], v[178:181], v[40:43]
	v_mfma_f32_16x16x32_bf16 v[28:31], v[146:149], v[186:189], v[28:31]
	v_mfma_f32_16x16x32_bf16 v[24:27], v[162:165], v[186:189], v[24:27]
	v_mfma_f32_16x16x32_bf16 v[12:15], v[146:149], v[194:197], v[12:15]
	v_mfma_f32_16x16x32_bf16 v[8:11], v[162:165], v[194:197], v[8:11]
	v_mfma_f32_16x16x32_bf16 v[60:63], v[158:161], v[174:177], v[60:63]
	v_mfma_f32_16x16x32_bf16 v[56:59], v[166:169], v[174:177], v[56:59]
	v_mfma_f32_16x16x32_bf16 v[44:47], v[158:161], v[182:185], v[44:47]
	v_mfma_f32_16x16x32_bf16 v[40:43], v[166:169], v[182:185], v[40:43]
	v_mfma_f32_16x16x32_bf16 v[28:31], v[158:161], v[190:193], v[28:31]
	v_mfma_f32_16x16x32_bf16 v[24:27], v[166:169], v[190:193], v[24:27]
	v_mfma_f32_16x16x32_bf16 v[12:15], v[158:161], v[198:201], v[12:15]
	v_mfma_f32_16x16x32_bf16 v[8:11], v[166:169], v[198:201], v[8:11]
	v_mfma_f32_16x16x32_bf16 v[52:55], v[202:205], v[170:173], v[52:55]
	v_mfma_f32_16x16x32_bf16 v[48:51], v[210:213], v[170:173], v[48:51]
	v_mfma_f32_16x16x32_bf16 v[36:39], v[202:205], v[178:181], v[36:39]
	v_mfma_f32_16x16x32_bf16 v[32:35], v[210:213], v[178:181], v[32:35]
	v_mfma_f32_16x16x32_bf16 v[20:23], v[202:205], v[186:189], v[20:23]
	v_mfma_f32_16x16x32_bf16 v[16:19], v[210:213], v[186:189], v[16:19]
	v_mfma_f32_16x16x32_bf16 v[4:7], v[202:205], v[194:197], v[4:7]
	v_mfma_f32_16x16x32_bf16 v[0:3], v[210:213], v[194:197], v[0:3]
	v_mfma_f32_16x16x32_bf16 v[52:55], v[206:209], v[174:177], v[52:55]
	v_mfma_f32_16x16x32_bf16 v[48:51], v[214:217], v[174:177], v[48:51]
	v_mfma_f32_16x16x32_bf16 v[36:39], v[206:209], v[182:185], v[36:39]
	v_mfma_f32_16x16x32_bf16 v[32:35], v[214:217], v[182:185], v[32:35]
	v_mfma_f32_16x16x32_bf16 v[20:23], v[206:209], v[190:193], v[20:23]
	v_mfma_f32_16x16x32_bf16 v[16:19], v[214:217], v[190:193], v[16:19]
	v_mfma_f32_16x16x32_bf16 v[4:7], v[206:209], v[198:201], v[4:7]
	v_mfma_f32_16x16x32_bf16 v[0:3], v[214:217], v[198:201], v[0:3]
	s_barrier
	s_add_i32 s55, 0, 0x18000
	v_add_u32_e32 v157, s55, v152
	ds_read_b128 v[146:149], v157
	ds_read_b128 v[158:161], v157 offset:1024
	ds_read_b128 v[162:165], v157 offset:2048
	ds_read_b128 v[166:169], v157 offset:3072
	ds_read_b128 v[170:173], v155 offset:32768
	ds_read_b128 v[174:177], v155 offset:33792
	ds_read_b128 v[178:181], v155 offset:34816
	ds_read_b128 v[182:185], v155 offset:35840
	ds_read_b128 v[186:189], v155 offset:36864
	ds_read_b128 v[190:193], v155 offset:37888
	ds_read_b128 v[194:197], v155 offset:38912
	ds_read_b128 v[198:201], v155 offset:39936
	s_add_i32 s98, 0, 0x1c000
	v_add_u32_e32 v246, s98, v152
	ds_read_b128 v[202:205], v246
	ds_read_b128 v[206:209], v246 offset:1024
	ds_read_b128 v[210:213], v246 offset:2048
	ds_read_b128 v[214:217], v246 offset:3072
	s_add_u32 s66, s66, 0x40000
	s_addc_u32 s67, s67, 0
	s_mov_b32 m0, s70
	v_lshl_add_u64 v[244:245], s[66:67], 0, v[130:131]
	global_load_lds_dwordx4 v[244:245], off
	v_lshl_add_u64 v[244:245], s[66:67], 0, v[134:135]
	s_mov_b32 m0, s71
	s_nop 0
	global_load_lds_dwordx4 v[244:245], off
	s_waitcnt vmcnt(8) lgkmcnt(0)
	s_barrier
	v_mfma_f32_16x16x32_bf16 v[124:127], v[146:149], v[170:173], v[124:127]
	v_mfma_f32_16x16x32_bf16 v[120:123], v[162:165], v[170:173], v[120:123]
	v_mfma_f32_16x16x32_bf16 v[108:111], v[146:149], v[178:181], v[108:111]
	v_mfma_f32_16x16x32_bf16 v[104:107], v[162:165], v[178:181], v[104:107]
	v_mfma_f32_16x16x32_bf16 v[92:95], v[146:149], v[186:189], v[92:95]
	v_mfma_f32_16x16x32_bf16 v[88:91], v[162:165], v[186:189], v[88:91]
	v_mfma_f32_16x16x32_bf16 v[76:79], v[146:149], v[194:197], v[76:79]
	v_mfma_f32_16x16x32_bf16 v[72:75], v[162:165], v[194:197], v[72:75]
	v_mfma_f32_16x16x32_bf16 v[124:127], v[158:161], v[174:177], v[124:127]
	v_mfma_f32_16x16x32_bf16 v[120:123], v[166:169], v[174:177], v[120:123]
	v_mfma_f32_16x16x32_bf16 v[108:111], v[158:161], v[182:185], v[108:111]
	v_mfma_f32_16x16x32_bf16 v[104:107], v[166:169], v[182:185], v[104:107]
	v_mfma_f32_16x16x32_bf16 v[92:95], v[158:161], v[190:193], v[92:95]
	v_mfma_f32_16x16x32_bf16 v[88:91], v[166:169], v[190:193], v[88:91]
	v_mfma_f32_16x16x32_bf16 v[76:79], v[158:161], v[198:201], v[76:79]
	v_mfma_f32_16x16x32_bf16 v[72:75], v[166:169], v[198:201], v[72:75]
	v_mfma_f32_16x16x32_bf16 v[116:119], v[202:205], v[170:173], v[116:119]
	v_mfma_f32_16x16x32_bf16 v[112:115], v[210:213], v[170:173], v[112:115]
	v_mfma_f32_16x16x32_bf16 v[100:103], v[202:205], v[178:181], v[100:103]
	v_mfma_f32_16x16x32_bf16 v[96:99], v[210:213], v[178:181], v[96:99]
	v_mfma_f32_16x16x32_bf16 v[84:87], v[202:205], v[186:189], v[84:87]
	v_mfma_f32_16x16x32_bf16 v[80:83], v[210:213], v[186:189], v[80:83]
	v_mfma_f32_16x16x32_bf16 v[68:71], v[202:205], v[194:197], v[68:71]
	v_mfma_f32_16x16x32_bf16 v[64:67], v[210:213], v[194:197], v[64:67]
	v_mfma_f32_16x16x32_bf16 v[116:119], v[206:209], v[174:177], v[116:119]
	v_mfma_f32_16x16x32_bf16 v[112:115], v[214:217], v[174:177], v[112:115]
	v_mfma_f32_16x16x32_bf16 v[100:103], v[206:209], v[182:185], v[100:103]
	v_mfma_f32_16x16x32_bf16 v[96:99], v[214:217], v[182:185], v[96:99]
	v_mfma_f32_16x16x32_bf16 v[84:87], v[206:209], v[190:193], v[84:87]
	v_mfma_f32_16x16x32_bf16 v[80:83], v[214:217], v[190:193], v[80:83]
	v_mfma_f32_16x16x32_bf16 v[68:71], v[206:209], v[198:201], v[68:71]
	v_mfma_f32_16x16x32_bf16 v[64:67], v[214:217], v[198:201], v[64:67]
	s_barrier
; __device__ __forceinline__ float gelu_t(float x) { return x * __builtin_amdgcn_rcpf(1.f + __expf(-1.5957691216057308f * (x + 0.044715f * x * x * x))); }
; #define PG8_STAGE(bufoff, gbase, voff) do { _Pragma("unroll") for (int _i = 0; _i < 2; ++_i) \
;         __builtin_amdgcn_global_load_lds((const unsigned*)((const char*)(gbase) + (voff)[_i]), (LAS unsigned*)(lds + (bufoff) + ldsw + _i * 8192), 16, 0, 0); } while (0)
; #define PG8_LDA(dst, b, h) do { _Pragma("unroll") for (int m = 0; m < 4; ++m) _Pragma("unroll") for (int k = 0; k < 2; ++k) dst[m][k] = *(const LAS bf16x8*)(lds + PG8_SA(b, h) + aoff + m * 2048 + k * 1024); } while (0)
; #define PG8_LDB(dst, b, h) do { _Pragma("unroll") for (int n = 0; n < 2; ++n) _Pragma("unroll") for (int k = 0; k < 2; ++k) dst[n][k] = *(const LAS bf16x8*)(lds + PG8_SB(b, h) + boff + n * 2048 + k * 1024); } while (0)
; #define PG8_WAIT_V(n) asm volatile("s_waitcnt vmcnt(" #n ")" ::: "memory")
; #define PG8_WAIT_L(n) asm volatile("s_waitcnt lgkmcnt(" #n ")" ::: "memory")
; #define PG8_BAR __builtin_amdgcn_s_barrier()
; #define PG8_SCHED __builtin_amdgcn_sched_barrier(0)
;     __device__ __forceinline__ void operator()(const f32x4 (&acc)[2][2][4][2], const Unit& u, int wr, int wc, int fr, int fq) const {
;     ...
; #pragma unroll
;         for (int ai = 0; ai < 2; ++ai)
; #pragma unroll
;             for (int m = 0; m < 4; ++m) { const int row = row0 + ai * HALF + m * 16; u16* rowp = O + (size_t)row * ldc + col0;
; #pragma unroll
;                 for (int bj = 0; bj < 2; ++bj) { f32x4 v0 = acc[ai][bj][m][0], v1 = acc[ai][bj][m][1];
;                     if (col0 + bj * HALF >= gelu_from) { v0 = (f32x4){gelu_t(v0.x), gelu_t(v0.y), gelu_t(v0.z), gelu_t(v0.w)}; v1 = (f32x4){gelu_t(v1.x), gelu_t(v1.y), gelu_t(v1.z), gelu_t(v1.w)}; }
; template <class Epi>
; __device__ __forceinline__ void gemm_phase(LAS unsigned char* lds, const Gemm g, const StaticOrder& S, const Epi& E) {
;     ...
;             PG8_LDB(B1, 1, 1); PG8_STAGE(PG8_SB(1, 0), b3, voffB);
;             PG8_BAR; PG8_WAIT_L(0); PG8_MMA(0, 1, At, B1); PG8_BAR;
;             PG8_LDA(At, 1, 1); PG8_STAGE(PG8_SA(1, 0), a3, voffA);
;             PG8_BAR; PG8_WAIT_L(0); PG8_MMA(1, 0, At, B0); PG8_BAR; PG8_SCHED;
;             PG8_STAGE(PG8_SB(1, 1), b3 + hstepB, voffB);
;             PG8_WAIT_V(6); PG8_BAR; PG8_MMA(1, 1, At, B1); PG8_BAR;
;         }
	ds_read_b128 v[170:173], v155 offset:49152
	ds_read_b128 v[174:177], v155 offset:50176
	ds_read_b128 v[178:181], v155 offset:51200
	ds_read_b128 v[182:185], v155 offset:52224
	ds_read_b128 v[186:189], v155 offset:53248
	ds_read_b128 v[190:193], v155 offset:54272
	ds_read_b128 v[194:197], v155 offset:55296
	ds_read_b128 v[198:201], v155 offset:56320
	s_add_i32 s55, s55, s35
	v_lshl_add_u64 v[218:219], v[218:219], 0, s[28:29]
	s_mov_b32 m0, s55
	s_nop 0
	global_load_lds_dwordx4 v[218:219], off
	v_lshl_add_u64 v[218:219], v[220:221], 0, s[28:29]
	s_add_i32 m0, s55, 0x2000
	s_nop 0
	global_load_lds_dwordx4 v[218:219], off
	s_mov_b32 m0, s73
	v_lshl_add_u64 v[218:219], v[222:223], 0, s[28:29]
	global_load_lds_dwordx4 v[218:219], off
	v_lshl_add_u64 v[218:219], v[224:225], 0, s[28:29]
	s_mov_b32 m0, s74
	s_nop 0
	global_load_lds_dwordx4 v[218:219], off
	s_add_u32 s64, s64, 0x40080
	s_addc_u32 s65, s65, 0
	s_add_i32 s55, s98, s35
	v_lshl_add_u64 v[240:241], s[64:65], 0, v[132:133]
	s_mov_b32 m0, s55
	s_nop 0
	global_load_lds_dwordx4 v[240:241], off
	v_lshl_add_u64 v[240:241], s[64:65], 0, v[136:137]
	s_add_i32 m0, s55, 0x2000
	s_nop 0
	global_load_lds_dwordx4 v[240:241], off
	s_waitcnt vmcnt(8) lgkmcnt(0)
	s_barrier
	v_mfma_f32_16x16x32_bf16 v[60:63], v[146:149], v[170:173], v[60:63]
	v_mfma_f32_16x16x32_bf16 v[56:59], v[162:165], v[170:173], v[56:59]
	v_mfma_f32_16x16x32_bf16 v[44:47], v[146:149], v[178:181], v[44:47]
	v_mfma_f32_16x16x32_bf16 v[40:43], v[162:165], v[178:181], v[40:43]
	v_mfma_f32_16x16x32_bf16 v[28:31], v[146:149], v[186:189], v[28:31]
	v_mfma_f32_16x16x32_bf16 v[24:27], v[162:165], v[186:189], v[24:27]
	v_mfma_f32_16x16x32_bf16 v[12:15], v[146:149], v[194:197], v[12:15]
	v_mfma_f32_16x16x32_bf16 v[8:11], v[162:165], v[194:197], v[8:11]
	v_mfma_f32_16x16x32_bf16 v[60:63], v[158:161], v[174:177], v[60:63]
	v_mfma_f32_16x16x32_bf16 v[56:59], v[166:169], v[174:177], v[56:59]
	v_mfma_f32_16x16x32_bf16 v[44:47], v[158:161], v[182:185], v[44:47]
	v_mfma_f32_16x16x32_bf16 v[40:43], v[166:169], v[182:185], v[40:43]
	v_mfma_f32_16x16x32_bf16 v[28:31], v[158:161], v[190:193], v[28:31]
	v_mfma_f32_16x16x32_bf16 v[24:27], v[166:169], v[190:193], v[24:27]
	v_mfma_f32_16x16x32_bf16 v[12:15], v[158:161], v[198:201], v[12:15]
	v_mfma_f32_16x16x32_bf16 v[8:11], v[166:169], v[198:201], v[8:11]
	v_mfma_f32_16x16x32_bf16 v[52:55], v[202:205], v[170:173], v[52:55]
	v_mfma_f32_16x16x32_bf16 v[48:51], v[210:213], v[170:173], v[48:51]
	v_mfma_f32_16x16x32_bf16 v[36:39], v[202:205], v[178:181], v[36:39]
	v_mfma_f32_16x16x32_bf16 v[32:35], v[210:213], v[178:181], v[32:35]
	v_mfma_f32_16x16x32_bf16 v[20:23], v[202:205], v[186:189], v[20:23]
	v_mfma_f32_16x16x32_bf16 v[16:19], v[210:213], v[186:189], v[16:19]
	v_mfma_f32_16x16x32_bf16 v[4:7], v[202:205], v[194:197], v[4:7]
	v_mfma_f32_16x16x32_bf16 v[0:3], v[210:213], v[194:197], v[0:3]
	v_mfma_f32_16x16x32_bf16 v[52:55], v[206:209], v[174:177], v[52:55]
	v_mfma_f32_16x16x32_bf16 v[48:51], v[214:217], v[174:177], v[48:51]
	v_mfma_f32_16x16x32_bf16 v[36:39], v[206:209], v[182:185], v[36:39]
	v_mfma_f32_16x16x32_bf16 v[32:35], v[214:217], v[182:185], v[32:35]
	v_mfma_f32_16x16x32_bf16 v[20:23], v[206:209], v[190:193], v[20:23]
	v_mfma_f32_16x16x32_bf16 v[16:19], v[214:217], v[190:193], v[16:19]
	v_mfma_f32_16x16x32_bf16 v[4:7], v[206:209], v[198:201], v[4:7]
	v_mfma_f32_16x16x32_bf16 v[0:3], v[214:217], v[198:201], v[0:3]
	s_add_i32 s33, s33, 2
	s_add_u32 s62, s62, 0x100
	s_addc_u32 s63, s63, 0
	s_add_u32 s9, s9, 0x100
	s_addc_u32 s31, s31, 0
	s_cmp_gt_u32 s33, 13
	s_barrier
	s_cbranch_scc0 .LBB0_119
	v_lshl_or_b32 v146, s60, 8, v153
	v_cmp_lt_i32_e32 vcc, s80, v146
	s_and_saveexec_b64 s[60:61], vcc
	s_cbranch_execz .LBB0_122
	v_mul_f32_e32 v148, 0x3d372713, v125
	v_mul_f32_e32 v148, v125, v148
	v_fma_f32 v148, v125, v148, v125
	v_mul_f32_e32 v147, 0x3d372713, v124
	v_mul_f32_e32 v148, 0xbfcc422a, v148
	v_mul_f32_e32 v147, v124, v147
	v_mul_f32_e32 v148, 0x3fb8aa3b, v148
	v_fma_f32 v147, v124, v147, v124
	v_exp_f32_e32 v149, v148
	v_mul_f32_e32 v148, 0x3d372713, v126
	v_mul_f32_e32 v147, 0xbfcc422a, v147
	v_mul_f32_e32 v148, v126, v148
	v_mul_f32_e32 v147, 0x3fb8aa3b, v147
	v_fma_f32 v148, v126, v148, v126
	v_exp_f32_e32 v147, v147
	v_mul_f32_e32 v148, 0xbfcc422a, v148
	v_mul_f32_e32 v148, 0x3fb8aa3b, v148
	v_exp_f32_e32 v157, v148
	v_add_f32_e32 v147, 1.0, v147
	v_rcp_f32_e32 v148, v147
	v_add_f32_e32 v147, 1.0, v149
	v_rcp_f32_e32 v149, v147
	v_add_f32_e32 v147, 1.0, v157
	v_mul_f32_e32 v157, 0x3d372713, v127
	v_mul_f32_e32 v157, v127, v157
	v_mul_f32_e32 v158, 0x3d372713, v120
	v_fma_f32 v157, v127, v157, v127
	v_mul_f32_e32 v158, v120, v158
	v_mul_f32_e32 v157, 0xbfcc422a, v157
	v_fma_f32 v158, v120, v158, v120
	v_mul_f32_e32 v157, 0x3fb8aa3b, v157
	v_mul_f32_e32 v158, 0xbfcc422a, v158
	v_exp_f32_e32 v157, v157
	v_mul_f32_e32 v158, 0x3fb8aa3b, v158
	v_exp_f32_e32 v160, v158
	v_rcp_f32_e32 v158, v147
	v_add_f32_e32 v147, 1.0, v157
	v_rcp_f32_e32 v159, v147
	v_add_f32_e32 v147, 1.0, v160
	v_mul_f32_e32 v157, 0x3d372713, v122
	v_rcp_f32_e32 v160, v147
	v_mul_f32_e32 v147, 0x3d372713, v121
	v_mul_f32_e32 v157, v122, v157
	v_mul_f32_e32 v161, 0x3d372713, v123
	v_mul_f32_e32 v147, v121, v147
	v_fma_f32 v157, v122, v157, v122
	v_mul_f32_e32 v161, v123, v161
	v_fma_f32 v147, v121, v147, v121
	v_mul_f32_e32 v157, 0xbfcc422a, v157
	v_fma_f32 v161, v123, v161, v123
	v_mul_f32_e32 v147, 0xbfcc422a, v147
	v_mul_f32_e32 v157, 0x3fb8aa3b, v157
	v_mul_f32_e32 v161, 0xbfcc422a, v161
	v_mul_f32_e32 v147, 0x3fb8aa3b, v147
	v_exp_f32_e32 v157, v157
	v_mul_f32_e32 v161, 0x3fb8aa3b, v161
	v_exp_f32_e32 v147, v147
	v_exp_f32_e32 v161, v161
	v_add_f32_e32 v157, 1.0, v157
	v_rcp_f32_e32 v162, v157
	v_add_f32_e32 v147, 1.0, v147
	v_add_f32_e32 v157, 1.0, v161
	v_rcp_f32_e32 v163, v157
	v_rcp_f32_e32 v161, v147
	v_pk_mul_f32 v[126:127], v[126:127], v[158:159]
	v_pk_mul_f32 v[124:125], v[124:125], v[148:149]
	v_pk_mul_f32 v[122:123], v[122:123], v[162:163]
	v_pk_mul_f32 v[120:121], v[120:121], v[160:161]

; #define PG8_STAGE(bufoff, gbase, voff) do { _Pragma("unroll") for (int _i = 0; _i < 2; ++_i) \
;         __builtin_amdgcn_global_load_lds((const unsigned*)((const char*)(gbase) + (voff)[_i]), (LAS unsigned*)(lds + (bufoff) + ldsw + _i * 8192), 16, 0, 0); } while (0)
; #define PG8_WAIT_V(n) asm volatile("s_waitcnt vmcnt(" #n ")" ::: "memory")
; #define PG8_BAR __builtin_amdgcn_s_barrier()
; template <class Epi>
; __device__ __forceinline__ void gemm_phase(LAS unsigned char* lds, const Gemm g, const StaticOrder& S, const Epi& E) {
;     ...
;     for (int i = 0; i < 2; ++i) { int R, C; stage_rc(tid * 16 + i * 8192, R, C); const int Rb = Epi::PERM ? ((R & ~31) + perm32(R & 31)) : R;
;         voffA[i] = (unsigned)(R * lda + C) * 2u; voffB[i] = (unsigned)(Rb * K + C) * 2u; }
;     const size_t kstep = (size_t)(BK * 2);
;     const size_t hstepA = (size_t)HALF * lda * 2, hstepB = (size_t)HALF * K * 2;
;     const size_t tstepA = 2 * hstepA, tstepB = 2 * hstepB;
;     const unsigned ldsw = (unsigned)wid * 1024u;
;     const int aoff = lds_byte(wr * 64 + fr, fq * 8), boff = lds_byte(wc * 32 + fr, fq * 8);
;     ...
;     Unit cur, nxt; int ui = 0;
;     if (!S.next(0, cur)) return;
;     f32x4 acc[2][2][4][2];
; #pragma unroll
;     for (int a = 0; a < 2; ++a)
; #pragma unroll
;         for (int b = 0; b < 2; ++b)
; #pragma unroll
;             for (int m = 0; m < 4; ++m)
; #pragma unroll
;                 for (int n = 0; n < 2; ++n) acc[a][b][m][n] = (f32x4){0.f, 0.f, 0.f, 0.f};
;     bf16x8 At[4][2], B0[2][2], B1[2][2];
;     const char* cA = (const char*)g.A + (size_t)cur.pm * tstepA + (size_t)cur.kt0 * kstep; const char* cB = (const char*)g.Bt + (size_t)cur.pn * tstepB + (size_t)cur.kt0 * kstep;
;     PG8_STAGE(PG8_SB(0, 0), cB, voffB); PG8_STAGE(PG8_SA(0, 0), cA, voffA); PG8_STAGE(PG8_SB(0, 1), cB + hstepB, voffB); PG8_STAGE(PG8_SA(0, 1), cA + hstepA, voffA);
;     if (wr == 1) PG8_BAR;
;     PG8_WAIT_V(4); PG8_BAR;
;     PG8_STAGE(PG8_SB(1, 0), cB + kstep, voffB); PG8_STAGE(PG8_SA(1, 0), cA + kstep, voffA); PG8_STAGE(PG8_SB(1, 1), cB + hstepB + kstep, voffB);
;     PG8_WAIT_V(6); PG8_BAR;
.LBB0_439:
	s_lshl_b32 s0, s12, 5
	s_mov_b64 s[12:13], 0x80
	s_and_b32 s31, s0, 0x60
	s_add_i32 m0, s35, 0x18000
	v_lshl_add_u64 v[6:7], v[6:7], 0, s[12:13]
	s_lshl_b32 s21, s20, 13
	s_lshl_b32 s56, s31, 7
	s_waitcnt vmcnt(0)
	s_barrier
	global_load_lds_dwordx4 v[6:7], off
	v_lshl_add_u64 v[4:5], v[4:5], 0, s[12:13]
	s_add_i32 m0, s35, 0x1a000
	s_add_i32 s73, s35, 0x8000
	s_add_i32 s74, s35, 0xa000
	global_load_lds_dwordx4 v[4:5], off
	v_lshl_add_u64 v[0:1], v[0:1], 0, s[12:13]
	s_mov_b32 m0, s73
	s_add_u32 s0, s66, 0x40080
	global_load_lds_dwordx4 v[0:1], off
	v_lshl_add_u64 v[0:1], v[2:3], 0, s[12:13]
	s_mov_b32 m0, s74
	s_addc_u32 s1, s67, 0
	global_load_lds_dwordx4 v[0:1], off
	s_add_i32 m0, s35, 0x1c000
	v_lshl_add_u64 v[0:1], s[0:1], 0, v[132:133]
	global_load_lds_dwordx4 v[0:1], off
	v_lshl_add_u64 v[0:1], s[0:1], 0, v[136:137]
	s_add_i32 m0, s35, 0x1e000
	v_lshlrev_b32_e32 v2, 2, v129
	global_load_lds_dwordx4 v[0:1], off
	v_and_b32_e32 v0, 15, v129
	v_lshlrev_b32_e32 v1, 1, v11
	v_lshlrev_b32_e32 v3, 6, v129
	s_movk_i32 s0, 0x3c0
	v_lshl_or_b32 v155, s20, 6, v0
	v_lshl_or_b32 v0, v0, 6, v1
	v_and_b32_e32 v2, 32, v2
	v_and_or_b32 v1, v3, s0, v1
	v_bitop3_b32 v156, s56, v1, v2 bitop3:0xf6
	v_lshlrev_b32_e32 v1, 8, v129
	v_bitop3_b32 v0, v0, s21, v2 bitop3:0xde
	v_and_b32_e32 v1, 0x38000, v1
	v_lshlrev_b32_e32 v2, 11, v10
	v_or3_b32 v1, v8, v1, v2
	v_add_u32_e32 v138, v1, v9
	v_lshlrev_b32_e32 v1, 4, v12
	s_waitcnt vmcnt(6)
	v_and_b32_e32 v1, 0x78000, v1
	v_or3_b32 v1, v8, v1, v2
	s_add_i32 s78, 0, 0x10000
	s_add_i32 s79, 0, 0x14000
	s_ashr_i32 s75, s14, 31
	s_mov_b32 s76, s14
	s_ashr_i32 s77, s2, 31
	v_or_b32_e32 v157, s31, v11
	v_mov_b32_e32 v139, v133
	v_add_u32_e32 v140, v1, v9
	v_mov_b32_e32 v141, v133
	v_mov_b64_e32 v[142:143], 0xff
	v_add_u32_e32 v158, s78, v156
	v_add_u32_e32 v159, 0, v0
	v_add_u32_e32 v160, s79, v156
	s_mov_b32 s80, 0
	s_barrier
	s_branch .LBB0_442

; #define PG8_STAGE(bufoff, gbase, voff) do { _Pragma("unroll") for (int _i = 0; _i < 2; ++_i) \
;         __builtin_amdgcn_global_load_lds((const unsigned*)((const char*)(gbase) + (voff)[_i]), (LAS unsigned*)(lds + (bufoff) + ldsw + _i * 8192), 16, 0, 0); } while (0)
; #define PG8_LDA(dst, b, h) do { _Pragma("unroll") for (int m = 0; m < 4; ++m) _Pragma("unroll") for (int k = 0; k < 2; ++k) dst[m][k] = *(const LAS bf16x8*)(lds + PG8_SA(b, h) + aoff + m * 2048 + k * 1024); } while (0)
; #define PG8_LDB(dst, b, h) do { _Pragma("unroll") for (int n = 0; n < 2; ++n) _Pragma("unroll") for (int k = 0; k < 2; ++k) dst[n][k] = *(const LAS bf16x8*)(lds + PG8_SB(b, h) + boff + n * 2048 + k * 1024); } while (0)
; #define PG8_MMA(ai, bj, At, Bt) do { __builtin_amdgcn_s_setprio(1); _Pragma("unroll") for (int m = 0; m < 4; ++m) _Pragma("unroll") for (int n = 0; n < 2; ++n) _Pragma("unroll") for (int k = 0; k < 2; ++k) \
;         acc[ai][bj][m][n] = __builtin_amdgcn_mfma_f32_16x16x32_bf16(Bt[n][k], At[m][k], acc[ai][bj][m][n], 0, 0, 0); __builtin_amdgcn_s_setprio(0); } while (0)
; #define PG8_WAIT_V(n) asm volatile("s_waitcnt vmcnt(" #n ")" ::: "memory")
; #define PG8_WAIT_L(n) asm volatile("s_waitcnt lgkmcnt(" #n ")" ::: "memory")
; template <class Epi>
; __device__ __forceinline__ void gemm_phase(LAS unsigned char* lds, const Gemm g, const StaticOrder& S, const Epi& E) {
;     ...
;         for (int t = 0; t < nt; t += 2) {
;             const bool last = (t == nt - 2);
;             const char* a1 = cA + (size_t)(t + 1) * kstep;
;             const char* a2 = last ? nA : cA + (size_t)(t + 2) * kstep; const char* b2 = last ? nB : cB + (size_t)(t + 2) * kstep;
;             const char* a3 = a2 + kstep; const char* b3 = b2 + kstep;
;             PG8_LDB(B0, 0, 0); PG8_SCHED; PG8_LDA(At, 0, 0); PG8_STAGE(PG8_SA(1, 1), a1 + hstepA, voffA);
;             PG8_WAIT_L(8); PG8_BAR; PG8_WAIT_L(0); PG8_MMA(0, 0, At, B0); PG8_BAR; PG8_SCHED;
;             PG8_LDB(B1, 0, 1); PG8_STAGE(PG8_SB(0, 0), b2, voffB);
;             PG8_BAR; PG8_WAIT_L(0); PG8_MMA(0, 1, At, B1); PG8_BAR;
;             PG8_LDA(At, 0, 1); PG8_STAGE(PG8_SA(0, 0), a2, voffA);
;             PG8_BAR; PG8_WAIT_L(0); PG8_MMA(1, 0, At, B0); PG8_BAR; PG8_SCHED;
;             PG8_STAGE(PG8_SB(0, 1), b2 + hstepB, voffB);
;             PG8_WAIT_V(6); PG8_BAR; PG8_MMA(1, 1, At, B1); PG8_BAR;
.LBB0_456:
	s_add_i32 s85, s59, 2
	s_add_u32 s66, s64, 0xfffc0080
	s_addc_u32 s67, s65, -1
	s_cmp_eq_u32 s21, s59
	s_cselect_b32 s69, s63, s67
	s_cselect_b32 s68, s62, s66
	s_cselect_b32 s67, s1, s57
	s_cselect_b32 s66, s0, s31
	ds_read_b128 v[144:147], v158
	ds_read_b128 v[148:151], v158 offset:1024
	ds_read_b128 v[162:165], v158 offset:2048
	ds_read_b128 v[166:169], v158 offset:3072
	ds_read_b128 v[170:173], v159
	ds_read_b128 v[174:177], v159 offset:1024
	ds_read_b128 v[178:181], v159 offset:2048
	ds_read_b128 v[182:185], v159 offset:3072
	ds_read_b128 v[186:189], v159 offset:4096
	ds_read_b128 v[190:193], v159 offset:5120
	ds_read_b128 v[194:197], v159 offset:6144
	ds_read_b128 v[198:201], v159 offset:7168
	ds_read_b128 v[202:205], v160
	ds_read_b128 v[206:209], v160 offset:1024
	ds_read_b128 v[210:213], v160 offset:2048
	ds_read_b128 v[214:217], v160 offset:3072
	v_lshl_add_u64 v[152:153], s[64:65], 0, v[138:139]
	s_add_i32 m0, s35, 0xc000
	s_nop 0
	global_load_lds_dwordx4 v[152:153], off
	v_lshl_add_u64 v[152:153], s[64:65], 0, v[140:141]
	s_add_i32 m0, s35, 0xe000
	s_nop 0
	global_load_lds_dwordx4 v[152:153], off
	s_waitcnt vmcnt(8) lgkmcnt(0)
	s_barrier
	v_mfma_f32_16x16x32_bf16 v[124:127], v[144:147], v[170:173], v[124:127]
	v_mfma_f32_16x16x32_bf16 v[120:123], v[162:165], v[170:173], v[120:123]
	v_mfma_f32_16x16x32_bf16 v[116:119], v[144:147], v[178:181], v[116:119]
	v_mfma_f32_16x16x32_bf16 v[108:111], v[162:165], v[178:181], v[108:111]
	v_mfma_f32_16x16x32_bf16 v[100:103], v[144:147], v[186:189], v[100:103]
	v_mfma_f32_16x16x32_bf16 v[92:95], v[162:165], v[186:189], v[92:95]
	v_mfma_f32_16x16x32_bf16 v[84:87], v[144:147], v[194:197], v[84:87]
	v_mfma_f32_16x16x32_bf16 v[76:79], v[162:165], v[194:197], v[76:79]
	v_mfma_f32_16x16x32_bf16 v[124:127], v[148:151], v[174:177], v[124:127]
	v_mfma_f32_16x16x32_bf16 v[120:123], v[166:169], v[174:177], v[120:123]
	v_mfma_f32_16x16x32_bf16 v[116:119], v[148:151], v[182:185], v[116:119]
	v_mfma_f32_16x16x32_bf16 v[108:111], v[166:169], v[182:185], v[108:111]
	v_mfma_f32_16x16x32_bf16 v[100:103], v[148:151], v[190:193], v[100:103]
	v_mfma_f32_16x16x32_bf16 v[92:95], v[166:169], v[190:193], v[92:95]
	v_mfma_f32_16x16x32_bf16 v[84:87], v[148:151], v[198:201], v[84:87]
	v_mfma_f32_16x16x32_bf16 v[76:79], v[166:169], v[198:201], v[76:79]
	v_mfma_f32_16x16x32_bf16 v[112:115], v[202:205], v[170:173], v[112:115]
	v_mfma_f32_16x16x32_bf16 v[104:107], v[210:213], v[170:173], v[104:107]
	v_mfma_f32_16x16x32_bf16 v[96:99], v[202:205], v[178:181], v[96:99]
	v_mfma_f32_16x16x32_bf16 v[88:91], v[210:213], v[178:181], v[88:91]
	v_mfma_f32_16x16x32_bf16 v[80:83], v[202:205], v[186:189], v[80:83]
	v_mfma_f32_16x16x32_bf16 v[72:75], v[210:213], v[186:189], v[72:75]
	v_mfma_f32_16x16x32_bf16 v[68:71], v[202:205], v[194:197], v[68:71]
	v_mfma_f32_16x16x32_bf16 v[64:67], v[210:213], v[194:197], v[64:67]
	v_mfma_f32_16x16x32_bf16 v[112:115], v[206:209], v[174:177], v[112:115]
	v_mfma_f32_16x16x32_bf16 v[104:107], v[214:217], v[174:177], v[104:107]
	v_mfma_f32_16x16x32_bf16 v[96:99], v[206:209], v[182:185], v[96:99]
	v_mfma_f32_16x16x32_bf16 v[88:91], v[214:217], v[182:185], v[88:91]
	v_mfma_f32_16x16x32_bf16 v[80:83], v[206:209], v[190:193], v[80:83]
	v_mfma_f32_16x16x32_bf16 v[72:75], v[214:217], v[190:193], v[72:75]
	v_mfma_f32_16x16x32_bf16 v[68:71], v[206:209], v[198:201], v[68:71]
	v_mfma_f32_16x16x32_bf16 v[64:67], v[214:217], v[198:201], v[64:67]
	s_barrier
	ds_read_b128 v[170:173], v159 offset:16384
	ds_read_b128 v[174:177], v159 offset:17408
	ds_read_b128 v[178:181], v159 offset:18432
	ds_read_b128 v[182:185], v159 offset:19456
	ds_read_b128 v[186:189], v159 offset:20480
	ds_read_b128 v[190:193], v159 offset:21504
	ds_read_b128 v[194:197], v159 offset:22528
	ds_read_b128 v[198:201], v159 offset:23552
	s_add_i32 s59, s78, s33
	v_lshl_add_u64 v[152:153], s[66:67], 0, v[132:133]
	s_mov_b32 m0, s59
	s_nop 0
	global_load_lds_dwordx4 v[152:153], off
	v_lshl_add_u64 v[218:219], s[66:67], 0, v[136:137]
	s_add_i32 m0, s59, 0x2000
	s_nop 0
	global_load_lds_dwordx4 v[218:219], off
	s_mov_b32 m0, s35
	v_lshl_add_u64 v[220:221], s[68:69], 0, v[130:131]
	global_load_lds_dwordx4 v[220:221], off
	v_lshl_add_u64 v[222:223], s[68:69], 0, v[134:135]
	s_mov_b32 m0, s70
	s_nop 0
	global_load_lds_dwordx4 v[222:223], off
	s_add_u32 s86, s66, 0x40000
	s_addc_u32 s87, s67, 0
	s_add_i32 s59, s79, s33
	v_lshl_add_u64 v[240:241], s[86:87], 0, v[132:133]
	s_mov_b32 m0, s59
	s_nop 0
	global_load_lds_dwordx4 v[240:241], off
	v_lshl_add_u64 v[240:241], s[86:87], 0, v[136:137]
	s_add_i32 m0, s59, 0x2000
	s_nop 0
	global_load_lds_dwordx4 v[240:241], off
	s_waitcnt vmcnt(8) lgkmcnt(0)
	s_barrier
; #define PG8_STAGE(bufoff, gbase, voff) do { _Pragma("unroll") for (int _i = 0; _i < 2; ++_i) \
;         __builtin_amdgcn_global_load_lds((const unsigned*)((const char*)(gbase) + (voff)[_i]), (LAS unsigned*)(lds + (bufoff) + ldsw + _i * 8192), 16, 0, 0); } while (0)
; #define PG8_LDA(dst, b, h) do { _Pragma("unroll") for (int m = 0; m < 4; ++m) _Pragma("unroll") for (int k = 0; k < 2; ++k) dst[m][k] = *(const LAS bf16x8*)(lds + PG8_SA(b, h) + aoff + m * 2048 + k * 1024); } while (0)
; #define PG8_LDB(dst, b, h) do { _Pragma("unroll") for (int n = 0; n < 2; ++n) _Pragma("unroll") for (int k = 0; k < 2; ++k) dst[n][k] = *(const LAS bf16x8*)(lds + PG8_SB(b, h) + boff + n * 2048 + k * 1024); } while (0)
; #define PG8_MMA(ai, bj, At, Bt) do { __builtin_amdgcn_s_setprio(1); _Pragma("unroll") for (int m = 0; m < 4; ++m) _Pragma("unroll") for (int n = 0; n < 2; ++n) _Pragma("unroll") for (int k = 0; k < 2; ++k) \
;         acc[ai][bj][m][n] = __builtin_amdgcn_mfma_f32_16x16x32_bf16(Bt[n][k], At[m][k], acc[ai][bj][m][n], 0, 0, 0); __builtin_amdgcn_s_setprio(0); } while (0)
; #define PG8_WAIT_V(n) asm volatile("s_waitcnt vmcnt(" #n ")" ::: "memory")
; #define PG8_WAIT_L(n) asm volatile("s_waitcnt lgkmcnt(" #n ")" ::: "memory")
; #define PG8_BAR __builtin_amdgcn_s_barrier()
; #define PG8_SCHED __builtin_amdgcn_sched_barrier(0)
; template <class Epi>
; __device__ __forceinline__ void gemm_phase(LAS unsigned char* lds, const Gemm g, const StaticOrder& S, const Epi& E) {
;     ...
;             PG8_BAR; PG8_WAIT_L(0); PG8_MMA(1, 0, At, B0); PG8_BAR; PG8_SCHED;
;             PG8_STAGE(PG8_SB(0, 1), b2 + hstepB, voffB);
;             PG8_WAIT_V(6); PG8_BAR; PG8_MMA(1, 1, At, B1); PG8_BAR;
;             PG8_LDB(B0, 1, 0); PG8_SCHED; PG8_LDA(At, 1, 0); PG8_STAGE(PG8_SA(0, 1), a2 + hstepA, voffA);
;             PG8_WAIT_L(8); PG8_BAR; PG8_WAIT_L(0); PG8_MMA(0, 0, At, B0); PG8_BAR; PG8_SCHED;
;             PG8_LDB(B1, 1, 1); PG8_STAGE(PG8_SB(1, 0), b3, voffB);
;             PG8_BAR; PG8_WAIT_L(0); PG8_MMA(0, 1, At, B1); PG8_BAR;
	v_mfma_f32_16x16x32_bf16 v[60:63], v[144:147], v[170:173], v[60:63]
	v_mfma_f32_16x16x32_bf16 v[56:59], v[162:165], v[170:173], v[56:59]
	v_mfma_f32_16x16x32_bf16 v[52:55], v[144:147], v[178:181], v[52:55]
	v_mfma_f32_16x16x32_bf16 v[44:47], v[162:165], v[178:181], v[44:47]
	v_mfma_f32_16x16x32_bf16 v[36:39], v[144:147], v[186:189], v[36:39]
	v_mfma_f32_16x16x32_bf16 v[28:31], v[162:165], v[186:189], v[28:31]
	v_mfma_f32_16x16x32_bf16 v[20:23], v[144:147], v[194:197], v[20:23]
	v_mfma_f32_16x16x32_bf16 v[12:15], v[162:165], v[194:197], v[12:15]
	v_mfma_f32_16x16x32_bf16 v[60:63], v[148:151], v[174:177], v[60:63]
	v_mfma_f32_16x16x32_bf16 v[56:59], v[166:169], v[174:177], v[56:59]
	v_mfma_f32_16x16x32_bf16 v[52:55], v[148:151], v[182:185], v[52:55]
	v_mfma_f32_16x16x32_bf16 v[44:47], v[166:169], v[182:185], v[44:47]
	v_mfma_f32_16x16x32_bf16 v[36:39], v[148:151], v[190:193], v[36:39]
	v_mfma_f32_16x16x32_bf16 v[28:31], v[166:169], v[190:193], v[28:31]
	v_mfma_f32_16x16x32_bf16 v[20:23], v[148:151], v[198:201], v[20:23]
	v_mfma_f32_16x16x32_bf16 v[12:15], v[166:169], v[198:201], v[12:15]
	v_mfma_f32_16x16x32_bf16 v[48:51], v[202:205], v[170:173], v[48:51]
	v_mfma_f32_16x16x32_bf16 v[40:43], v[210:213], v[170:173], v[40:43]
	v_mfma_f32_16x16x32_bf16 v[32:35], v[202:205], v[178:181], v[32:35]
	v_mfma_f32_16x16x32_bf16 v[24:27], v[210:213], v[178:181], v[24:27]
	v_mfma_f32_16x16x32_bf16 v[16:19], v[202:205], v[186:189], v[16:19]
	v_mfma_f32_16x16x32_bf16 v[8:11], v[210:213], v[186:189], v[8:11]
	v_mfma_f32_16x16x32_bf16 v[4:7], v[202:205], v[194:197], v[4:7]
	v_mfma_f32_16x16x32_bf16 v[0:3], v[210:213], v[194:197], v[0:3]
	v_mfma_f32_16x16x32_bf16 v[48:51], v[206:209], v[174:177], v[48:51]
	v_mfma_f32_16x16x32_bf16 v[40:43], v[214:217], v[174:177], v[40:43]
	v_mfma_f32_16x16x32_bf16 v[32:35], v[206:209], v[182:185], v[32:35]
	v_mfma_f32_16x16x32_bf16 v[24:27], v[214:217], v[182:185], v[24:27]
	v_mfma_f32_16x16x32_bf16 v[16:19], v[206:209], v[190:193], v[16:19]
	v_mfma_f32_16x16x32_bf16 v[8:11], v[214:217], v[190:193], v[8:11]
	v_mfma_f32_16x16x32_bf16 v[4:7], v[206:209], v[198:201], v[4:7]
	v_mfma_f32_16x16x32_bf16 v[0:3], v[214:217], v[198:201], v[0:3]
	s_barrier
	s_add_i32 s59, 0, 0x18000
	v_add_u32_e32 v161, s59, v156
	ds_read_b128 v[144:147], v161
	ds_read_b128 v[148:151], v161 offset:1024
	ds_read_b128 v[162:165], v161 offset:2048
	ds_read_b128 v[166:169], v161 offset:3072
	ds_read_b128 v[170:173], v159 offset:32768
	ds_read_b128 v[174:177], v159 offset:33792
	ds_read_b128 v[178:181], v159 offset:34816
	ds_read_b128 v[182:185], v159 offset:35840
	ds_read_b128 v[186:189], v159 offset:36864
	ds_read_b128 v[190:193], v159 offset:37888
	ds_read_b128 v[194:197], v159 offset:38912
	ds_read_b128 v[198:201], v159 offset:39936
	s_add_i32 s98, 0, 0x1c000
	v_add_u32_e32 v246, s98, v156
	ds_read_b128 v[202:205], v246
	ds_read_b128 v[206:209], v246 offset:1024
	ds_read_b128 v[210:213], v246 offset:2048
	ds_read_b128 v[214:217], v246 offset:3072
	s_add_u32 s68, s68, 0x40000
	s_addc_u32 s69, s69, 0
	s_mov_b32 m0, s71
	v_lshl_add_u64 v[244:245], s[68:69], 0, v[130:131]
	global_load_lds_dwordx4 v[244:245], off
	v_lshl_add_u64 v[244:245], s[68:69], 0, v[134:135]
	s_mov_b32 m0, s72
	s_nop 0
	global_load_lds_dwordx4 v[244:245], off
	s_waitcnt vmcnt(8) lgkmcnt(0)
	s_barrier
	v_mfma_f32_16x16x32_bf16 v[124:127], v[144:147], v[170:173], v[124:127]
	v_mfma_f32_16x16x32_bf16 v[120:123], v[162:165], v[170:173], v[120:123]
	v_mfma_f32_16x16x32_bf16 v[116:119], v[144:147], v[178:181], v[116:119]
	v_mfma_f32_16x16x32_bf16 v[108:111], v[162:165], v[178:181], v[108:111]
	v_mfma_f32_16x16x32_bf16 v[100:103], v[144:147], v[186:189], v[100:103]
	v_mfma_f32_16x16x32_bf16 v[92:95], v[162:165], v[186:189], v[92:95]
	v_mfma_f32_16x16x32_bf16 v[84:87], v[144:147], v[194:197], v[84:87]
	v_mfma_f32_16x16x32_bf16 v[76:79], v[162:165], v[194:197], v[76:79]
	v_mfma_f32_16x16x32_bf16 v[124:127], v[148:151], v[174:177], v[124:127]
	v_mfma_f32_16x16x32_bf16 v[120:123], v[166:169], v[174:177], v[120:123]
	v_mfma_f32_16x16x32_bf16 v[116:119], v[148:151], v[182:185], v[116:119]
	v_mfma_f32_16x16x32_bf16 v[108:111], v[166:169], v[182:185], v[108:111]
	v_mfma_f32_16x16x32_bf16 v[100:103], v[148:151], v[190:193], v[100:103]
	v_mfma_f32_16x16x32_bf16 v[92:95], v[166:169], v[190:193], v[92:95]
	v_mfma_f32_16x16x32_bf16 v[84:87], v[148:151], v[198:201], v[84:87]
	v_mfma_f32_16x16x32_bf16 v[76:79], v[166:169], v[198:201], v[76:79]
	v_mfma_f32_16x16x32_bf16 v[112:115], v[202:205], v[170:173], v[112:115]
	v_mfma_f32_16x16x32_bf16 v[104:107], v[210:213], v[170:173], v[104:107]
	v_mfma_f32_16x16x32_bf16 v[96:99], v[202:205], v[178:181], v[96:99]
	v_mfma_f32_16x16x32_bf16 v[88:91], v[210:213], v[178:181], v[88:91]
	v_mfma_f32_16x16x32_bf16 v[80:83], v[202:205], v[186:189], v[80:83]
	v_mfma_f32_16x16x32_bf16 v[72:75], v[210:213], v[186:189], v[72:75]
	v_mfma_f32_16x16x32_bf16 v[68:71], v[202:205], v[194:197], v[68:71]
	v_mfma_f32_16x16x32_bf16 v[64:67], v[210:213], v[194:197], v[64:67]
	v_mfma_f32_16x16x32_bf16 v[112:115], v[206:209], v[174:177], v[112:115]
	v_mfma_f32_16x16x32_bf16 v[104:107], v[214:217], v[174:177], v[104:107]
	v_mfma_f32_16x16x32_bf16 v[96:99], v[206:209], v[182:185], v[96:99]
	v_mfma_f32_16x16x32_bf16 v[88:91], v[214:217], v[182:185], v[88:91]
	v_mfma_f32_16x16x32_bf16 v[80:83], v[206:209], v[190:193], v[80:83]
	v_mfma_f32_16x16x32_bf16 v[72:75], v[214:217], v[190:193], v[72:75]
	v_mfma_f32_16x16x32_bf16 v[68:71], v[206:209], v[198:201], v[68:71]
	v_mfma_f32_16x16x32_bf16 v[64:67], v[214:217], v[198:201], v[64:67]
	s_barrier
; #define PG8_STAGE(bufoff, gbase, voff) do { _Pragma("unroll") for (int _i = 0; _i < 2; ++_i) \
;         __builtin_amdgcn_global_load_lds((const unsigned*)((const char*)(gbase) + (voff)[_i]), (LAS unsigned*)(lds + (bufoff) + ldsw + _i * 8192), 16, 0, 0); } while (0)
; #define PG8_LDA(dst, b, h) do { _Pragma("unroll") for (int m = 0; m < 4; ++m) _Pragma("unroll") for (int k = 0; k < 2; ++k) dst[m][k] = *(const LAS bf16x8*)(lds + PG8_SA(b, h) + aoff + m * 2048 + k * 1024); } while (0)
; #define PG8_LDB(dst, b, h) do { _Pragma("unroll") for (int n = 0; n < 2; ++n) _Pragma("unroll") for (int k = 0; k < 2; ++k) dst[n][k] = *(const LAS bf16x8*)(lds + PG8_SB(b, h) + boff + n * 2048 + k * 1024); } while (0)
; #define PG8_MMA(ai, bj, At, Bt) do { __builtin_amdgcn_s_setprio(1); _Pragma("unroll") for (int m = 0; m < 4; ++m) _Pragma("unroll") for (int n = 0; n < 2; ++n) _Pragma("unroll") for (int k = 0; k < 2; ++k) \
;         acc[ai][bj][m][n] = __builtin_amdgcn_mfma_f32_16x16x32_bf16(Bt[n][k], At[m][k], acc[ai][bj][m][n], 0, 0, 0); __builtin_amdgcn_s_setprio(0); } while (0)
; #define PG8_WAIT_V(n) asm volatile("s_waitcnt vmcnt(" #n ")" ::: "memory")
; #define PG8_WAIT_L(n) asm volatile("s_waitcnt lgkmcnt(" #n ")" ::: "memory")
; #define PG8_BAR __builtin_amdgcn_s_barrier()
; #define PG8_SCHED __builtin_amdgcn_sched_barrier(0)
; template <class Epi>
; __device__ __forceinline__ void gemm_phase(LAS unsigned char* lds, const Gemm g, const StaticOrder& S, const Epi& E) {
;     ...
;             PG8_LDB(B1, 1, 1); PG8_STAGE(PG8_SB(1, 0), b3, voffB);
;             PG8_BAR; PG8_WAIT_L(0); PG8_MMA(0, 1, At, B1); PG8_BAR;
;             PG8_LDA(At, 1, 1); PG8_STAGE(PG8_SA(1, 0), a3, voffA);
;             PG8_BAR; PG8_WAIT_L(0); PG8_MMA(1, 0, At, B0); PG8_BAR; PG8_SCHED;
;             PG8_STAGE(PG8_SB(1, 1), b3 + hstepB, voffB);
;             PG8_WAIT_V(6); PG8_BAR; PG8_MMA(1, 1, At, B1); PG8_BAR;
;         }
	ds_read_b128 v[170:173], v159 offset:49152
	ds_read_b128 v[174:177], v159 offset:50176
	ds_read_b128 v[178:181], v159 offset:51200
	ds_read_b128 v[182:185], v159 offset:52224
	ds_read_b128 v[186:189], v159 offset:53248
	ds_read_b128 v[190:193], v159 offset:54272
	ds_read_b128 v[194:197], v159 offset:55296
	ds_read_b128 v[198:201], v159 offset:56320
	s_add_i32 s59, s59, s33
	v_lshl_add_u64 v[152:153], v[152:153], 0, s[12:13]
	s_mov_b32 m0, s59
	s_nop 0
	global_load_lds_dwordx4 v[152:153], off
	v_lshl_add_u64 v[152:153], v[218:219], 0, s[12:13]
	s_add_i32 m0, s59, 0x2000
	s_nop 0
	global_load_lds_dwordx4 v[152:153], off
	s_mov_b32 m0, s73
	v_lshl_add_u64 v[152:153], v[220:221], 0, s[12:13]
	global_load_lds_dwordx4 v[152:153], off
	v_lshl_add_u64 v[152:153], v[222:223], 0, s[12:13]
	s_mov_b32 m0, s74
	s_nop 0
	global_load_lds_dwordx4 v[152:153], off
	s_add_u32 s66, s66, 0x40080
	s_addc_u32 s67, s67, 0
	s_add_i32 s59, s98, s33
	v_lshl_add_u64 v[240:241], s[66:67], 0, v[132:133]
	s_mov_b32 m0, s59
	s_nop 0
	global_load_lds_dwordx4 v[240:241], off
	v_lshl_add_u64 v[240:241], s[66:67], 0, v[136:137]
	s_add_i32 m0, s59, 0x2000
	s_nop 0
	global_load_lds_dwordx4 v[240:241], off
	s_waitcnt vmcnt(8) lgkmcnt(0)
	s_barrier
	v_mfma_f32_16x16x32_bf16 v[60:63], v[144:147], v[170:173], v[60:63]
	v_mfma_f32_16x16x32_bf16 v[56:59], v[162:165], v[170:173], v[56:59]
	v_mfma_f32_16x16x32_bf16 v[52:55], v[144:147], v[178:181], v[52:55]
	v_mfma_f32_16x16x32_bf16 v[44:47], v[162:165], v[178:181], v[44:47]
	v_mfma_f32_16x16x32_bf16 v[36:39], v[144:147], v[186:189], v[36:39]
	v_mfma_f32_16x16x32_bf16 v[28:31], v[162:165], v[186:189], v[28:31]
	v_mfma_f32_16x16x32_bf16 v[20:23], v[144:147], v[194:197], v[20:23]
	v_mfma_f32_16x16x32_bf16 v[12:15], v[162:165], v[194:197], v[12:15]
	v_mfma_f32_16x16x32_bf16 v[60:63], v[148:151], v[174:177], v[60:63]
	v_mfma_f32_16x16x32_bf16 v[56:59], v[166:169], v[174:177], v[56:59]
	v_mfma_f32_16x16x32_bf16 v[52:55], v[148:151], v[182:185], v[52:55]
	v_mfma_f32_16x16x32_bf16 v[44:47], v[166:169], v[182:185], v[44:47]
	v_mfma_f32_16x16x32_bf16 v[36:39], v[148:151], v[190:193], v[36:39]
	v_mfma_f32_16x16x32_bf16 v[28:31], v[166:169], v[190:193], v[28:31]
	v_mfma_f32_16x16x32_bf16 v[20:23], v[148:151], v[198:201], v[20:23]
	v_mfma_f32_16x16x32_bf16 v[12:15], v[166:169], v[198:201], v[12:15]
	v_mfma_f32_16x16x32_bf16 v[48:51], v[202:205], v[170:173], v[48:51]
	v_mfma_f32_16x16x32_bf16 v[40:43], v[210:213], v[170:173], v[40:43]
	v_mfma_f32_16x16x32_bf16 v[32:35], v[202:205], v[178:181], v[32:35]
	v_mfma_f32_16x16x32_bf16 v[24:27], v[210:213], v[178:181], v[24:27]
	v_mfma_f32_16x16x32_bf16 v[16:19], v[202:205], v[186:189], v[16:19]
	v_mfma_f32_16x16x32_bf16 v[8:11], v[210:213], v[186:189], v[8:11]
	v_mfma_f32_16x16x32_bf16 v[4:7], v[202:205], v[194:197], v[4:7]
	v_mfma_f32_16x16x32_bf16 v[0:3], v[210:213], v[194:197], v[0:3]
	v_mfma_f32_16x16x32_bf16 v[48:51], v[206:209], v[174:177], v[48:51]
	v_mfma_f32_16x16x32_bf16 v[40:43], v[214:217], v[174:177], v[40:43]
	v_mfma_f32_16x16x32_bf16 v[32:35], v[206:209], v[182:185], v[32:35]
	v_mfma_f32_16x16x32_bf16 v[24:27], v[214:217], v[182:185], v[24:27]
	v_mfma_f32_16x16x32_bf16 v[16:19], v[206:209], v[190:193], v[16:19]
	v_mfma_f32_16x16x32_bf16 v[8:11], v[214:217], v[190:193], v[8:11]
	v_mfma_f32_16x16x32_bf16 v[4:7], v[206:209], v[198:201], v[4:7]
	v_mfma_f32_16x16x32_bf16 v[0:3], v[214:217], v[198:201], v[0:3]
	s_add_u32 s64, s64, 0x100
	s_addc_u32 s65, s65, 0
	s_add_u32 s31, s31, 0x100
	s_addc_u32 s57, s57, 0
	s_cmp_ge_i32 s85, s84
	s_mov_b32 s59, s85
	s_barrier
	s_cbranch_scc0 .LBB0_456
;     __device__ __forceinline__ void operator()(const f32x4 (&acc)[2][2][4][2], const Unit& u, int wr, int wc, int fr, int fq) const {
;         const int row0 = u.pm * BM + wr * 64 + fr, col0 = u.pn * BM + wc * 32 + 8 * fq;
;         if (u.part) {
;             float* base = tailacc + (size_t)(u.part - 1) * slab - (size_t)tail_row0 * tail_ld;
; #pragma unroll
;             for (int ai = 0; ai < 2; ++ai)
; #pragma unroll
;                 for (int m = 0; m < 4; ++m) { float* rowp = base + (size_t)(row0 + ai * HALF + m * 16) * tail_ld + col0;
; #pragma unroll
;                     for (int bj = 0; bj < 2; ++bj)
; #pragma unroll
;                         for (int n = 0; n < 2; ++n) *(f32x4*)(rowp + bj * HALF + 4 * n) = acc[ai][bj][m][n]; }
;             return;
	v_lshl_add_u32 v152, s8, 8, v155
	v_lshl_or_b32 v144, s30, 8, v157
	v_or_b32_e32 v150, 16, v152
	v_or_b32_e32 v148, 32, v152
	v_or_b32_e32 v146, 48, v152
	s_cmp_lg_u32 s81, 0
	v_ashrrev_i32_e32 v145, 31, v144
	v_ashrrev_i32_e32 v153, 31, v152
	v_ashrrev_i32_e32 v151, 31, v150
	v_ashrrev_i32_e32 v149, 31, v148
	v_ashrrev_i32_e32 v147, 31, v146
	s_cbranch_scc0 .LBB0_459
	s_add_i32 s8, s81, -1
	s_lshl_b64 s[30:31], s[8:9], 21
	s_add_u32 s30, s4, s30
	s_addc_u32 s31, s5, s31
	v_lshl_add_u64 v[162:163], v[144:145], 2, s[30:31]
	s_brev_b32 s30, 63
	s_mov_b32 s31, -1
	v_lshl_add_u64 v[162:163], v[162:163], 0, s[30:31]
	v_lshlrev_b64 v[164:165], 12, v[152:153]
	v_lshlrev_b64 v[166:167], 12, v[150:151]
	v_lshl_add_u64 v[164:165], v[162:163], 0, v[164:165]
	v_lshl_add_u64 v[166:167], v[162:163], 0, v[166:167]
	global_store_dwordx4 v[164:165], v[124:127], off
	global_store_dwordx4 v[164:165], v[120:123], off offset:16
	global_store_dwordx4 v[164:165], v[112:115], off offset:512
	global_store_dwordx4 v[164:165], v[104:107], off offset:528
	global_store_dwordx4 v[166:167], v[116:119], off
	global_store_dwordx4 v[166:167], v[108:111], off offset:16
	global_store_dwordx4 v[166:167], v[96:99], off offset:512
	global_store_dwordx4 v[166:167], v[88:91], off offset:528
	v_lshlrev_b64 v[166:167], 12, v[148:149]
	v_lshl_add_u64 v[166:167], v[162:163], 0, v[166:167]
	global_store_dwordx4 v[166:167], v[100:103], off
	global_store_dwordx4 v[166:167], v[92:95], off offset:16
	global_store_dwordx4 v[166:167], v[80:83], off offset:512
	global_store_dwordx4 v[166:167], v[72:75], off offset:528
	v_lshlrev_b64 v[166:167], 12, v[146:147]
	s_mov_b32 s8, 0x80000
	v_lshl_add_u64 v[162:163], v[162:163], 0, v[166:167]
	v_add_co_u32_e32 v166, vcc, s8, v164
	s_mov_b64 s[30:31], 0x80000
	s_nop 0
	v_addc_co_u32_e32 v167, vcc, 0, v165, vcc
	s_mov_b32 s8, 0x90000
	global_store_dwordx4 v[162:163], v[84:87], off
	global_store_dwordx4 v[162:163], v[76:79], off offset:16
	global_store_dwordx4 v[162:163], v[68:71], off offset:512
	global_store_dwordx4 v[162:163], v[64:67], off offset:528
	v_lshl_add_u64 v[162:163], v[164:165], 0, s[30:31]
	global_store_dwordx4 v[166:167], v[60:63], off
	global_store_dwordx4 v[162:163], v[56:59], off offset:16
	global_store_dwordx4 v[162:163], v[48:51], off offset:512
	global_store_dwordx4 v[162:163], v[40:43], off offset:528
	v_add_co_u32_e32 v166, vcc, s8, v164
	s_mov_b64 s[30:31], 0x90000
	s_nop 0
	v_addc_co_u32_e32 v167, vcc, 0, v165, vcc
	s_mov_b32 s8, 0xa0000
	v_lshl_add_u64 v[162:163], v[164:165], 0, s[30:31]
	global_store_dwordx4 v[166:167], v[52:55], off
	global_store_dwordx4 v[162:163], v[44:47], off offset:16
	global_store_dwordx4 v[162:163], v[32:35], off offset:512
	global_store_dwordx4 v[162:163], v[24:27], off offset:528
	s_mov_b64 s[30:31], 0xa0000
	v_add_co_u32_e32 v166, vcc, s8, v164
	v_lshl_add_u64 v[162:163], v[164:165], 0, s[30:31]
	s_nop 0
	v_addc_co_u32_e32 v167, vcc, 0, v165, vcc
	s_mov_b64 s[30:31], 0xb0000
	global_store_dwordx4 v[166:167], v[36:39], off
	global_store_dwordx4 v[162:163], v[28:31], off offset:16
	global_store_dwordx4 v[162:163], v[16:19], off offset:512
	global_store_dwordx4 v[162:163], v[8:11], off offset:528
	v_lshl_add_u64 v[162:163], v[164:165], 0, s[30:31]
	v_add_co_u32_e32 v164, vcc, 0xb0000, v164
	s_nop 1
	v_addc_co_u32_e32 v165, vcc, 0, v165, vcc
	global_store_dwordx4 v[164:165], v[20:23], off
	global_store_dwordx4 v[162:163], v[12:15], off offset:16
	global_store_dwordx4 v[162:163], v[4:7], off offset:512
	global_store_dwordx4 v[162:163], v[0:3], off offset:528
	s_cbranch_execnz .LBB0_441
	s_branch .LBB0_440

; #define PG8_STAGE(bufoff, gbase, voff) do { _Pragma("unroll") for (int _i = 0; _i < 2; ++_i) \
;         __builtin_amdgcn_global_load_lds((const unsigned*)((const char*)(gbase) + (voff)[_i]), (LAS unsigned*)(lds + (bufoff) + ldsw + _i * 8192), 16, 0, 0); } while (0)
; #define PG8_WAIT_V(n) asm volatile("s_waitcnt vmcnt(" #n ")" ::: "memory")
; #define PG8_BAR __builtin_amdgcn_s_barrier()
; template <class Epi>
; __device__ __forceinline__ void gemm_phase(LAS unsigned char* lds, const Gemm g, const StaticOrder& S, const Epi& E) {
;     ...
;     for (int i = 0; i < 2; ++i) { int R, C; stage_rc(tid * 16 + i * 8192, R, C); const int Rb = Epi::PERM ? ((R & ~31) + perm32(R & 31)) : R;
;         voffA[i] = (unsigned)(R * lda + C) * 2u; voffB[i] = (unsigned)(Rb * K + C) * 2u; }
;     const size_t kstep = (size_t)(BK * 2);
;     const size_t hstepA = (size_t)HALF * lda * 2, hstepB = (size_t)HALF * K * 2;
;     const size_t tstepA = 2 * hstepA, tstepB = 2 * hstepB;
;     const unsigned ldsw = (unsigned)wid * 1024u;
;     const int aoff = lds_byte(wr * 64 + fr, fq * 8), boff = lds_byte(wc * 32 + fr, fq * 8);
;     ...
;     Unit cur, nxt; int ui = 0;
;     if (!S.next(0, cur)) return;
;     f32x4 acc[2][2][4][2];
; #pragma unroll
;     for (int a = 0; a < 2; ++a)
; #pragma unroll
;         for (int b = 0; b < 2; ++b)
; #pragma unroll
;             for (int m = 0; m < 4; ++m)
; #pragma unroll
;                 for (int n = 0; n < 2; ++n) acc[a][b][m][n] = (f32x4){0.f, 0.f, 0.f, 0.f};
;     bf16x8 At[4][2], B0[2][2], B1[2][2];
;     const char* cA = (const char*)g.A + (size_t)cur.pm * tstepA + (size_t)cur.kt0 * kstep; const char* cB = (const char*)g.Bt + (size_t)cur.pn * tstepB + (size_t)cur.kt0 * kstep;
;     PG8_STAGE(PG8_SB(0, 0), cB, voffB); PG8_STAGE(PG8_SA(0, 0), cA, voffA); PG8_STAGE(PG8_SB(0, 1), cB + hstepB, voffB); PG8_STAGE(PG8_SA(0, 1), cA + hstepA, voffA);
;     if (wr == 1) PG8_BAR;
;     PG8_WAIT_V(4); PG8_BAR;
;     PG8_STAGE(PG8_SB(1, 0), cB + kstep, voffB); PG8_STAGE(PG8_SA(1, 0), cA + kstep, voffA); PG8_STAGE(PG8_SB(1, 1), cB + hstepB + kstep, voffB);
;     PG8_WAIT_V(6); PG8_BAR;
.LBB0_673:
	s_lshl_b32 s6, s6, 5
	s_mov_b64 s[28:29], 0x80
	s_and_b32 s36, s6, 0x60
	s_add_i32 m0, s35, 0x18000
	v_lshl_add_u64 v[6:7], v[6:7], 0, s[28:29]
	s_lshl_b32 s70, s1, 6
	s_lshl_b32 s1, s1, 13
	s_lshl_b32 s37, s36, 7
	s_waitcnt vmcnt(0)
	s_barrier
	global_load_lds_dwordx4 v[6:7], off
	v_lshl_add_u64 v[4:5], v[4:5], 0, s[28:29]
	s_add_i32 m0, s35, 0x1a000
	s_add_i32 s71, s35, 0x8000
	s_add_i32 s72, s35, 0xa000
	global_load_lds_dwordx4 v[4:5], off
	v_lshl_add_u64 v[2:3], v[2:3], 0, s[28:29]
	s_mov_b32 m0, s71
	s_add_u32 s6, s62, 0x40080
	global_load_lds_dwordx4 v[2:3], off
	v_lshl_add_u64 v[0:1], v[0:1], 0, s[28:29]
	s_mov_b32 m0, s72
	s_addc_u32 s7, s63, 0
	global_load_lds_dwordx4 v[0:1], off
	s_add_i32 m0, s35, 0x1c000
	v_lshl_add_u64 v[0:1], s[6:7], 0, v[138:139]
	global_load_lds_dwordx4 v[0:1], off
	v_lshl_add_u64 v[0:1], s[6:7], 0, v[142:143]
	s_add_i32 m0, s35, 0x1e000
	s_sext_i32_i8 s59, s0
	global_load_lds_dwordx4 v[0:1], off
	v_and_b32_e32 v135, 15, v129
	v_lshlrev_b32_e32 v0, 1, v11
	v_lshlrev_b32_e32 v2, 2, v129
	v_lshlrev_b32_e32 v3, 6, v129
	s_movk_i32 s0, 0x3c0
	v_lshl_or_b32 v1, v135, 6, v0
	v_and_b32_e32 v2, 32, v2
	v_and_or_b32 v0, v3, s0, v0
	v_bitop3_b32 v156, s37, v0, v2 bitop3:0xf6
	v_lshlrev_b32_e32 v0, 8, v129
	v_bitop3_b32 v1, v1, s1, v2 bitop3:0xde
	v_and_b32_e32 v0, 0x38000, v0
	v_lshlrev_b32_e32 v2, 11, v10
	v_or3_b32 v0, v8, v0, v2
	v_add_u32_e32 v144, v0, v9
	v_lshlrev_b32_e32 v0, 4, v12
	s_waitcnt vmcnt(6)
	v_and_b32_e32 v0, 0x78000, v0
	v_or3_b32 v0, v8, v0, v2
	s_add_i32 s75, 0, 0x10000
	s_add_i32 s76, 0, 0x14000
	v_cmp_lt_u32_e64 s[0:1], 13, v135
	v_add_u32_e32 v157, -14, v135
	s_ashr_i32 s73, s14, 31
	s_mov_b32 s74, s14
	v_or_b32_e32 v158, s36, v11
	v_mov_b32_e32 v145, v139
	v_add_u32_e32 v146, v0, v9
	v_mov_b32_e32 v147, v139
	v_mov_b64_e32 v[148:149], 0x5ac
	v_mov_b64_e32 v[150:151], 0x5ab
	v_add_u32_e32 v159, s75, v156
	v_add_u32_e32 v160, 0, v1
	v_add_u32_e32 v161, s76, v156
	s_movk_i32 s77, 0x2c00
	s_barrier
	s_branch .LBB0_675

; #define PG8_STAGE(bufoff, gbase, voff) do { _Pragma("unroll") for (int _i = 0; _i < 2; ++_i) \
;         __builtin_amdgcn_global_load_lds((const unsigned*)((const char*)(gbase) + (voff)[_i]), (LAS unsigned*)(lds + (bufoff) + ldsw + _i * 8192), 16, 0, 0); } while (0)
; #define PG8_LDA(dst, b, h) do { _Pragma("unroll") for (int m = 0; m < 4; ++m) _Pragma("unroll") for (int k = 0; k < 2; ++k) dst[m][k] = *(const LAS bf16x8*)(lds + PG8_SA(b, h) + aoff + m * 2048 + k * 1024); } while (0)
; #define PG8_LDB(dst, b, h) do { _Pragma("unroll") for (int n = 0; n < 2; ++n) _Pragma("unroll") for (int k = 0; k < 2; ++k) dst[n][k] = *(const LAS bf16x8*)(lds + PG8_SB(b, h) + boff + n * 2048 + k * 1024); } while (0)
; #define PG8_MMA(ai, bj, At, Bt) do { __builtin_amdgcn_s_setprio(1); _Pragma("unroll") for (int m = 0; m < 4; ++m) _Pragma("unroll") for (int n = 0; n < 2; ++n) _Pragma("unroll") for (int k = 0; k < 2; ++k) \
;         acc[ai][bj][m][n] = __builtin_amdgcn_mfma_f32_16x16x32_bf16(Bt[n][k], At[m][k], acc[ai][bj][m][n], 0, 0, 0); __builtin_amdgcn_s_setprio(0); } while (0)
; #define PG8_WAIT_V(n) asm volatile("s_waitcnt vmcnt(" #n ")" ::: "memory")
; #define PG8_WAIT_L(n) asm volatile("s_waitcnt lgkmcnt(" #n ")" ::: "memory")
; template <class Epi>
; __device__ __forceinline__ void gemm_phase(LAS unsigned char* lds, const Gemm g, const StaticOrder& S, const Epi& E) {
;     ...
;         for (int t = 0; t < nt; t += 2) {
;             const bool last = (t == nt - 2);
;             const char* a1 = cA + (size_t)(t + 1) * kstep;
;             const char* a2 = last ? nA : cA + (size_t)(t + 2) * kstep; const char* b2 = last ? nB : cB + (size_t)(t + 2) * kstep;
;             const char* a3 = a2 + kstep; const char* b3 = b2 + kstep;
;             PG8_LDB(B0, 0, 0); PG8_SCHED; PG8_LDA(At, 0, 0); PG8_STAGE(PG8_SA(1, 1), a1 + hstepA, voffA);
;             PG8_WAIT_L(8); PG8_BAR; PG8_WAIT_L(0); PG8_MMA(0, 0, At, B0); PG8_BAR; PG8_SCHED;
;             PG8_LDB(B1, 0, 1); PG8_STAGE(PG8_SB(0, 0), b2, voffB);
;             PG8_BAR; PG8_WAIT_L(0); PG8_MMA(0, 1, At, B1); PG8_BAR;
;             PG8_LDA(At, 0, 1); PG8_STAGE(PG8_SA(0, 0), a2, voffA);
;             PG8_BAR; PG8_WAIT_L(0); PG8_MMA(1, 0, At, B0); PG8_BAR; PG8_SCHED;
;             PG8_STAGE(PG8_SB(0, 1), b2 + hstepB, voffB);
;             PG8_WAIT_V(6); PG8_BAR; PG8_MMA(1, 1, At, B1); PG8_BAR;
.LBB0_682:
	s_add_u32 s62, s60, 0xfffc0080
	s_addc_u32 s63, s61, -1
	s_cmp_eq_u32 s78, 12
	s_cselect_b32 s65, s41, s63
	s_cselect_b32 s64, s40, s62
	s_cselect_b32 s63, s57, s39
	s_cselect_b32 s62, s56, s37
	ds_read_b128 v[152:155], v159
	ds_read_b128 v[162:165], v159 offset:1024
	ds_read_b128 v[166:169], v159 offset:2048
	ds_read_b128 v[170:173], v159 offset:3072
	ds_read_b128 v[174:177], v160
	ds_read_b128 v[178:181], v160 offset:1024
	ds_read_b128 v[182:185], v160 offset:2048
	ds_read_b128 v[186:189], v160 offset:3072
	ds_read_b128 v[190:193], v160 offset:4096
	ds_read_b128 v[194:197], v160 offset:5120
	ds_read_b128 v[198:201], v160 offset:6144
	ds_read_b128 v[202:205], v160 offset:7168
	ds_read_b128 v[206:209], v161
	ds_read_b128 v[210:213], v161 offset:1024
	ds_read_b128 v[214:217], v161 offset:2048
	ds_read_b128 v[218:221], v161 offset:3072
	v_lshl_add_u64 v[242:243], s[60:61], 0, v[144:145]
	s_add_i32 m0, s35, 0xc000
	s_nop 0
	global_load_lds_dwordx4 v[242:243], off
	v_lshl_add_u64 v[242:243], s[60:61], 0, v[146:147]
	s_add_i32 m0, s35, 0xe000
	s_nop 0
	global_load_lds_dwordx4 v[242:243], off
	s_waitcnt vmcnt(8) lgkmcnt(0)
	s_barrier
	v_mfma_f32_16x16x32_bf16 v[124:127], v[152:155], v[174:177], v[124:127]
	v_mfma_f32_16x16x32_bf16 v[120:123], v[166:169], v[174:177], v[120:123]
	v_mfma_f32_16x16x32_bf16 v[116:119], v[152:155], v[182:185], v[116:119]
	v_mfma_f32_16x16x32_bf16 v[108:111], v[166:169], v[182:185], v[108:111]
	v_mfma_f32_16x16x32_bf16 v[100:103], v[152:155], v[190:193], v[100:103]
	v_mfma_f32_16x16x32_bf16 v[92:95], v[166:169], v[190:193], v[92:95]
	v_mfma_f32_16x16x32_bf16 v[84:87], v[152:155], v[198:201], v[84:87]
	v_mfma_f32_16x16x32_bf16 v[76:79], v[166:169], v[198:201], v[76:79]
	v_mfma_f32_16x16x32_bf16 v[124:127], v[162:165], v[178:181], v[124:127]
	v_mfma_f32_16x16x32_bf16 v[120:123], v[170:173], v[178:181], v[120:123]
	v_mfma_f32_16x16x32_bf16 v[116:119], v[162:165], v[186:189], v[116:119]
	v_mfma_f32_16x16x32_bf16 v[108:111], v[170:173], v[186:189], v[108:111]
	v_mfma_f32_16x16x32_bf16 v[100:103], v[162:165], v[194:197], v[100:103]
	v_mfma_f32_16x16x32_bf16 v[92:95], v[170:173], v[194:197], v[92:95]
	v_mfma_f32_16x16x32_bf16 v[84:87], v[162:165], v[202:205], v[84:87]
	v_mfma_f32_16x16x32_bf16 v[76:79], v[170:173], v[202:205], v[76:79]
	v_mfma_f32_16x16x32_bf16 v[112:115], v[206:209], v[174:177], v[112:115]
	v_mfma_f32_16x16x32_bf16 v[104:107], v[214:217], v[174:177], v[104:107]
	v_mfma_f32_16x16x32_bf16 v[96:99], v[206:209], v[182:185], v[96:99]
	v_mfma_f32_16x16x32_bf16 v[88:91], v[214:217], v[182:185], v[88:91]
	v_mfma_f32_16x16x32_bf16 v[80:83], v[206:209], v[190:193], v[80:83]
	v_mfma_f32_16x16x32_bf16 v[72:75], v[214:217], v[190:193], v[72:75]
	v_mfma_f32_16x16x32_bf16 v[68:71], v[206:209], v[198:201], v[68:71]
	v_mfma_f32_16x16x32_bf16 v[64:67], v[214:217], v[198:201], v[64:67]
	v_mfma_f32_16x16x32_bf16 v[112:115], v[210:213], v[178:181], v[112:115]
	v_mfma_f32_16x16x32_bf16 v[104:107], v[218:221], v[178:181], v[104:107]
	v_mfma_f32_16x16x32_bf16 v[96:99], v[210:213], v[186:189], v[96:99]
	v_mfma_f32_16x16x32_bf16 v[88:91], v[218:221], v[186:189], v[88:91]
	v_mfma_f32_16x16x32_bf16 v[80:83], v[210:213], v[194:197], v[80:83]
	v_mfma_f32_16x16x32_bf16 v[72:75], v[218:221], v[194:197], v[72:75]
	v_mfma_f32_16x16x32_bf16 v[68:71], v[210:213], v[202:205], v[68:71]
	v_mfma_f32_16x16x32_bf16 v[64:67], v[218:221], v[202:205], v[64:67]
	s_barrier
	ds_read_b128 v[174:177], v160 offset:16384
	ds_read_b128 v[178:181], v160 offset:17408
	ds_read_b128 v[182:185], v160 offset:18432
	ds_read_b128 v[186:189], v160 offset:19456
	ds_read_b128 v[190:193], v160 offset:20480
	ds_read_b128 v[194:197], v160 offset:21504
	ds_read_b128 v[198:201], v160 offset:22528
	ds_read_b128 v[202:205], v160 offset:23552
	s_add_i32 s79, s75, s33
	v_lshl_add_u64 v[222:223], s[62:63], 0, v[138:139]
	s_mov_b32 m0, s79
	s_nop 0
	global_load_lds_dwordx4 v[222:223], off
	v_lshl_add_u64 v[224:225], s[62:63], 0, v[142:143]
	s_add_i32 m0, s79, 0x2000
	s_nop 0
	global_load_lds_dwordx4 v[224:225], off
	s_mov_b32 m0, s35
	v_lshl_add_u64 v[226:227], s[64:65], 0, v[136:137]
	global_load_lds_dwordx4 v[226:227], off
	v_lshl_add_u64 v[228:229], s[64:65], 0, v[140:141]
	s_mov_b32 m0, s66
	s_nop 0
	global_load_lds_dwordx4 v[228:229], off
	s_add_u32 s80, s62, 0x40000
	s_addc_u32 s81, s63, 0
	s_add_i32 s79, s76, s33
	v_lshl_add_u64 v[240:241], s[80:81], 0, v[138:139]
	s_mov_b32 m0, s79
	s_nop 0
	global_load_lds_dwordx4 v[240:241], off
	v_lshl_add_u64 v[240:241], s[80:81], 0, v[142:143]
	s_add_i32 m0, s79, 0x2000
	s_nop 0
	global_load_lds_dwordx4 v[240:241], off
	s_waitcnt vmcnt(8) lgkmcnt(0)
	s_barrier
; #define PG8_STAGE(bufoff, gbase, voff) do { _Pragma("unroll") for (int _i = 0; _i < 2; ++_i) \
;         __builtin_amdgcn_global_load_lds((const unsigned*)((const char*)(gbase) + (voff)[_i]), (LAS unsigned*)(lds + (bufoff) + ldsw + _i * 8192), 16, 0, 0); } while (0)
; #define PG8_LDA(dst, b, h) do { _Pragma("unroll") for (int m = 0; m < 4; ++m) _Pragma("unroll") for (int k = 0; k < 2; ++k) dst[m][k] = *(const LAS bf16x8*)(lds + PG8_SA(b, h) + aoff + m * 2048 + k * 1024); } while (0)
; #define PG8_LDB(dst, b, h) do { _Pragma("unroll") for (int n = 0; n < 2; ++n) _Pragma("unroll") for (int k = 0; k < 2; ++k) dst[n][k] = *(const LAS bf16x8*)(lds + PG8_SB(b, h) + boff + n * 2048 + k * 1024); } while (0)
; #define PG8_MMA(ai, bj, At, Bt) do { __builtin_amdgcn_s_setprio(1); _Pragma("unroll") for (int m = 0; m < 4; ++m) _Pragma("unroll") for (int n = 0; n < 2; ++n) _Pragma("unroll") for (int k = 0; k < 2; ++k) \
;         acc[ai][bj][m][n] = __builtin_amdgcn_mfma_f32_16x16x32_bf16(Bt[n][k], At[m][k], acc[ai][bj][m][n], 0, 0, 0); __builtin_amdgcn_s_setprio(0); } while (0)
; #define PG8_WAIT_V(n) asm volatile("s_waitcnt vmcnt(" #n ")" ::: "memory")
; #define PG8_WAIT_L(n) asm volatile("s_waitcnt lgkmcnt(" #n ")" ::: "memory")
; #define PG8_BAR __builtin_amdgcn_s_barrier()
; #define PG8_SCHED __builtin_amdgcn_sched_barrier(0)
; template <class Epi>
; __device__ __forceinline__ void gemm_phase(LAS unsigned char* lds, const Gemm g, const StaticOrder& S, const Epi& E) {
;     ...
;             PG8_BAR; PG8_WAIT_L(0); PG8_MMA(1, 0, At, B0); PG8_BAR; PG8_SCHED;
;             PG8_STAGE(PG8_SB(0, 1), b2 + hstepB, voffB);
;             PG8_WAIT_V(6); PG8_BAR; PG8_MMA(1, 1, At, B1); PG8_BAR;
;             PG8_LDB(B0, 1, 0); PG8_SCHED; PG8_LDA(At, 1, 0); PG8_STAGE(PG8_SA(0, 1), a2 + hstepA, voffA);
;             PG8_WAIT_L(8); PG8_BAR; PG8_WAIT_L(0); PG8_MMA(0, 0, At, B0); PG8_BAR; PG8_SCHED;
;             PG8_LDB(B1, 1, 1); PG8_STAGE(PG8_SB(1, 0), b3, voffB);
;             PG8_BAR; PG8_WAIT_L(0); PG8_MMA(0, 1, At, B1); PG8_BAR;
	v_mfma_f32_16x16x32_bf16 v[60:63], v[152:155], v[174:177], v[60:63]
	v_mfma_f32_16x16x32_bf16 v[56:59], v[166:169], v[174:177], v[56:59]
	v_mfma_f32_16x16x32_bf16 v[52:55], v[152:155], v[182:185], v[52:55]
	v_mfma_f32_16x16x32_bf16 v[44:47], v[166:169], v[182:185], v[44:47]
	v_mfma_f32_16x16x32_bf16 v[36:39], v[152:155], v[190:193], v[36:39]
	v_mfma_f32_16x16x32_bf16 v[28:31], v[166:169], v[190:193], v[28:31]
	v_mfma_f32_16x16x32_bf16 v[20:23], v[152:155], v[198:201], v[20:23]
	v_mfma_f32_16x16x32_bf16 v[12:15], v[166:169], v[198:201], v[12:15]
	v_mfma_f32_16x16x32_bf16 v[60:63], v[162:165], v[178:181], v[60:63]
	v_mfma_f32_16x16x32_bf16 v[56:59], v[170:173], v[178:181], v[56:59]
	v_mfma_f32_16x16x32_bf16 v[52:55], v[162:165], v[186:189], v[52:55]
	v_mfma_f32_16x16x32_bf16 v[44:47], v[170:173], v[186:189], v[44:47]
	v_mfma_f32_16x16x32_bf16 v[36:39], v[162:165], v[194:197], v[36:39]
	v_mfma_f32_16x16x32_bf16 v[28:31], v[170:173], v[194:197], v[28:31]
	v_mfma_f32_16x16x32_bf16 v[20:23], v[162:165], v[202:205], v[20:23]
	v_mfma_f32_16x16x32_bf16 v[12:15], v[170:173], v[202:205], v[12:15]
	v_mfma_f32_16x16x32_bf16 v[48:51], v[206:209], v[174:177], v[48:51]
	v_mfma_f32_16x16x32_bf16 v[40:43], v[214:217], v[174:177], v[40:43]
	v_mfma_f32_16x16x32_bf16 v[32:35], v[206:209], v[182:185], v[32:35]
	v_mfma_f32_16x16x32_bf16 v[24:27], v[214:217], v[182:185], v[24:27]
	v_mfma_f32_16x16x32_bf16 v[16:19], v[206:209], v[190:193], v[16:19]
	v_mfma_f32_16x16x32_bf16 v[8:11], v[214:217], v[190:193], v[8:11]
	v_mfma_f32_16x16x32_bf16 v[4:7], v[206:209], v[198:201], v[4:7]
	v_mfma_f32_16x16x32_bf16 v[0:3], v[214:217], v[198:201], v[0:3]
	v_mfma_f32_16x16x32_bf16 v[48:51], v[210:213], v[178:181], v[48:51]
	v_mfma_f32_16x16x32_bf16 v[40:43], v[218:221], v[178:181], v[40:43]
	v_mfma_f32_16x16x32_bf16 v[32:35], v[210:213], v[186:189], v[32:35]
	v_mfma_f32_16x16x32_bf16 v[24:27], v[218:221], v[186:189], v[24:27]
	v_mfma_f32_16x16x32_bf16 v[16:19], v[210:213], v[194:197], v[16:19]
	v_mfma_f32_16x16x32_bf16 v[8:11], v[218:221], v[194:197], v[8:11]
	v_mfma_f32_16x16x32_bf16 v[4:7], v[210:213], v[202:205], v[4:7]
	v_mfma_f32_16x16x32_bf16 v[0:3], v[218:221], v[202:205], v[0:3]
	s_barrier
	s_add_i32 s79, 0, 0x18000
	v_add_u32_e32 v170, s79, v156
	ds_read_b128 v[152:155], v170
	ds_read_b128 v[162:165], v170 offset:1024
	ds_read_b128 v[166:169], v170 offset:2048
	ds_read_b128 v[170:173], v170 offset:3072
	ds_read_b128 v[174:177], v160 offset:32768
	ds_read_b128 v[178:181], v160 offset:33792
	ds_read_b128 v[182:185], v160 offset:34816
	ds_read_b128 v[186:189], v160 offset:35840
	ds_read_b128 v[190:193], v160 offset:36864
	ds_read_b128 v[194:197], v160 offset:37888
	ds_read_b128 v[198:201], v160 offset:38912
	ds_read_b128 v[202:205], v160 offset:39936
	s_add_i32 s98, 0, 0x1c000
	v_add_u32_e32 v218, s98, v156
	ds_read_b128 v[206:209], v218
	ds_read_b128 v[210:213], v218 offset:1024
	ds_read_b128 v[214:217], v218 offset:2048
	ds_read_b128 v[218:221], v218 offset:3072
	s_add_u32 s64, s64, 0x40000
	s_addc_u32 s65, s65, 0
	s_mov_b32 m0, s67
	v_lshl_add_u64 v[244:245], s[64:65], 0, v[136:137]
	global_load_lds_dwordx4 v[244:245], off
	v_lshl_add_u64 v[244:245], s[64:65], 0, v[140:141]
	s_mov_b32 m0, s68
	s_nop 0
	global_load_lds_dwordx4 v[244:245], off
	s_waitcnt vmcnt(8) lgkmcnt(0)
	s_barrier
	v_mfma_f32_16x16x32_bf16 v[124:127], v[152:155], v[174:177], v[124:127]
	v_mfma_f32_16x16x32_bf16 v[120:123], v[166:169], v[174:177], v[120:123]
	v_mfma_f32_16x16x32_bf16 v[116:119], v[152:155], v[182:185], v[116:119]
	v_mfma_f32_16x16x32_bf16 v[108:111], v[166:169], v[182:185], v[108:111]
	v_mfma_f32_16x16x32_bf16 v[100:103], v[152:155], v[190:193], v[100:103]
	v_mfma_f32_16x16x32_bf16 v[92:95], v[166:169], v[190:193], v[92:95]
	v_mfma_f32_16x16x32_bf16 v[84:87], v[152:155], v[198:201], v[84:87]
	v_mfma_f32_16x16x32_bf16 v[76:79], v[166:169], v[198:201], v[76:79]
	v_mfma_f32_16x16x32_bf16 v[124:127], v[162:165], v[178:181], v[124:127]
	v_mfma_f32_16x16x32_bf16 v[120:123], v[170:173], v[178:181], v[120:123]
	v_mfma_f32_16x16x32_bf16 v[116:119], v[162:165], v[186:189], v[116:119]
	v_mfma_f32_16x16x32_bf16 v[108:111], v[170:173], v[186:189], v[108:111]
	v_mfma_f32_16x16x32_bf16 v[100:103], v[162:165], v[194:197], v[100:103]
	v_mfma_f32_16x16x32_bf16 v[92:95], v[170:173], v[194:197], v[92:95]
	v_mfma_f32_16x16x32_bf16 v[84:87], v[162:165], v[202:205], v[84:87]
	v_mfma_f32_16x16x32_bf16 v[76:79], v[170:173], v[202:205], v[76:79]
	v_mfma_f32_16x16x32_bf16 v[112:115], v[206:209], v[174:177], v[112:115]
	v_mfma_f32_16x16x32_bf16 v[104:107], v[214:217], v[174:177], v[104:107]
	v_mfma_f32_16x16x32_bf16 v[96:99], v[206:209], v[182:185], v[96:99]
	v_mfma_f32_16x16x32_bf16 v[88:91], v[214:217], v[182:185], v[88:91]
	v_mfma_f32_16x16x32_bf16 v[80:83], v[206:209], v[190:193], v[80:83]
	v_mfma_f32_16x16x32_bf16 v[72:75], v[214:217], v[190:193], v[72:75]
	v_mfma_f32_16x16x32_bf16 v[68:71], v[206:209], v[198:201], v[68:71]
	v_mfma_f32_16x16x32_bf16 v[64:67], v[214:217], v[198:201], v[64:67]
	v_mfma_f32_16x16x32_bf16 v[112:115], v[210:213], v[178:181], v[112:115]
	v_mfma_f32_16x16x32_bf16 v[104:107], v[218:221], v[178:181], v[104:107]
	v_mfma_f32_16x16x32_bf16 v[96:99], v[210:213], v[186:189], v[96:99]
	v_mfma_f32_16x16x32_bf16 v[88:91], v[218:221], v[186:189], v[88:91]
	v_mfma_f32_16x16x32_bf16 v[80:83], v[210:213], v[194:197], v[80:83]
	v_mfma_f32_16x16x32_bf16 v[72:75], v[218:221], v[194:197], v[72:75]
	v_mfma_f32_16x16x32_bf16 v[68:71], v[210:213], v[202:205], v[68:71]
	v_mfma_f32_16x16x32_bf16 v[64:67], v[218:221], v[202:205], v[64:67]
	s_barrier
; __device__ __forceinline__ unsigned pk2(float lo, float hi) { unsigned r; asm("v_cvt_pk_bf16_f32 %0, %1, %2" : "=v"(r) : "v"(lo), "v"(hi)); return r; }
; __device__ __forceinline__ float gelu_t(float x) { return x * __builtin_amdgcn_rcpf(1.f + __expf(-1.5957691216057308f * (x + 0.044715f * x * x * x))); }
; #define PG8_STAGE(bufoff, gbase, voff) do { _Pragma("unroll") for (int _i = 0; _i < 2; ++_i) \
;         __builtin_amdgcn_global_load_lds((const unsigned*)((const char*)(gbase) + (voff)[_i]), (LAS unsigned*)(lds + (bufoff) + ldsw + _i * 8192), 16, 0, 0); } while (0)
; #define PG8_LDA(dst, b, h) do { _Pragma("unroll") for (int m = 0; m < 4; ++m) _Pragma("unroll") for (int k = 0; k < 2; ++k) dst[m][k] = *(const LAS bf16x8*)(lds + PG8_SA(b, h) + aoff + m * 2048 + k * 1024); } while (0)
; #define PG8_WAIT_V(n) asm volatile("s_waitcnt vmcnt(" #n ")" ::: "memory")
; #define PG8_WAIT_L(n) asm volatile("s_waitcnt lgkmcnt(" #n ")" ::: "memory")
;     __device__ __forceinline__ void operator()(const f32x4 (&acc)[2][2][4][2], const Unit& u, int wr, int wc, int fr, int fq) const {
;     ...
; #pragma unroll
;         for (int ai = 0; ai < 2; ++ai)
; #pragma unroll
;             for (int m = 0; m < 4; ++m) { const int row = row0 + ai * HALF + m * 16; u16* rowp = O + (size_t)row * ldc + col0;
; #pragma unroll
;                 for (int bj = 0; bj < 2; ++bj) { f32x4 v0 = acc[ai][bj][m][0], v1 = acc[ai][bj][m][1];
;                     if (col0 + bj * HALF >= gelu_from) { v0 = (f32x4){gelu_t(v0.x), gelu_t(v0.y), gelu_t(v0.z), gelu_t(v0.w)}; v1 = (f32x4){gelu_t(v1.x), gelu_t(v1.y), gelu_t(v1.z), gelu_t(v1.w)}; }
;                     u32x4 w; w.x = pk2(v0[0], v0[1]); w.y = pk2(v0[2], v0[3]); w.z = pk2(v1[0], v1[1]); w.w = pk2(v1[2], v1[3]);
;                     *(u32x4*)(rowp + bj * HALF) = w;
;                     if (halo != nullptr && m == 3 && fr >= 14) *(u32x4*)(halo + (size_t)((row >> 6) * 2 + (fr - 14)) * ldc + col0 + bj * HALF) = w; } }
; template <class Epi>
; __device__ __forceinline__ void gemm_phase(LAS unsigned char* lds, const Gemm g, const StaticOrder& S, const Epi& E) {
;     ...
;             PG8_LDA(At, 1, 1); PG8_STAGE(PG8_SA(1, 0), a3, voffA);
;             PG8_BAR; PG8_WAIT_L(0); PG8_MMA(1, 0, At, B0); PG8_BAR; PG8_SCHED;
;             PG8_STAGE(PG8_SB(1, 1), b3 + hstepB, voffB);
;             PG8_WAIT_V(6); PG8_BAR; PG8_MMA(1, 1, At, B1); PG8_BAR;
	ds_read_b128 v[174:177], v160 offset:49152
	ds_read_b128 v[178:181], v160 offset:50176
	ds_read_b128 v[182:185], v160 offset:51200
	ds_read_b128 v[186:189], v160 offset:52224
	ds_read_b128 v[190:193], v160 offset:53248
	ds_read_b128 v[194:197], v160 offset:54272
	ds_read_b128 v[198:201], v160 offset:55296
	ds_read_b128 v[202:205], v160 offset:56320
	s_add_i32 s65, s79, s33
	v_lshl_add_u64 v[222:223], v[222:223], 0, s[28:29]
	s_mov_b32 m0, s65
	s_nop 0
	global_load_lds_dwordx4 v[222:223], off
	v_lshl_add_u64 v[222:223], v[224:225], 0, s[28:29]
	s_add_i32 m0, s65, 0x2000
	s_nop 0
	global_load_lds_dwordx4 v[222:223], off
	s_mov_b32 m0, s71
	v_lshl_add_u64 v[222:223], v[226:227], 0, s[28:29]
	global_load_lds_dwordx4 v[222:223], off
	v_lshl_add_u64 v[222:223], v[228:229], 0, s[28:29]
	s_mov_b32 m0, s72
	s_nop 0
	global_load_lds_dwordx4 v[222:223], off
	s_add_u32 s62, s62, 0x40080
	s_addc_u32 s63, s63, 0
	s_add_i32 s64, s98, s33
	v_lshl_add_u64 v[240:241], s[62:63], 0, v[138:139]
	s_mov_b32 m0, s64
	s_nop 0
	global_load_lds_dwordx4 v[240:241], off
	v_lshl_add_u64 v[240:241], s[62:63], 0, v[142:143]
	s_add_i32 m0, s64, 0x2000
	s_nop 0
	global_load_lds_dwordx4 v[240:241], off
	s_waitcnt vmcnt(8) lgkmcnt(0)
	s_barrier
	v_mfma_f32_16x16x32_bf16 v[60:63], v[152:155], v[174:177], v[60:63]
	v_mfma_f32_16x16x32_bf16 v[56:59], v[166:169], v[174:177], v[56:59]
	v_mfma_f32_16x16x32_bf16 v[52:55], v[152:155], v[182:185], v[52:55]
	v_mfma_f32_16x16x32_bf16 v[44:47], v[166:169], v[182:185], v[44:47]
	v_mfma_f32_16x16x32_bf16 v[36:39], v[152:155], v[190:193], v[36:39]
	v_mfma_f32_16x16x32_bf16 v[28:31], v[166:169], v[190:193], v[28:31]
	v_mfma_f32_16x16x32_bf16 v[20:23], v[152:155], v[198:201], v[20:23]
	v_mfma_f32_16x16x32_bf16 v[12:15], v[166:169], v[198:201], v[12:15]
	v_mfma_f32_16x16x32_bf16 v[60:63], v[162:165], v[178:181], v[60:63]
	v_mfma_f32_16x16x32_bf16 v[56:59], v[170:173], v[178:181], v[56:59]
	v_mfma_f32_16x16x32_bf16 v[52:55], v[162:165], v[186:189], v[52:55]
	v_mfma_f32_16x16x32_bf16 v[44:47], v[170:173], v[186:189], v[44:47]
	v_mfma_f32_16x16x32_bf16 v[36:39], v[162:165], v[194:197], v[36:39]
	v_mfma_f32_16x16x32_bf16 v[28:31], v[170:173], v[194:197], v[28:31]
	v_mfma_f32_16x16x32_bf16 v[20:23], v[162:165], v[202:205], v[20:23]
	v_mfma_f32_16x16x32_bf16 v[12:15], v[170:173], v[202:205], v[12:15]
	v_mfma_f32_16x16x32_bf16 v[48:51], v[206:209], v[174:177], v[48:51]
	v_mfma_f32_16x16x32_bf16 v[40:43], v[214:217], v[174:177], v[40:43]
	v_mfma_f32_16x16x32_bf16 v[32:35], v[206:209], v[182:185], v[32:35]
	v_mfma_f32_16x16x32_bf16 v[24:27], v[214:217], v[182:185], v[24:27]
	v_mfma_f32_16x16x32_bf16 v[16:19], v[206:209], v[190:193], v[16:19]
	v_mfma_f32_16x16x32_bf16 v[8:11], v[214:217], v[190:193], v[8:11]
	v_mfma_f32_16x16x32_bf16 v[4:7], v[206:209], v[198:201], v[4:7]
	v_mfma_f32_16x16x32_bf16 v[0:3], v[214:217], v[198:201], v[0:3]
	v_mfma_f32_16x16x32_bf16 v[48:51], v[210:213], v[178:181], v[48:51]
	v_mfma_f32_16x16x32_bf16 v[40:43], v[218:221], v[178:181], v[40:43]
	v_mfma_f32_16x16x32_bf16 v[32:35], v[210:213], v[186:189], v[32:35]
	v_mfma_f32_16x16x32_bf16 v[24:27], v[218:221], v[186:189], v[24:27]
	v_mfma_f32_16x16x32_bf16 v[16:19], v[210:213], v[194:197], v[16:19]
	v_mfma_f32_16x16x32_bf16 v[8:11], v[218:221], v[194:197], v[8:11]
	v_mfma_f32_16x16x32_bf16 v[4:7], v[210:213], v[202:205], v[4:7]
	v_mfma_f32_16x16x32_bf16 v[0:3], v[218:221], v[202:205], v[0:3]
	s_add_i32 s78, s78, 2
	s_add_u32 s60, s60, 0x100
	s_addc_u32 s61, s61, 0
	s_add_u32 s37, s37, 0x100
	s_addc_u32 s39, s39, 0
	s_cmp_gt_u32 s78, 13
	s_barrier
	s_cbranch_scc0 .LBB0_682
	s_lshl_b32 s37, s58, 8
	s_add_i32 s37, s37, s70
	v_lshl_or_b32 v152, s59, 8, v158
	v_or_b32_e32 v162, s37, v135
	v_ashrrev_i32_e32 v153, 31, v152
	v_mov_b64_e32 v[164:165], s[4:5]
	v_mad_i64_i32 v[166:167], s[58:59], v162, s77, v[164:165]
	v_lshlrev_b64 v[154:155], 1, v[152:153]
	v_cvt_pk_bf16_f32 v112, v112, v113
	v_cvt_pk_bf16_f32 v113, v114, v115
	v_cvt_pk_bf16_f32 v114, v104, v105
	v_or_b32_e32 v104, 16, v162
	v_lshl_add_u64 v[166:167], v[166:167], 0, v[154:155]
	v_mad_i64_i32 v[104:105], s[58:59], v104, s77, v[164:165]
	v_cvt_pk_bf16_f32 v96, v96, v97
	v_cvt_pk_bf16_f32 v97, v98, v99
	v_cvt_pk_bf16_f32 v98, v88, v89
	v_or_b32_e32 v88, 32, v162
	v_cvt_pk_bf16_f32 v115, v106, v107
	global_store_dwordx4 v[166:167], v[112:115], off offset:256
	v_mad_i64_i32 v[88:89], s[58:59], v88, s77, v[164:165]
	s_nop 0
	v_lshl_add_u64 v[112:113], v[104:105], 0, v[154:155]
	v_cvt_pk_bf16_f32 v80, v80, v81
	v_cvt_pk_bf16_f32 v81, v82, v83
	v_cvt_pk_bf16_f32 v82, v72, v73
	v_or_b32_e32 v72, 48, v162
	s_ashr_i32 s37, s37, 5
	v_cvt_pk_bf16_f32 v99, v90, v91
	global_store_dwordx4 v[112:113], v[96:99], off offset:256
	v_mad_i64_i32 v[72:73], s[58:59], v72, s77, v[164:165]
	s_nop 0
	v_lshl_add_u64 v[96:97], v[88:89], 0, v[154:155]
	v_add_u32_e32 v163, s37, v157
	v_cvt_pk_bf16_f32 v83, v74, v75
	global_store_dwordx4 v[96:97], v[80:83], off offset:256
	v_cvt_pk_bf16_f32 v124, v124, v125
	v_cvt_pk_bf16_f32 v125, v126, v127
	v_cvt_pk_bf16_f32 v126, v120, v121
	v_cvt_pk_bf16_f32 v127, v122, v123
	global_store_dwordx4 v[166:167], v[124:127], off
	s_nop 0
	v_lshl_add_u64 v[80:81], v[72:73], 0, v[154:155]
	v_cvt_pk_bf16_f32 v104, v116, v117
	v_cvt_pk_bf16_f32 v105, v118, v119
	v_cvt_pk_bf16_f32 v106, v108, v109
	v_cvt_pk_bf16_f32 v107, v110, v111
	global_store_dwordx4 v[112:113], v[104:107], off
	v_cvt_pk_bf16_f32 v88, v100, v101
	v_cvt_pk_bf16_f32 v89, v102, v103
	v_cvt_pk_bf16_f32 v90, v92, v93
	v_cvt_pk_bf16_f32 v91, v94, v95
	global_store_dwordx4 v[96:97], v[88:91], off
	v_cvt_pk_bf16_f32 v72, v84, v85
	v_cvt_pk_bf16_f32 v73, v86, v87
	v_cvt_pk_bf16_f32 v74, v76, v77
	v_cvt_pk_bf16_f32 v75, v78, v79
	global_store_dwordx4 v[80:81], v[72:75], off
	s_and_saveexec_b64 s[58:59], s[0:1]
	s_cbranch_execz .LBB0_685
	v_mov_b64_e32 v[76:77], s[18:19]
	v_mad_i64_i32 v[76:77], s[60:61], v163, s77, v[76:77]
	v_lshl_add_u64 v[76:77], v[152:153], 1, v[76:77]
	global_store_dwordx4 v[76:77], v[72:75], off

; #define PG8_STAGE(bufoff, gbase, voff) do { _Pragma("unroll") for (int _i = 0; _i < 2; ++_i) \
;         __builtin_amdgcn_global_load_lds((const unsigned*)((const char*)(gbase) + (voff)[_i]), (LAS unsigned*)(lds + (bufoff) + ldsw + _i * 8192), 16, 0, 0); } while (0)
; #define PG8_WAIT_V(n) asm volatile("s_waitcnt vmcnt(" #n ")" ::: "memory")
; #define PG8_BAR __builtin_amdgcn_s_barrier()
; template <class Epi>
; __device__ __forceinline__ void gemm_phase(LAS unsigned char* lds, const Gemm g, const StaticOrder& S, const Epi& E) {
;     ...
;     const char* cA = (const char*)g.A + (size_t)cur.pm * tstepA + (size_t)cur.kt0 * kstep; const char* cB = (const char*)g.Bt + (size_t)cur.pn * tstepB + (size_t)cur.kt0 * kstep;
;     PG8_STAGE(PG8_SB(0, 0), cB, voffB); PG8_STAGE(PG8_SA(0, 0), cA, voffA); PG8_STAGE(PG8_SB(0, 1), cB + hstepB, voffB); PG8_STAGE(PG8_SA(0, 1), cA + hstepA, voffA);
;     if (wr == 1) PG8_BAR;
;     PG8_WAIT_V(4); PG8_BAR;
;     PG8_STAGE(PG8_SB(1, 0), cB + kstep, voffB); PG8_STAGE(PG8_SA(1, 0), cA + kstep, voffA); PG8_STAGE(PG8_SB(1, 1), cB + hstepB + kstep, voffB);
;     PG8_WAIT_V(6); PG8_BAR;
.LBB0_893:
	s_lshl_b32 s0, s22, 5
	s_mov_b64 s[22:23], 0x80
	s_add_i32 m0, s33, 0x18000
	v_lshl_add_u64 v[6:7], v[6:7], 0, s[22:23]
	s_lshl_b32 s24, s18, 13
	s_and_b32 s25, s0, 0x60
	s_waitcnt vmcnt(0)
	s_barrier
	global_load_lds_dwordx4 v[6:7], off
	v_lshl_add_u64 v[4:5], v[4:5], 0, s[22:23]
	s_add_i32 m0, s33, 0x1a000
	s_add_i32 s60, s33, 0x8000
	s_add_i32 s61, s33, 0xa000
	global_load_lds_dwordx4 v[4:5], off
	v_lshl_add_u64 v[0:1], v[0:1], 0, s[22:23]
	s_mov_b32 m0, s60
	s_add_u32 s0, s54, 0xb0080
	global_load_lds_dwordx4 v[0:1], off
	v_lshl_add_u64 v[0:1], v[2:3], 0, s[22:23]
	s_mov_b32 m0, s61
	s_addc_u32 s1, s55, 0
	global_load_lds_dwordx4 v[0:1], off
	s_add_i32 m0, s33, 0x1c000
	v_lshl_add_u64 v[0:1], s[0:1], 0, v[138:139]
	global_load_lds_dwordx4 v[0:1], off
	v_lshl_add_u64 v[0:1], s[0:1], 0, v[142:143]
	s_add_i32 m0, s33, 0x1e000
	v_lshl_or_b32 v168, s25, 7, v160
	global_load_lds_dwordx4 v[0:1], off
	v_lshlrev_b32_e32 v1, 2, v161
	v_lshl_or_b32 v0, v161, 6, v135
	v_and_b32_e32 v1, 32, v1
	v_bitop3_b32 v0, v0, s24, v1 bitop3:0xde
	s_waitcnt vmcnt(6)
	v_add_u16_e32 v1, v8, v9
	v_lshrrev_b16_e32 v1, 1, v1
	s_add_i32 s65, 0, 0x10000
	s_add_i32 s66, 0, 0x14000
	v_lshl_or_b32 v167, s18, 6, v161
	s_ashr_i32 s62, s14, 31
	s_mov_b32 s63, s14
	s_ashr_i32 s64, s2, 31
	v_or_b32_e32 v169, s25, v133
	v_add_lshl_u32 v144, v10, v1, 1
	v_mov_b32_e32 v145, v139
	v_add_lshl_u32 v146, v11, v1, 1
	v_mov_b32_e32 v147, v139
	v_mov_b64_e32 v[148:149], 0xff
	v_add_u32_e32 v170, s65, v168
	v_add_u32_e32 v171, 0, v0
	v_add_u32_e32 v172, s66, v168
	s_mov_b32 s67, 0x90000
	s_mov_b64 s[24:25], 0xa0000
	s_mov_b32 s68, 0xa0000
	s_mov_b64 s[26:27], 0x40000
	s_mov_b32 s69, 0x40000
	s_mov_b64 s[28:29], 0x48000
	s_mov_b32 s70, 0x48000
	s_mov_b64 s[36:37], 0x50000
	s_mov_b32 s71, 0x50000
	s_mov_b64 s[38:39], 0x58000
	s_mov_b32 s72, 0x58000
	s_mov_b32 s73, 0
	s_barrier
	s_branch .LBB0_896

; #define PG8_STAGE(bufoff, gbase, voff) do { _Pragma("unroll") for (int _i = 0; _i < 2; ++_i) \
;         __builtin_amdgcn_global_load_lds((const unsigned*)((const char*)(gbase) + (voff)[_i]), (LAS unsigned*)(lds + (bufoff) + ldsw + _i * 8192), 16, 0, 0); } while (0)
; #define PG8_LDA(dst, b, h) do { _Pragma("unroll") for (int m = 0; m < 4; ++m) _Pragma("unroll") for (int k = 0; k < 2; ++k) dst[m][k] = *(const LAS bf16x8*)(lds + PG8_SA(b, h) + aoff + m * 2048 + k * 1024); } while (0)
; #define PG8_LDB(dst, b, h) do { _Pragma("unroll") for (int n = 0; n < 2; ++n) _Pragma("unroll") for (int k = 0; k < 2; ++k) dst[n][k] = *(const LAS bf16x8*)(lds + PG8_SB(b, h) + boff + n * 2048 + k * 1024); } while (0)
; #define PG8_WAIT_V(n) asm volatile("s_waitcnt vmcnt(" #n ")" ::: "memory")
; #define PG8_WAIT_L(n) asm volatile("s_waitcnt lgkmcnt(" #n ")" ::: "memory")
; #define PG8_BAR __builtin_amdgcn_s_barrier()
; #define PG8_SCHED __builtin_amdgcn_sched_barrier(0)
; template <class Epi>
; __device__ __forceinline__ void gemm_phase(LAS unsigned char* lds, const Gemm g, const StaticOrder& S, const Epi& E) {
;     ...
;         const bool has_next = S.next(ui + 1, nxt);
;         const char* nA = has_next ? (const char*)g.A + (size_t)nxt.pm * tstepA + (size_t)nxt.kt0 * kstep : cA; const char* nB = has_next ? (const char*)g.Bt + (size_t)nxt.pn * tstepB + (size_t)nxt.kt0 * kstep : cB;
;         const int nt = cur.nkt;
;         for (int t = 0; t < nt; t += 2) {
;             const bool last = (t == nt - 2);
;             const char* a1 = cA + (size_t)(t + 1) * kstep;
;             const char* a2 = last ? nA : cA + (size_t)(t + 2) * kstep; const char* b2 = last ? nB : cB + (size_t)(t + 2) * kstep;
;             const char* a3 = a2 + kstep; const char* b3 = b2 + kstep;
;             PG8_LDB(B0, 0, 0); PG8_SCHED; PG8_LDA(At, 0, 0); PG8_STAGE(PG8_SA(1, 1), a1 + hstepA, voffA);
;             PG8_WAIT_L(8); PG8_BAR; PG8_WAIT_L(0); PG8_MMA(0, 0, At, B0); PG8_BAR; PG8_SCHED;
;             PG8_LDB(B1, 0, 1); PG8_STAGE(PG8_SB(0, 0), b2, voffB);
;             PG8_BAR; PG8_WAIT_L(0); PG8_MMA(0, 1, At, B1); PG8_BAR;
;             PG8_LDA(At, 0, 1); PG8_STAGE(PG8_SA(0, 0), a2, voffA);
;             PG8_BAR; PG8_WAIT_L(0); PG8_MMA(1, 0, At, B0); PG8_BAR; PG8_SCHED;
;             PG8_STAGE(PG8_SB(0, 1), b2 + hstepB, voffB);
;             PG8_WAIT_V(6); PG8_BAR; PG8_MMA(1, 1, At, B1); PG8_BAR;
.LBB0_910:
	s_add_i32 s83, s54, 2
	s_add_u32 s55, s46, 0xffea0080
	s_addc_u32 s56, s47, -1
	s_cmp_eq_u32 s18, s54
	s_cselect_b32 s54, s0, s41
	s_cselect_b32 s57, s45, s56
	s_cselect_b32 s56, s44, s55
	s_cselect_b32 s55, s1, s82
	ds_read_b128 v[150:153], v170
	ds_read_b128 v[154:157], v170 offset:1024
	ds_read_b128 v[174:177], v170 offset:2048
	ds_read_b128 v[178:181], v170 offset:3072
	ds_read_b128 v[182:185], v171
	ds_read_b128 v[186:189], v171 offset:1024
	ds_read_b128 v[190:193], v171 offset:2048
	ds_read_b128 v[194:197], v171 offset:3072
	ds_read_b128 v[198:201], v171 offset:4096
	ds_read_b128 v[202:205], v171 offset:5120
	ds_read_b128 v[206:209], v171 offset:6144
	ds_read_b128 v[210:213], v171 offset:7168
	ds_read_b128 v[214:217], v172
	ds_read_b128 v[218:221], v172 offset:1024
	ds_read_b128 v[222:225], v172 offset:2048
	ds_read_b128 v[226:229], v172 offset:3072
	v_lshl_add_u64 v[158:159], s[46:47], 0, v[144:145]
	s_add_i32 m0, s33, 0xc000
	s_nop 0
	global_load_lds_dwordx4 v[158:159], off
	v_lshl_add_u64 v[158:159], s[46:47], 0, v[146:147]
	s_add_i32 m0, s33, 0xe000
	s_nop 0
	global_load_lds_dwordx4 v[158:159], off
	s_waitcnt vmcnt(8) lgkmcnt(0)
	s_barrier
	v_mfma_f32_16x16x32_bf16 v[124:127], v[150:153], v[182:185], v[124:127]
	v_mfma_f32_16x16x32_bf16 v[120:123], v[174:177], v[182:185], v[120:123]
	v_mfma_f32_16x16x32_bf16 v[116:119], v[150:153], v[190:193], v[116:119]
	v_mfma_f32_16x16x32_bf16 v[108:111], v[174:177], v[190:193], v[108:111]
	v_mfma_f32_16x16x32_bf16 v[100:103], v[150:153], v[198:201], v[100:103]
	v_mfma_f32_16x16x32_bf16 v[92:95], v[174:177], v[198:201], v[92:95]
	v_mfma_f32_16x16x32_bf16 v[84:87], v[150:153], v[206:209], v[84:87]
	v_mfma_f32_16x16x32_bf16 v[76:79], v[174:177], v[206:209], v[76:79]
	v_mfma_f32_16x16x32_bf16 v[124:127], v[154:157], v[186:189], v[124:127]
	v_mfma_f32_16x16x32_bf16 v[120:123], v[178:181], v[186:189], v[120:123]
	v_mfma_f32_16x16x32_bf16 v[116:119], v[154:157], v[194:197], v[116:119]
	v_mfma_f32_16x16x32_bf16 v[108:111], v[178:181], v[194:197], v[108:111]
	v_mfma_f32_16x16x32_bf16 v[100:103], v[154:157], v[202:205], v[100:103]
	v_mfma_f32_16x16x32_bf16 v[92:95], v[178:181], v[202:205], v[92:95]
	v_mfma_f32_16x16x32_bf16 v[84:87], v[154:157], v[210:213], v[84:87]
	v_mfma_f32_16x16x32_bf16 v[76:79], v[178:181], v[210:213], v[76:79]
	v_mfma_f32_16x16x32_bf16 v[112:115], v[214:217], v[182:185], v[112:115]
	v_mfma_f32_16x16x32_bf16 v[104:107], v[222:225], v[182:185], v[104:107]
	v_mfma_f32_16x16x32_bf16 v[96:99], v[214:217], v[190:193], v[96:99]
	v_mfma_f32_16x16x32_bf16 v[88:91], v[222:225], v[190:193], v[88:91]
	v_mfma_f32_16x16x32_bf16 v[80:83], v[214:217], v[198:201], v[80:83]
	v_mfma_f32_16x16x32_bf16 v[72:75], v[222:225], v[198:201], v[72:75]
	v_mfma_f32_16x16x32_bf16 v[68:71], v[214:217], v[206:209], v[68:71]
	v_mfma_f32_16x16x32_bf16 v[64:67], v[222:225], v[206:209], v[64:67]
	v_mfma_f32_16x16x32_bf16 v[112:115], v[218:221], v[186:189], v[112:115]
	v_mfma_f32_16x16x32_bf16 v[104:107], v[226:229], v[186:189], v[104:107]
	v_mfma_f32_16x16x32_bf16 v[96:99], v[218:221], v[194:197], v[96:99]
	v_mfma_f32_16x16x32_bf16 v[88:91], v[226:229], v[194:197], v[88:91]
	v_mfma_f32_16x16x32_bf16 v[80:83], v[218:221], v[202:205], v[80:83]
	v_mfma_f32_16x16x32_bf16 v[72:75], v[226:229], v[202:205], v[72:75]
	v_mfma_f32_16x16x32_bf16 v[68:71], v[218:221], v[210:213], v[68:71]
	v_mfma_f32_16x16x32_bf16 v[64:67], v[226:229], v[210:213], v[64:67]
	s_barrier
	ds_read_b128 v[182:185], v171 offset:16384
	ds_read_b128 v[186:189], v171 offset:17408
	ds_read_b128 v[190:193], v171 offset:18432
	ds_read_b128 v[194:197], v171 offset:19456
	ds_read_b128 v[198:201], v171 offset:20480
	ds_read_b128 v[202:205], v171 offset:21504
	ds_read_b128 v[206:209], v171 offset:22528
	ds_read_b128 v[210:213], v171 offset:23552
	s_add_i32 s84, s65, s21
	v_lshl_add_u64 v[158:159], s[54:55], 0, v[138:139]
	s_mov_b32 m0, s84
	s_nop 0
	global_load_lds_dwordx4 v[158:159], off
	v_lshl_add_u64 v[230:231], s[54:55], 0, v[142:143]
	s_add_i32 m0, s84, 0x2000
	s_nop 0
	global_load_lds_dwordx4 v[230:231], off
	s_mov_b32 m0, s33
	v_lshl_add_u64 v[232:233], s[56:57], 0, v[136:137]
	global_load_lds_dwordx4 v[232:233], off
	v_lshl_add_u64 v[234:235], s[56:57], 0, v[140:141]
	s_mov_b32 m0, s35
	s_nop 0
	global_load_lds_dwordx4 v[234:235], off
	s_add_u32 s84, s54, 0xb0000
	s_addc_u32 s85, s55, 0
	s_add_i32 s86, s66, s21
	v_lshl_add_u64 v[240:241], s[84:85], 0, v[138:139]
	s_mov_b32 m0, s86
	s_nop 0
	global_load_lds_dwordx4 v[240:241], off
	v_lshl_add_u64 v[240:241], s[84:85], 0, v[142:143]
	s_add_i32 m0, s86, 0x2000
	s_nop 0
	global_load_lds_dwordx4 v[240:241], off
	s_waitcnt vmcnt(8) lgkmcnt(0)
	s_barrier
; #define PG8_STAGE(bufoff, gbase, voff) do { _Pragma("unroll") for (int _i = 0; _i < 2; ++_i) \
;         __builtin_amdgcn_global_load_lds((const unsigned*)((const char*)(gbase) + (voff)[_i]), (LAS unsigned*)(lds + (bufoff) + ldsw + _i * 8192), 16, 0, 0); } while (0)
; #define PG8_LDA(dst, b, h) do { _Pragma("unroll") for (int m = 0; m < 4; ++m) _Pragma("unroll") for (int k = 0; k < 2; ++k) dst[m][k] = *(const LAS bf16x8*)(lds + PG8_SA(b, h) + aoff + m * 2048 + k * 1024); } while (0)
; #define PG8_LDB(dst, b, h) do { _Pragma("unroll") for (int n = 0; n < 2; ++n) _Pragma("unroll") for (int k = 0; k < 2; ++k) dst[n][k] = *(const LAS bf16x8*)(lds + PG8_SB(b, h) + boff + n * 2048 + k * 1024); } while (0)
; #define PG8_MMA(ai, bj, At, Bt) do { __builtin_amdgcn_s_setprio(1); _Pragma("unroll") for (int m = 0; m < 4; ++m) _Pragma("unroll") for (int n = 0; n < 2; ++n) _Pragma("unroll") for (int k = 0; k < 2; ++k) \
;         acc[ai][bj][m][n] = __builtin_amdgcn_mfma_f32_16x16x32_bf16(Bt[n][k], At[m][k], acc[ai][bj][m][n], 0, 0, 0); __builtin_amdgcn_s_setprio(0); } while (0)
; #define PG8_WAIT_V(n) asm volatile("s_waitcnt vmcnt(" #n ")" ::: "memory")
; #define PG8_WAIT_L(n) asm volatile("s_waitcnt lgkmcnt(" #n ")" ::: "memory")
; #define PG8_BAR __builtin_amdgcn_s_barrier()
; #define PG8_SCHED __builtin_amdgcn_sched_barrier(0)
; template <class Epi>
; __device__ __forceinline__ void gemm_phase(LAS unsigned char* lds, const Gemm g, const StaticOrder& S, const Epi& E) {
;     ...
;             PG8_BAR; PG8_WAIT_L(0); PG8_MMA(1, 0, At, B0); PG8_BAR; PG8_SCHED;
;             PG8_STAGE(PG8_SB(0, 1), b2 + hstepB, voffB);
;             PG8_WAIT_V(6); PG8_BAR; PG8_MMA(1, 1, At, B1); PG8_BAR;
;             PG8_LDB(B0, 1, 0); PG8_SCHED; PG8_LDA(At, 1, 0); PG8_STAGE(PG8_SA(0, 1), a2 + hstepA, voffA);
;             PG8_WAIT_L(8); PG8_BAR; PG8_WAIT_L(0); PG8_MMA(0, 0, At, B0); PG8_BAR; PG8_SCHED;
;             PG8_LDB(B1, 1, 1); PG8_STAGE(PG8_SB(1, 0), b3, voffB);
;             PG8_BAR; PG8_WAIT_L(0); PG8_MMA(0, 1, At, B1); PG8_BAR;
	v_mfma_f32_16x16x32_bf16 v[60:63], v[150:153], v[182:185], v[60:63]
	v_mfma_f32_16x16x32_bf16 v[56:59], v[174:177], v[182:185], v[56:59]
	v_mfma_f32_16x16x32_bf16 v[52:55], v[150:153], v[190:193], v[52:55]
	v_mfma_f32_16x16x32_bf16 v[44:47], v[174:177], v[190:193], v[44:47]
	v_mfma_f32_16x16x32_bf16 v[36:39], v[150:153], v[198:201], v[36:39]
	v_mfma_f32_16x16x32_bf16 v[28:31], v[174:177], v[198:201], v[28:31]
	v_mfma_f32_16x16x32_bf16 v[20:23], v[150:153], v[206:209], v[20:23]
	v_mfma_f32_16x16x32_bf16 v[12:15], v[174:177], v[206:209], v[12:15]
	v_mfma_f32_16x16x32_bf16 v[60:63], v[154:157], v[186:189], v[60:63]
	v_mfma_f32_16x16x32_bf16 v[56:59], v[178:181], v[186:189], v[56:59]
	v_mfma_f32_16x16x32_bf16 v[52:55], v[154:157], v[194:197], v[52:55]
	v_mfma_f32_16x16x32_bf16 v[44:47], v[178:181], v[194:197], v[44:47]
	v_mfma_f32_16x16x32_bf16 v[36:39], v[154:157], v[202:205], v[36:39]
	v_mfma_f32_16x16x32_bf16 v[28:31], v[178:181], v[202:205], v[28:31]
	v_mfma_f32_16x16x32_bf16 v[20:23], v[154:157], v[210:213], v[20:23]
	v_mfma_f32_16x16x32_bf16 v[12:15], v[178:181], v[210:213], v[12:15]
	v_mfma_f32_16x16x32_bf16 v[48:51], v[214:217], v[182:185], v[48:51]
	v_mfma_f32_16x16x32_bf16 v[40:43], v[222:225], v[182:185], v[40:43]
	v_mfma_f32_16x16x32_bf16 v[32:35], v[214:217], v[190:193], v[32:35]
	v_mfma_f32_16x16x32_bf16 v[24:27], v[222:225], v[190:193], v[24:27]
	v_mfma_f32_16x16x32_bf16 v[16:19], v[214:217], v[198:201], v[16:19]
	v_mfma_f32_16x16x32_bf16 v[8:11], v[222:225], v[198:201], v[8:11]
	v_mfma_f32_16x16x32_bf16 v[4:7], v[214:217], v[206:209], v[4:7]
	v_mfma_f32_16x16x32_bf16 v[0:3], v[222:225], v[206:209], v[0:3]
	v_mfma_f32_16x16x32_bf16 v[48:51], v[218:221], v[186:189], v[48:51]
	v_mfma_f32_16x16x32_bf16 v[40:43], v[226:229], v[186:189], v[40:43]
	v_mfma_f32_16x16x32_bf16 v[32:35], v[218:221], v[194:197], v[32:35]
	v_mfma_f32_16x16x32_bf16 v[24:27], v[226:229], v[194:197], v[24:27]
	v_mfma_f32_16x16x32_bf16 v[16:19], v[218:221], v[202:205], v[16:19]
	v_mfma_f32_16x16x32_bf16 v[8:11], v[226:229], v[202:205], v[8:11]
	v_mfma_f32_16x16x32_bf16 v[4:7], v[218:221], v[210:213], v[4:7]
	v_mfma_f32_16x16x32_bf16 v[0:3], v[226:229], v[210:213], v[0:3]
	s_barrier
	s_add_i32 s84, 0, 0x18000
	v_add_u32_e32 v173, s84, v168
	ds_read_b128 v[150:153], v173
	ds_read_b128 v[154:157], v173 offset:1024
	ds_read_b128 v[174:177], v173 offset:2048
	ds_read_b128 v[178:181], v173 offset:3072
	ds_read_b128 v[182:185], v171 offset:32768
	ds_read_b128 v[186:189], v171 offset:33792
	ds_read_b128 v[190:193], v171 offset:34816
	ds_read_b128 v[194:197], v171 offset:35840
	ds_read_b128 v[198:201], v171 offset:36864
	ds_read_b128 v[202:205], v171 offset:37888
	ds_read_b128 v[206:209], v171 offset:38912
	ds_read_b128 v[210:213], v171 offset:39936
	s_add_i32 s98, 0, 0x1c000
	v_add_u32_e32 v246, s98, v168
	ds_read_b128 v[214:217], v246
	ds_read_b128 v[218:221], v246 offset:1024
	ds_read_b128 v[222:225], v246 offset:2048
	ds_read_b128 v[226:229], v246 offset:3072
	s_add_u32 s56, s56, 0x160000
	s_addc_u32 s57, s57, 0
	s_mov_b32 m0, s58
	v_lshl_add_u64 v[244:245], s[56:57], 0, v[136:137]
	global_load_lds_dwordx4 v[244:245], off
	v_lshl_add_u64 v[244:245], s[56:57], 0, v[140:141]
	s_mov_b32 m0, s59
	s_nop 0
	global_load_lds_dwordx4 v[244:245], off
	s_waitcnt vmcnt(8) lgkmcnt(0)
	s_barrier
	v_mfma_f32_16x16x32_bf16 v[124:127], v[150:153], v[182:185], v[124:127]
	v_mfma_f32_16x16x32_bf16 v[120:123], v[174:177], v[182:185], v[120:123]
	v_mfma_f32_16x16x32_bf16 v[116:119], v[150:153], v[190:193], v[116:119]
	v_mfma_f32_16x16x32_bf16 v[108:111], v[174:177], v[190:193], v[108:111]
	v_mfma_f32_16x16x32_bf16 v[100:103], v[150:153], v[198:201], v[100:103]
	v_mfma_f32_16x16x32_bf16 v[92:95], v[174:177], v[198:201], v[92:95]
	v_mfma_f32_16x16x32_bf16 v[84:87], v[150:153], v[206:209], v[84:87]
	v_mfma_f32_16x16x32_bf16 v[76:79], v[174:177], v[206:209], v[76:79]
	v_mfma_f32_16x16x32_bf16 v[124:127], v[154:157], v[186:189], v[124:127]
	v_mfma_f32_16x16x32_bf16 v[120:123], v[178:181], v[186:189], v[120:123]
	v_mfma_f32_16x16x32_bf16 v[116:119], v[154:157], v[194:197], v[116:119]
	v_mfma_f32_16x16x32_bf16 v[108:111], v[178:181], v[194:197], v[108:111]
	v_mfma_f32_16x16x32_bf16 v[100:103], v[154:157], v[202:205], v[100:103]
	v_mfma_f32_16x16x32_bf16 v[92:95], v[178:181], v[202:205], v[92:95]
	v_mfma_f32_16x16x32_bf16 v[84:87], v[154:157], v[210:213], v[84:87]
	v_mfma_f32_16x16x32_bf16 v[76:79], v[178:181], v[210:213], v[76:79]
	v_mfma_f32_16x16x32_bf16 v[112:115], v[214:217], v[182:185], v[112:115]
	v_mfma_f32_16x16x32_bf16 v[104:107], v[222:225], v[182:185], v[104:107]
	v_mfma_f32_16x16x32_bf16 v[96:99], v[214:217], v[190:193], v[96:99]
	v_mfma_f32_16x16x32_bf16 v[88:91], v[222:225], v[190:193], v[88:91]
	v_mfma_f32_16x16x32_bf16 v[80:83], v[214:217], v[198:201], v[80:83]
	v_mfma_f32_16x16x32_bf16 v[72:75], v[222:225], v[198:201], v[72:75]
	v_mfma_f32_16x16x32_bf16 v[68:71], v[214:217], v[206:209], v[68:71]
	v_mfma_f32_16x16x32_bf16 v[64:67], v[222:225], v[206:209], v[64:67]
	v_mfma_f32_16x16x32_bf16 v[112:115], v[218:221], v[186:189], v[112:115]
	v_mfma_f32_16x16x32_bf16 v[104:107], v[226:229], v[186:189], v[104:107]
	v_mfma_f32_16x16x32_bf16 v[96:99], v[218:221], v[194:197], v[96:99]
	v_mfma_f32_16x16x32_bf16 v[88:91], v[226:229], v[194:197], v[88:91]
	v_mfma_f32_16x16x32_bf16 v[80:83], v[218:221], v[202:205], v[80:83]
	v_mfma_f32_16x16x32_bf16 v[72:75], v[226:229], v[202:205], v[72:75]
	v_mfma_f32_16x16x32_bf16 v[68:71], v[218:221], v[210:213], v[68:71]
	v_mfma_f32_16x16x32_bf16 v[64:67], v[226:229], v[210:213], v[64:67]
	s_barrier
; #define PG8_STAGE(bufoff, gbase, voff) do { _Pragma("unroll") for (int _i = 0; _i < 2; ++_i) \
;         __builtin_amdgcn_global_load_lds((const unsigned*)((const char*)(gbase) + (voff)[_i]), (LAS unsigned*)(lds + (bufoff) + ldsw + _i * 8192), 16, 0, 0); } while (0)
; #define PG8_LDA(dst, b, h) do { _Pragma("unroll") for (int m = 0; m < 4; ++m) _Pragma("unroll") for (int k = 0; k < 2; ++k) dst[m][k] = *(const LAS bf16x8*)(lds + PG8_SA(b, h) + aoff + m * 2048 + k * 1024); } while (0)
; #define PG8_MMA(ai, bj, At, Bt) do { __builtin_amdgcn_s_setprio(1); _Pragma("unroll") for (int m = 0; m < 4; ++m) _Pragma("unroll") for (int n = 0; n < 2; ++n) _Pragma("unroll") for (int k = 0; k < 2; ++k) \
;         acc[ai][bj][m][n] = __builtin_amdgcn_mfma_f32_16x16x32_bf16(Bt[n][k], At[m][k], acc[ai][bj][m][n], 0, 0, 0); __builtin_amdgcn_s_setprio(0); } while (0)
; #define PG8_WAIT_V(n) asm volatile("s_waitcnt vmcnt(" #n ")" ::: "memory")
; #define PG8_WAIT_L(n) asm volatile("s_waitcnt lgkmcnt(" #n ")" ::: "memory")
; #define PG8_BAR __builtin_amdgcn_s_barrier()
; #define PG8_SCHED __builtin_amdgcn_sched_barrier(0)
; template <class Epi>
; __device__ __forceinline__ void gemm_phase(LAS unsigned char* lds, const Gemm g, const StaticOrder& S, const Epi& E) {
;     ...
;         for (int t = 0; t < nt; t += 2) {
;     ...
;             PG8_LDA(At, 1, 1); PG8_STAGE(PG8_SA(1, 0), a3, voffA);
;             PG8_BAR; PG8_WAIT_L(0); PG8_MMA(1, 0, At, B0); PG8_BAR; PG8_SCHED;
;             PG8_STAGE(PG8_SB(1, 1), b3 + hstepB, voffB);
;             PG8_WAIT_V(6); PG8_BAR; PG8_MMA(1, 1, At, B1); PG8_BAR;
	ds_read_b128 v[182:185], v171 offset:49152
	ds_read_b128 v[186:189], v171 offset:50176
	ds_read_b128 v[190:193], v171 offset:51200
	ds_read_b128 v[194:197], v171 offset:52224
	ds_read_b128 v[198:201], v171 offset:53248
	ds_read_b128 v[202:205], v171 offset:54272
	ds_read_b128 v[206:209], v171 offset:55296
	ds_read_b128 v[210:213], v171 offset:56320
	s_add_i32 s57, s84, s21
	v_lshl_add_u64 v[158:159], v[158:159], 0, s[22:23]
	s_mov_b32 m0, s57
	s_nop 0
	global_load_lds_dwordx4 v[158:159], off
	v_lshl_add_u64 v[158:159], v[230:231], 0, s[22:23]
	s_add_i32 m0, s57, 0x2000
	s_nop 0
	global_load_lds_dwordx4 v[158:159], off
	s_mov_b32 m0, s60
	v_lshl_add_u64 v[158:159], v[232:233], 0, s[22:23]
	global_load_lds_dwordx4 v[158:159], off
	v_lshl_add_u64 v[158:159], v[234:235], 0, s[22:23]
	s_mov_b32 m0, s61
	s_nop 0
	global_load_lds_dwordx4 v[158:159], off
	s_add_u32 s54, s54, 0xb0080
	s_addc_u32 s55, s55, 0
	s_add_i32 s56, s98, s21
	v_lshl_add_u64 v[240:241], s[54:55], 0, v[138:139]
	s_mov_b32 m0, s56
	s_nop 0
	global_load_lds_dwordx4 v[240:241], off
	v_lshl_add_u64 v[240:241], s[54:55], 0, v[142:143]
	s_add_i32 m0, s56, 0x2000
	s_nop 0
	global_load_lds_dwordx4 v[240:241], off
	s_waitcnt vmcnt(8) lgkmcnt(0)
	s_barrier
	v_mfma_f32_16x16x32_bf16 v[60:63], v[150:153], v[182:185], v[60:63]
	v_mfma_f32_16x16x32_bf16 v[56:59], v[174:177], v[182:185], v[56:59]
	v_mfma_f32_16x16x32_bf16 v[52:55], v[150:153], v[190:193], v[52:55]
	v_mfma_f32_16x16x32_bf16 v[44:47], v[174:177], v[190:193], v[44:47]
	v_mfma_f32_16x16x32_bf16 v[36:39], v[150:153], v[198:201], v[36:39]
	v_mfma_f32_16x16x32_bf16 v[28:31], v[174:177], v[198:201], v[28:31]
	v_mfma_f32_16x16x32_bf16 v[20:23], v[150:153], v[206:209], v[20:23]
	v_mfma_f32_16x16x32_bf16 v[12:15], v[174:177], v[206:209], v[12:15]
	v_mfma_f32_16x16x32_bf16 v[60:63], v[154:157], v[186:189], v[60:63]
	v_mfma_f32_16x16x32_bf16 v[56:59], v[178:181], v[186:189], v[56:59]
	v_mfma_f32_16x16x32_bf16 v[52:55], v[154:157], v[194:197], v[52:55]
	v_mfma_f32_16x16x32_bf16 v[44:47], v[178:181], v[194:197], v[44:47]
	v_mfma_f32_16x16x32_bf16 v[36:39], v[154:157], v[202:205], v[36:39]
	v_mfma_f32_16x16x32_bf16 v[28:31], v[178:181], v[202:205], v[28:31]
	v_mfma_f32_16x16x32_bf16 v[20:23], v[154:157], v[210:213], v[20:23]
	v_mfma_f32_16x16x32_bf16 v[12:15], v[178:181], v[210:213], v[12:15]
	v_mfma_f32_16x16x32_bf16 v[48:51], v[214:217], v[182:185], v[48:51]
	v_mfma_f32_16x16x32_bf16 v[40:43], v[222:225], v[182:185], v[40:43]
	v_mfma_f32_16x16x32_bf16 v[32:35], v[214:217], v[190:193], v[32:35]
	v_mfma_f32_16x16x32_bf16 v[24:27], v[222:225], v[190:193], v[24:27]
	v_mfma_f32_16x16x32_bf16 v[16:19], v[214:217], v[198:201], v[16:19]
	v_mfma_f32_16x16x32_bf16 v[8:11], v[222:225], v[198:201], v[8:11]
	v_mfma_f32_16x16x32_bf16 v[4:7], v[214:217], v[206:209], v[4:7]
	v_mfma_f32_16x16x32_bf16 v[0:3], v[222:225], v[206:209], v[0:3]
	v_mfma_f32_16x16x32_bf16 v[48:51], v[218:221], v[186:189], v[48:51]
	v_mfma_f32_16x16x32_bf16 v[40:43], v[226:229], v[186:189], v[40:43]
	v_mfma_f32_16x16x32_bf16 v[32:35], v[218:221], v[194:197], v[32:35]
	v_mfma_f32_16x16x32_bf16 v[24:27], v[226:229], v[194:197], v[24:27]
	v_mfma_f32_16x16x32_bf16 v[16:19], v[218:221], v[202:205], v[16:19]
	v_mfma_f32_16x16x32_bf16 v[8:11], v[226:229], v[202:205], v[8:11]
	v_mfma_f32_16x16x32_bf16 v[4:7], v[218:221], v[210:213], v[4:7]
	v_mfma_f32_16x16x32_bf16 v[0:3], v[226:229], v[210:213], v[0:3]
	s_add_u32 s46, s46, 0x100
	s_addc_u32 s47, s47, 0
	s_add_u32 s41, s41, 0x100
	s_addc_u32 s82, s82, 0
	s_cmp_ge_i32 s83, s81
	s_mov_b32 s54, s83
	s_barrier
;     __device__ __forceinline__ void operator()(const f32x4 (&acc)[2][2][4][2], const Unit& u, int wr, int wc, int fr, int fq) const {
;     ...
;         if (u.part) {
;             float* base = tailacc + (size_t)(u.part - 1) * slab - (size_t)tail_row0 * tail_ld;
; #pragma unroll
;             for (int ai = 0; ai < 2; ++ai)
; #pragma unroll
;                 for (int m = 0; m < 4; ++m) { float* rowp = base + (size_t)(row0 + ai * HALF + m * 16) * tail_ld + col0;
; #pragma unroll
;                     for (int bj = 0; bj < 2; ++bj)
; #pragma unroll
;                         for (int n = 0; n < 2; ++n) *(f32x4*)(rowp + bj * HALF + 4 * n) = acc[ai][bj][m][n]; }
;             return;
	s_cbranch_scc0 .LBB0_910
	v_lshl_add_u32 v158, s78, 8, v167
	v_lshl_or_b32 v150, s79, 8, v169
	v_or_b32_e32 v156, 16, v158
	v_or_b32_e32 v154, 32, v158
	v_or_b32_e32 v152, 48, v158
	s_cmp_lg_u32 s80, 0
	v_ashrrev_i32_e32 v151, 31, v150
	v_ashrrev_i32_e32 v159, 31, v158
	v_ashrrev_i32_e32 v157, 31, v156
	v_ashrrev_i32_e32 v155, 31, v154
	v_ashrrev_i32_e32 v153, 31, v152
	s_cbranch_scc0 .LBB0_913
	s_add_i32 s18, s80, -1
	s_lshl_b64 s[46:47], s[18:19], 21
	s_add_u32 s46, s92, s46
	s_addc_u32 s47, s93, s47
	v_lshl_add_u64 v[174:175], v[150:151], 2, s[46:47]
	s_brev_b32 s46, 63
	s_mov_b32 s47, -1
	v_lshl_add_u64 v[174:175], v[174:175], 0, s[46:47]
	v_lshlrev_b64 v[176:177], 12, v[158:159]
	v_lshlrev_b64 v[178:179], 12, v[156:157]
	v_lshl_add_u64 v[176:177], v[174:175], 0, v[176:177]
	v_lshl_add_u64 v[178:179], v[174:175], 0, v[178:179]
	global_store_dwordx4 v[176:177], v[124:127], off
	global_store_dwordx4 v[176:177], v[120:123], off offset:16
	global_store_dwordx4 v[176:177], v[112:115], off offset:512
	global_store_dwordx4 v[176:177], v[104:107], off offset:528
	global_store_dwordx4 v[178:179], v[116:119], off
	global_store_dwordx4 v[178:179], v[108:111], off offset:16
	global_store_dwordx4 v[178:179], v[96:99], off offset:512
	global_store_dwordx4 v[178:179], v[88:91], off offset:528
	v_lshlrev_b64 v[178:179], 12, v[154:155]
	v_lshl_add_u64 v[178:179], v[174:175], 0, v[178:179]
	global_store_dwordx4 v[178:179], v[100:103], off
	global_store_dwordx4 v[178:179], v[92:95], off offset:16
	global_store_dwordx4 v[178:179], v[80:83], off offset:512
	global_store_dwordx4 v[178:179], v[72:75], off offset:528
	v_lshlrev_b64 v[178:179], 12, v[152:153]
	s_mov_b32 s18, 0x80000
	v_lshl_add_u64 v[174:175], v[174:175], 0, v[178:179]
	v_add_co_u32_e32 v178, vcc, s18, v176
	s_mov_b64 s[46:47], 0x80000
	s_nop 0
	v_addc_co_u32_e32 v179, vcc, 0, v177, vcc
	global_store_dwordx4 v[174:175], v[84:87], off
	global_store_dwordx4 v[174:175], v[76:79], off offset:16
	global_store_dwordx4 v[174:175], v[68:71], off offset:512
	global_store_dwordx4 v[174:175], v[64:67], off offset:528
	v_lshl_add_u64 v[174:175], v[176:177], 0, s[46:47]
	global_store_dwordx4 v[178:179], v[60:63], off
	global_store_dwordx4 v[174:175], v[56:59], off offset:16
	global_store_dwordx4 v[174:175], v[48:51], off offset:512
	global_store_dwordx4 v[174:175], v[40:43], off offset:528
	v_add_co_u32_e32 v178, vcc, s67, v176
	s_mov_b64 s[46:47], 0x90000
	s_nop 0
	v_addc_co_u32_e32 v179, vcc, 0, v177, vcc
	v_lshl_add_u64 v[174:175], v[176:177], 0, s[46:47]
	global_store_dwordx4 v[178:179], v[52:55], off
	global_store_dwordx4 v[174:175], v[44:47], off offset:16
	global_store_dwordx4 v[174:175], v[32:35], off offset:512
	global_store_dwordx4 v[174:175], v[24:27], off offset:528
	v_add_co_u32_e32 v178, vcc, s68, v176
	v_lshl_add_u64 v[174:175], v[176:177], 0, s[24:25]
	s_nop 0
	v_addc_co_u32_e32 v179, vcc, 0, v177, vcc
	s_mov_b64 s[46:47], 0xb0000
	global_store_dwordx4 v[178:179], v[36:39], off
	global_store_dwordx4 v[174:175], v[28:31], off offset:16
	global_store_dwordx4 v[174:175], v[16:19], off offset:512
	global_store_dwordx4 v[174:175], v[8:11], off offset:528
	v_lshl_add_u64 v[174:175], v[176:177], 0, s[46:47]
	v_add_co_u32_e32 v176, vcc, 0xb0000, v176
	s_nop 1
	v_addc_co_u32_e32 v177, vcc, 0, v177, vcc
	global_store_dwordx4 v[176:177], v[20:23], off
	global_store_dwordx4 v[174:175], v[12:15], off offset:16
	global_store_dwordx4 v[174:175], v[4:7], off offset:512
	global_store_dwordx4 v[174:175], v[0:3], off offset:528
	s_cbranch_execnz .LBB0_895
	s_branch .LBB0_894

; #define PG8_STAGE(bufoff, gbase, voff) do { _Pragma("unroll") for (int _i = 0; _i < 2; ++_i) \
;         __builtin_amdgcn_global_load_lds((const unsigned*)((const char*)(gbase) + (voff)[_i]), (LAS unsigned*)(lds + (bufoff) + ldsw + _i * 8192), 16, 0, 0); } while (0)
; #define PG8_WAIT_V(n) asm volatile("s_waitcnt vmcnt(" #n ")" ::: "memory")
; #define PG8_BAR __builtin_amdgcn_s_barrier()
; template <class Epi>
; __device__ __forceinline__ void gemm_phase(LAS unsigned char* lds, const Gemm g, const StaticOrder& S, const Epi& E) {
;     ...
;     const char* cA = (const char*)g.A + (size_t)cur.pm * tstepA + (size_t)cur.kt0 * kstep; const char* cB = (const char*)g.Bt + (size_t)cur.pn * tstepB + (size_t)cur.kt0 * kstep;
;     PG8_STAGE(PG8_SB(0, 0), cB, voffB); PG8_STAGE(PG8_SA(0, 0), cA, voffA); PG8_STAGE(PG8_SB(0, 1), cB + hstepB, voffB); PG8_STAGE(PG8_SA(0, 1), cA + hstepA, voffA);
;     if (wr == 1) PG8_BAR;
;     PG8_WAIT_V(4); PG8_BAR;
;     PG8_STAGE(PG8_SB(1, 0), cB + kstep, voffB); PG8_STAGE(PG8_SA(1, 0), cA + kstep, voffA); PG8_STAGE(PG8_SB(1, 1), cB + hstepB + kstep, voffB);
;     PG8_WAIT_V(6); PG8_BAR;
.LBB0_1129:
	s_add_u32 s10, s92, 0x4301e00
	s_addc_u32 s11, s93, 0
	s_lshl_b32 s0, s12, 5
	s_mov_b64 s[12:13], 0x80
	s_and_b32 s24, s0, 0x60
	s_add_i32 m0, s33, 0x18000
	v_lshl_add_u64 v[6:7], v[6:7], 0, s[12:13]
	s_lshl_b32 s23, s22, 13
	s_lshl_b32 s25, s24, 7
	s_waitcnt vmcnt(0)
	s_barrier
	global_load_lds_dwordx4 v[6:7], off
	v_lshl_add_u64 v[4:5], v[4:5], 0, s[12:13]
	s_add_i32 m0, s33, 0x1a000
	s_add_i32 s60, s33, 0x8000
	s_add_i32 s61, s33, 0xa000
	global_load_lds_dwordx4 v[4:5], off
	v_lshl_add_u64 v[2:3], v[2:3], 0, s[12:13]
	s_mov_b32 m0, s60
	s_add_u32 s0, s54, 0x40080
	global_load_lds_dwordx4 v[2:3], off
	v_lshl_add_u64 v[0:1], v[0:1], 0, s[12:13]
	s_mov_b32 m0, s61
	s_addc_u32 s1, s55, 0
	global_load_lds_dwordx4 v[0:1], off
	s_add_i32 m0, s33, 0x1c000
	v_lshl_add_u64 v[0:1], s[0:1], 0, v[138:139]
	global_load_lds_dwordx4 v[0:1], off
	v_lshl_add_u64 v[0:1], s[0:1], 0, v[142:143]
	s_add_i32 m0, s33, 0x1e000
	v_lshlrev_b32_e32 v2, 2, v129
	global_load_lds_dwordx4 v[0:1], off
	v_and_b32_e32 v0, 15, v129
	v_lshlrev_b32_e32 v1, 1, v11
	v_lshlrev_b32_e32 v3, 6, v129
	s_movk_i32 s0, 0x3c0
	v_lshl_or_b32 v133, s22, 6, v0
	v_lshl_or_b32 v0, v0, 6, v1
	v_and_b32_e32 v2, 32, v2
	v_and_or_b32 v1, v3, s0, v1
	v_bitop3_b32 v135, s25, v1, v2 bitop3:0xf6
	v_lshlrev_b32_e32 v1, 8, v129
	v_bitop3_b32 v0, v0, s23, v2 bitop3:0xde
	v_and_b32_e32 v1, 0x38000, v1
	v_lshlrev_b32_e32 v2, 11, v10
	v_or3_b32 v1, v8, v1, v2
	v_add_u32_e32 v144, v1, v9
	v_lshlrev_b32_e32 v1, 4, v12
	s_waitcnt vmcnt(6)
	v_and_b32_e32 v1, 0x78000, v1
	v_or3_b32 v1, v8, v1, v2
	s_add_i32 s66, 0, 0x10000
	s_add_i32 s67, 0, 0x14000
	s_brev_b32 s22, 63
	s_ashr_i32 s62, s14, 31
	s_mov_b32 s63, s14
	s_ashr_i32 s65, s2, 31
	v_or_b32_e32 v162, s24, v11
	v_mov_b32_e32 v145, v139
	v_add_u32_e32 v146, v1, v9
	v_mov_b32_e32 v147, v139
	v_mov_b64_e32 v[148:149], 0xff
	v_add_u32_e32 v129, s66, v135
	v_add_u32_e32 v163, 0, v0
	v_add_u32_e32 v164, s67, v135
	s_mov_b32 s23, -1
	s_mov_b64 s[24:25], 0x80000
	s_mov_b32 s68, 0x80000
	s_mov_b64 s[26:27], 0x90000
	s_mov_b32 s69, 0x90000
	s_mov_b64 s[28:29], 0xa0000
	s_mov_b32 s70, 0xa0000
	s_mov_b64 s[36:37], 0xb0000
	s_movk_i32 s71, 0x2c00
	s_mov_b32 s72, 0
	s_barrier
	s_branch .LBB0_1132

; #define PG8_STAGE(bufoff, gbase, voff) do { _Pragma("unroll") for (int _i = 0; _i < 2; ++_i) \
;         __builtin_amdgcn_global_load_lds((const unsigned*)((const char*)(gbase) + (voff)[_i]), (LAS unsigned*)(lds + (bufoff) + ldsw + _i * 8192), 16, 0, 0); } while (0)
; #define PG8_LDA(dst, b, h) do { _Pragma("unroll") for (int m = 0; m < 4; ++m) _Pragma("unroll") for (int k = 0; k < 2; ++k) dst[m][k] = *(const LAS bf16x8*)(lds + PG8_SA(b, h) + aoff + m * 2048 + k * 1024); } while (0)
; #define PG8_LDB(dst, b, h) do { _Pragma("unroll") for (int n = 0; n < 2; ++n) _Pragma("unroll") for (int k = 0; k < 2; ++k) dst[n][k] = *(const LAS bf16x8*)(lds + PG8_SB(b, h) + boff + n * 2048 + k * 1024); } while (0)
; #define PG8_WAIT_V(n) asm volatile("s_waitcnt vmcnt(" #n ")" ::: "memory")
; #define PG8_WAIT_L(n) asm volatile("s_waitcnt lgkmcnt(" #n ")" ::: "memory")
; #define PG8_BAR __builtin_amdgcn_s_barrier()
; #define PG8_SCHED __builtin_amdgcn_sched_barrier(0)
; template <class Epi>
; __device__ __forceinline__ void gemm_phase(LAS unsigned char* lds, const Gemm g, const StaticOrder& S, const Epi& E) {
;     ...
;         const bool has_next = S.next(ui + 1, nxt);
;         const char* nA = has_next ? (const char*)g.A + (size_t)nxt.pm * tstepA + (size_t)nxt.kt0 * kstep : cA; const char* nB = has_next ? (const char*)g.Bt + (size_t)nxt.pn * tstepB + (size_t)nxt.kt0 * kstep : cB;
;         const int nt = cur.nkt;
;         for (int t = 0; t < nt; t += 2) {
;             const bool last = (t == nt - 2);
;             const char* a1 = cA + (size_t)(t + 1) * kstep;
;             const char* a2 = last ? nA : cA + (size_t)(t + 2) * kstep; const char* b2 = last ? nB : cB + (size_t)(t + 2) * kstep;
;             const char* a3 = a2 + kstep; const char* b3 = b2 + kstep;
;             PG8_LDB(B0, 0, 0); PG8_SCHED; PG8_LDA(At, 0, 0); PG8_STAGE(PG8_SA(1, 1), a1 + hstepA, voffA);
;             PG8_WAIT_L(8); PG8_BAR; PG8_WAIT_L(0); PG8_MMA(0, 0, At, B0); PG8_BAR; PG8_SCHED;
;             PG8_LDB(B1, 0, 1); PG8_STAGE(PG8_SB(0, 0), b2, voffB);
;             PG8_BAR; PG8_WAIT_L(0); PG8_MMA(0, 1, At, B1); PG8_BAR;
;             PG8_LDA(At, 0, 1); PG8_STAGE(PG8_SA(0, 0), a2, voffA);
;             PG8_BAR; PG8_WAIT_L(0); PG8_MMA(1, 0, At, B0); PG8_BAR; PG8_SCHED;
;             PG8_STAGE(PG8_SB(0, 1), b2 + hstepB, voffB);
;             PG8_WAIT_V(6); PG8_BAR; PG8_MMA(1, 1, At, B1); PG8_BAR;
.LBB0_1146:
	s_add_i32 s77, s45, 2
	s_add_u32 s54, s50, 0xfffc0080
	s_addc_u32 s55, s51, -1
	s_cmp_eq_u32 s39, s45
	s_cselect_b32 s57, s49, s55
	s_cselect_b32 s56, s48, s54
	s_cselect_b32 s55, s1, s43
	s_cselect_b32 s54, s0, s41
	ds_read_b128 v[150:153], v129
	ds_read_b128 v[154:157], v129 offset:1024
	ds_read_b128 v[158:161], v129 offset:2048
	ds_read_b128 v[166:169], v129 offset:3072
	ds_read_b128 v[170:173], v163
	ds_read_b128 v[174:177], v163 offset:1024
	ds_read_b128 v[178:181], v163 offset:2048
	ds_read_b128 v[182:185], v163 offset:3072
	ds_read_b128 v[186:189], v163 offset:4096
	ds_read_b128 v[190:193], v163 offset:5120
	ds_read_b128 v[194:197], v163 offset:6144
	ds_read_b128 v[198:201], v163 offset:7168
	ds_read_b128 v[202:205], v164
	ds_read_b128 v[206:209], v164 offset:1024
	ds_read_b128 v[210:213], v164 offset:2048
	ds_read_b128 v[214:217], v164 offset:3072
	v_lshl_add_u64 v[242:243], s[50:51], 0, v[144:145]
	s_add_i32 m0, s33, 0xc000
	s_nop 0
	global_load_lds_dwordx4 v[242:243], off
	v_lshl_add_u64 v[242:243], s[50:51], 0, v[146:147]
	s_add_i32 m0, s33, 0xe000
	s_nop 0
	global_load_lds_dwordx4 v[242:243], off
	s_waitcnt vmcnt(8) lgkmcnt(0)
	s_barrier
	v_mfma_f32_16x16x32_bf16 v[124:127], v[150:153], v[170:173], v[124:127]
	v_mfma_f32_16x16x32_bf16 v[120:123], v[158:161], v[170:173], v[120:123]
	v_mfma_f32_16x16x32_bf16 v[116:119], v[150:153], v[178:181], v[116:119]
	v_mfma_f32_16x16x32_bf16 v[108:111], v[158:161], v[178:181], v[108:111]
	v_mfma_f32_16x16x32_bf16 v[100:103], v[150:153], v[186:189], v[100:103]
	v_mfma_f32_16x16x32_bf16 v[92:95], v[158:161], v[186:189], v[92:95]
	v_mfma_f32_16x16x32_bf16 v[84:87], v[150:153], v[194:197], v[84:87]
	v_mfma_f32_16x16x32_bf16 v[76:79], v[158:161], v[194:197], v[76:79]
	v_mfma_f32_16x16x32_bf16 v[124:127], v[154:157], v[174:177], v[124:127]
	v_mfma_f32_16x16x32_bf16 v[120:123], v[166:169], v[174:177], v[120:123]
	v_mfma_f32_16x16x32_bf16 v[116:119], v[154:157], v[182:185], v[116:119]
	v_mfma_f32_16x16x32_bf16 v[108:111], v[166:169], v[182:185], v[108:111]
	v_mfma_f32_16x16x32_bf16 v[100:103], v[154:157], v[190:193], v[100:103]
	v_mfma_f32_16x16x32_bf16 v[92:95], v[166:169], v[190:193], v[92:95]
	v_mfma_f32_16x16x32_bf16 v[84:87], v[154:157], v[198:201], v[84:87]
	v_mfma_f32_16x16x32_bf16 v[76:79], v[166:169], v[198:201], v[76:79]
	v_mfma_f32_16x16x32_bf16 v[112:115], v[202:205], v[170:173], v[112:115]
	v_mfma_f32_16x16x32_bf16 v[104:107], v[210:213], v[170:173], v[104:107]
	v_mfma_f32_16x16x32_bf16 v[96:99], v[202:205], v[178:181], v[96:99]
	v_mfma_f32_16x16x32_bf16 v[88:91], v[210:213], v[178:181], v[88:91]
	v_mfma_f32_16x16x32_bf16 v[80:83], v[202:205], v[186:189], v[80:83]
	v_mfma_f32_16x16x32_bf16 v[72:75], v[210:213], v[186:189], v[72:75]
	v_mfma_f32_16x16x32_bf16 v[68:71], v[202:205], v[194:197], v[68:71]
	v_mfma_f32_16x16x32_bf16 v[64:67], v[210:213], v[194:197], v[64:67]
	v_mfma_f32_16x16x32_bf16 v[112:115], v[206:209], v[174:177], v[112:115]
	v_mfma_f32_16x16x32_bf16 v[104:107], v[214:217], v[174:177], v[104:107]
	v_mfma_f32_16x16x32_bf16 v[96:99], v[206:209], v[182:185], v[96:99]
	v_mfma_f32_16x16x32_bf16 v[88:91], v[214:217], v[182:185], v[88:91]
	v_mfma_f32_16x16x32_bf16 v[80:83], v[206:209], v[190:193], v[80:83]
	v_mfma_f32_16x16x32_bf16 v[72:75], v[214:217], v[190:193], v[72:75]
	v_mfma_f32_16x16x32_bf16 v[68:71], v[206:209], v[198:201], v[68:71]
	v_mfma_f32_16x16x32_bf16 v[64:67], v[214:217], v[198:201], v[64:67]
	s_barrier
	ds_read_b128 v[170:173], v163 offset:16384
	ds_read_b128 v[174:177], v163 offset:17408
	ds_read_b128 v[178:181], v163 offset:18432
	ds_read_b128 v[182:185], v163 offset:19456
	ds_read_b128 v[186:189], v163 offset:20480
	ds_read_b128 v[190:193], v163 offset:21504
	ds_read_b128 v[194:197], v163 offset:22528
	ds_read_b128 v[198:201], v163 offset:23552
	s_add_i32 s45, s66, s21
	v_lshl_add_u64 v[218:219], s[54:55], 0, v[138:139]
	s_mov_b32 m0, s45
	s_nop 0
	global_load_lds_dwordx4 v[218:219], off
	v_lshl_add_u64 v[220:221], s[54:55], 0, v[142:143]
	s_add_i32 m0, s45, 0x2000
	s_nop 0
	global_load_lds_dwordx4 v[220:221], off
	s_mov_b32 m0, s33
	v_lshl_add_u64 v[222:223], s[56:57], 0, v[136:137]
	global_load_lds_dwordx4 v[222:223], off
	v_lshl_add_u64 v[224:225], s[56:57], 0, v[140:141]
	s_mov_b32 m0, s35
	s_nop 0
	global_load_lds_dwordx4 v[224:225], off
	s_add_u32 s78, s54, 0x40000
	s_addc_u32 s79, s55, 0
	s_add_i32 s45, s67, s21
	v_lshl_add_u64 v[240:241], s[78:79], 0, v[138:139]
	s_mov_b32 m0, s45
	s_nop 0
	global_load_lds_dwordx4 v[240:241], off
	v_lshl_add_u64 v[240:241], s[78:79], 0, v[142:143]
	s_add_i32 m0, s45, 0x2000
	s_nop 0
	global_load_lds_dwordx4 v[240:241], off
	s_waitcnt vmcnt(8) lgkmcnt(0)
	s_barrier
; #define PG8_STAGE(bufoff, gbase, voff) do { _Pragma("unroll") for (int _i = 0; _i < 2; ++_i) \
;         __builtin_amdgcn_global_load_lds((const unsigned*)((const char*)(gbase) + (voff)[_i]), (LAS unsigned*)(lds + (bufoff) + ldsw + _i * 8192), 16, 0, 0); } while (0)
; #define PG8_LDA(dst, b, h) do { _Pragma("unroll") for (int m = 0; m < 4; ++m) _Pragma("unroll") for (int k = 0; k < 2; ++k) dst[m][k] = *(const LAS bf16x8*)(lds + PG8_SA(b, h) + aoff + m * 2048 + k * 1024); } while (0)
; #define PG8_LDB(dst, b, h) do { _Pragma("unroll") for (int n = 0; n < 2; ++n) _Pragma("unroll") for (int k = 0; k < 2; ++k) dst[n][k] = *(const LAS bf16x8*)(lds + PG8_SB(b, h) + boff + n * 2048 + k * 1024); } while (0)
; #define PG8_MMA(ai, bj, At, Bt) do { __builtin_amdgcn_s_setprio(1); _Pragma("unroll") for (int m = 0; m < 4; ++m) _Pragma("unroll") for (int n = 0; n < 2; ++n) _Pragma("unroll") for (int k = 0; k < 2; ++k) \
;         acc[ai][bj][m][n] = __builtin_amdgcn_mfma_f32_16x16x32_bf16(Bt[n][k], At[m][k], acc[ai][bj][m][n], 0, 0, 0); __builtin_amdgcn_s_setprio(0); } while (0)
; #define PG8_WAIT_V(n) asm volatile("s_waitcnt vmcnt(" #n ")" ::: "memory")
; #define PG8_WAIT_L(n) asm volatile("s_waitcnt lgkmcnt(" #n ")" ::: "memory")
; #define PG8_BAR __builtin_amdgcn_s_barrier()
; #define PG8_SCHED __builtin_amdgcn_sched_barrier(0)
; template <class Epi>
; __device__ __forceinline__ void gemm_phase(LAS unsigned char* lds, const Gemm g, const StaticOrder& S, const Epi& E) {
;     ...
;             PG8_BAR; PG8_WAIT_L(0); PG8_MMA(1, 0, At, B0); PG8_BAR; PG8_SCHED;
;             PG8_STAGE(PG8_SB(0, 1), b2 + hstepB, voffB);
;             PG8_WAIT_V(6); PG8_BAR; PG8_MMA(1, 1, At, B1); PG8_BAR;
;             PG8_LDB(B0, 1, 0); PG8_SCHED; PG8_LDA(At, 1, 0); PG8_STAGE(PG8_SA(0, 1), a2 + hstepA, voffA);
;             PG8_WAIT_L(8); PG8_BAR; PG8_WAIT_L(0); PG8_MMA(0, 0, At, B0); PG8_BAR; PG8_SCHED;
;             PG8_LDB(B1, 1, 1); PG8_STAGE(PG8_SB(1, 0), b3, voffB);
;             PG8_BAR; PG8_WAIT_L(0); PG8_MMA(0, 1, At, B1); PG8_BAR;
	v_mfma_f32_16x16x32_bf16 v[60:63], v[150:153], v[170:173], v[60:63]
	v_mfma_f32_16x16x32_bf16 v[56:59], v[158:161], v[170:173], v[56:59]
	v_mfma_f32_16x16x32_bf16 v[52:55], v[150:153], v[178:181], v[52:55]
	v_mfma_f32_16x16x32_bf16 v[44:47], v[158:161], v[178:181], v[44:47]
	v_mfma_f32_16x16x32_bf16 v[36:39], v[150:153], v[186:189], v[36:39]
	v_mfma_f32_16x16x32_bf16 v[28:31], v[158:161], v[186:189], v[28:31]
	v_mfma_f32_16x16x32_bf16 v[20:23], v[150:153], v[194:197], v[20:23]
	v_mfma_f32_16x16x32_bf16 v[12:15], v[158:161], v[194:197], v[12:15]
	v_mfma_f32_16x16x32_bf16 v[60:63], v[154:157], v[174:177], v[60:63]
	v_mfma_f32_16x16x32_bf16 v[56:59], v[166:169], v[174:177], v[56:59]
	v_mfma_f32_16x16x32_bf16 v[52:55], v[154:157], v[182:185], v[52:55]
	v_mfma_f32_16x16x32_bf16 v[44:47], v[166:169], v[182:185], v[44:47]
	v_mfma_f32_16x16x32_bf16 v[36:39], v[154:157], v[190:193], v[36:39]
	v_mfma_f32_16x16x32_bf16 v[28:31], v[166:169], v[190:193], v[28:31]
	v_mfma_f32_16x16x32_bf16 v[20:23], v[154:157], v[198:201], v[20:23]
	v_mfma_f32_16x16x32_bf16 v[12:15], v[166:169], v[198:201], v[12:15]
	v_mfma_f32_16x16x32_bf16 v[48:51], v[202:205], v[170:173], v[48:51]
	v_mfma_f32_16x16x32_bf16 v[40:43], v[210:213], v[170:173], v[40:43]
	v_mfma_f32_16x16x32_bf16 v[32:35], v[202:205], v[178:181], v[32:35]
	v_mfma_f32_16x16x32_bf16 v[24:27], v[210:213], v[178:181], v[24:27]
	v_mfma_f32_16x16x32_bf16 v[16:19], v[202:205], v[186:189], v[16:19]
	v_mfma_f32_16x16x32_bf16 v[8:11], v[210:213], v[186:189], v[8:11]
	v_mfma_f32_16x16x32_bf16 v[4:7], v[202:205], v[194:197], v[4:7]
	v_mfma_f32_16x16x32_bf16 v[0:3], v[210:213], v[194:197], v[0:3]
	v_mfma_f32_16x16x32_bf16 v[48:51], v[206:209], v[174:177], v[48:51]
	v_mfma_f32_16x16x32_bf16 v[40:43], v[214:217], v[174:177], v[40:43]
	v_mfma_f32_16x16x32_bf16 v[32:35], v[206:209], v[182:185], v[32:35]
	v_mfma_f32_16x16x32_bf16 v[24:27], v[214:217], v[182:185], v[24:27]
	v_mfma_f32_16x16x32_bf16 v[16:19], v[206:209], v[190:193], v[16:19]
	v_mfma_f32_16x16x32_bf16 v[8:11], v[214:217], v[190:193], v[8:11]
	v_mfma_f32_16x16x32_bf16 v[4:7], v[206:209], v[198:201], v[4:7]
	v_mfma_f32_16x16x32_bf16 v[0:3], v[214:217], v[198:201], v[0:3]
	s_barrier
	s_add_i32 s45, 0, 0x18000
	v_add_u32_e32 v165, s45, v135
	ds_read_b128 v[150:153], v165
	ds_read_b128 v[154:157], v165 offset:1024
	ds_read_b128 v[158:161], v165 offset:2048
	ds_read_b128 v[166:169], v165 offset:3072
	ds_read_b128 v[170:173], v163 offset:32768
	ds_read_b128 v[174:177], v163 offset:33792
	ds_read_b128 v[178:181], v163 offset:34816
	ds_read_b128 v[182:185], v163 offset:35840
	ds_read_b128 v[186:189], v163 offset:36864
	ds_read_b128 v[190:193], v163 offset:37888
	ds_read_b128 v[194:197], v163 offset:38912
	ds_read_b128 v[198:201], v163 offset:39936
	s_add_i32 s98, 0, 0x1c000
	v_add_u32_e32 v246, s98, v135
	ds_read_b128 v[202:205], v246
	ds_read_b128 v[206:209], v246 offset:1024
	ds_read_b128 v[210:213], v246 offset:2048
	ds_read_b128 v[214:217], v246 offset:3072
	s_add_u32 s56, s56, 0x40000
	s_addc_u32 s57, s57, 0
	s_mov_b32 m0, s58
	v_lshl_add_u64 v[244:245], s[56:57], 0, v[136:137]
	global_load_lds_dwordx4 v[244:245], off
	v_lshl_add_u64 v[244:245], s[56:57], 0, v[140:141]
	s_mov_b32 m0, s59
	s_nop 0
	global_load_lds_dwordx4 v[244:245], off
	s_waitcnt vmcnt(8) lgkmcnt(0)
	s_barrier
	v_mfma_f32_16x16x32_bf16 v[124:127], v[150:153], v[170:173], v[124:127]
	v_mfma_f32_16x16x32_bf16 v[120:123], v[158:161], v[170:173], v[120:123]
	v_mfma_f32_16x16x32_bf16 v[116:119], v[150:153], v[178:181], v[116:119]
	v_mfma_f32_16x16x32_bf16 v[108:111], v[158:161], v[178:181], v[108:111]
	v_mfma_f32_16x16x32_bf16 v[100:103], v[150:153], v[186:189], v[100:103]
	v_mfma_f32_16x16x32_bf16 v[92:95], v[158:161], v[186:189], v[92:95]
	v_mfma_f32_16x16x32_bf16 v[84:87], v[150:153], v[194:197], v[84:87]
	v_mfma_f32_16x16x32_bf16 v[76:79], v[158:161], v[194:197], v[76:79]
	v_mfma_f32_16x16x32_bf16 v[124:127], v[154:157], v[174:177], v[124:127]
	v_mfma_f32_16x16x32_bf16 v[120:123], v[166:169], v[174:177], v[120:123]
	v_mfma_f32_16x16x32_bf16 v[116:119], v[154:157], v[182:185], v[116:119]
	v_mfma_f32_16x16x32_bf16 v[108:111], v[166:169], v[182:185], v[108:111]
	v_mfma_f32_16x16x32_bf16 v[100:103], v[154:157], v[190:193], v[100:103]
	v_mfma_f32_16x16x32_bf16 v[92:95], v[166:169], v[190:193], v[92:95]
	v_mfma_f32_16x16x32_bf16 v[84:87], v[154:157], v[198:201], v[84:87]
	v_mfma_f32_16x16x32_bf16 v[76:79], v[166:169], v[198:201], v[76:79]
	v_mfma_f32_16x16x32_bf16 v[112:115], v[202:205], v[170:173], v[112:115]
	v_mfma_f32_16x16x32_bf16 v[104:107], v[210:213], v[170:173], v[104:107]
	v_mfma_f32_16x16x32_bf16 v[96:99], v[202:205], v[178:181], v[96:99]
	v_mfma_f32_16x16x32_bf16 v[88:91], v[210:213], v[178:181], v[88:91]
	v_mfma_f32_16x16x32_bf16 v[80:83], v[202:205], v[186:189], v[80:83]
	v_mfma_f32_16x16x32_bf16 v[72:75], v[210:213], v[186:189], v[72:75]
	v_mfma_f32_16x16x32_bf16 v[68:71], v[202:205], v[194:197], v[68:71]
	v_mfma_f32_16x16x32_bf16 v[64:67], v[210:213], v[194:197], v[64:67]
	v_mfma_f32_16x16x32_bf16 v[112:115], v[206:209], v[174:177], v[112:115]
	v_mfma_f32_16x16x32_bf16 v[104:107], v[214:217], v[174:177], v[104:107]
	v_mfma_f32_16x16x32_bf16 v[96:99], v[206:209], v[182:185], v[96:99]
	v_mfma_f32_16x16x32_bf16 v[88:91], v[214:217], v[182:185], v[88:91]
	v_mfma_f32_16x16x32_bf16 v[80:83], v[206:209], v[190:193], v[80:83]
	v_mfma_f32_16x16x32_bf16 v[72:75], v[214:217], v[190:193], v[72:75]
	v_mfma_f32_16x16x32_bf16 v[68:71], v[206:209], v[198:201], v[68:71]
	v_mfma_f32_16x16x32_bf16 v[64:67], v[214:217], v[198:201], v[64:67]
	s_barrier
; #define PG8_STAGE(bufoff, gbase, voff) do { _Pragma("unroll") for (int _i = 0; _i < 2; ++_i) \
;         __builtin_amdgcn_global_load_lds((const unsigned*)((const char*)(gbase) + (voff)[_i]), (LAS unsigned*)(lds + (bufoff) + ldsw + _i * 8192), 16, 0, 0); } while (0)
; #define PG8_LDA(dst, b, h) do { _Pragma("unroll") for (int m = 0; m < 4; ++m) _Pragma("unroll") for (int k = 0; k < 2; ++k) dst[m][k] = *(const LAS bf16x8*)(lds + PG8_SA(b, h) + aoff + m * 2048 + k * 1024); } while (0)
; #define PG8_MMA(ai, bj, At, Bt) do { __builtin_amdgcn_s_setprio(1); _Pragma("unroll") for (int m = 0; m < 4; ++m) _Pragma("unroll") for (int n = 0; n < 2; ++n) _Pragma("unroll") for (int k = 0; k < 2; ++k) \
;         acc[ai][bj][m][n] = __builtin_amdgcn_mfma_f32_16x16x32_bf16(Bt[n][k], At[m][k], acc[ai][bj][m][n], 0, 0, 0); __builtin_amdgcn_s_setprio(0); } while (0)
; #define PG8_WAIT_V(n) asm volatile("s_waitcnt vmcnt(" #n ")" ::: "memory")
; #define PG8_WAIT_L(n) asm volatile("s_waitcnt lgkmcnt(" #n ")" ::: "memory")
; #define PG8_BAR __builtin_amdgcn_s_barrier()
; #define PG8_SCHED __builtin_amdgcn_sched_barrier(0)
;     __device__ __forceinline__ void operator()(const f32x4 (&acc)[2][2][4][2], const Unit& u, int wr, int wc, int fr, int fq) const {
;     ...
;         if (u.part) {
;             float* base = tailacc + (size_t)(u.part - 1) * slab - (size_t)tail_row0 * tail_ld;
; #pragma unroll
;             for (int ai = 0; ai < 2; ++ai)
; #pragma unroll
;                 for (int m = 0; m < 4; ++m) { float* rowp = base + (size_t)(row0 + ai * HALF + m * 16) * tail_ld + col0;
; #pragma unroll
;                     for (int bj = 0; bj < 2; ++bj)
; #pragma unroll
;                         for (int n = 0; n < 2; ++n) *(f32x4*)(rowp + bj * HALF + 4 * n) = acc[ai][bj][m][n]; }
;             return;
; template <class Epi>
; __device__ __forceinline__ void gemm_phase(LAS unsigned char* lds, const Gemm g, const StaticOrder& S, const Epi& E) {
;     ...
;             PG8_LDA(At, 1, 1); PG8_STAGE(PG8_SA(1, 0), a3, voffA);
;             PG8_BAR; PG8_WAIT_L(0); PG8_MMA(1, 0, At, B0); PG8_BAR; PG8_SCHED;
;             PG8_STAGE(PG8_SB(1, 1), b3 + hstepB, voffB);
;             PG8_WAIT_V(6); PG8_BAR; PG8_MMA(1, 1, At, B1); PG8_BAR;
	ds_read_b128 v[170:173], v163 offset:49152
	ds_read_b128 v[174:177], v163 offset:50176
	ds_read_b128 v[178:181], v163 offset:51200
	ds_read_b128 v[182:185], v163 offset:52224
	ds_read_b128 v[186:189], v163 offset:53248
	ds_read_b128 v[190:193], v163 offset:54272
	ds_read_b128 v[194:197], v163 offset:55296
	ds_read_b128 v[198:201], v163 offset:56320
	s_add_i32 s45, s45, s21
	v_lshl_add_u64 v[218:219], v[218:219], 0, s[12:13]
	s_mov_b32 m0, s45
	s_nop 0
	global_load_lds_dwordx4 v[218:219], off
	v_lshl_add_u64 v[218:219], v[220:221], 0, s[12:13]
	s_add_i32 m0, s45, 0x2000
	s_nop 0
	global_load_lds_dwordx4 v[218:219], off
	s_mov_b32 m0, s60
	v_lshl_add_u64 v[218:219], v[222:223], 0, s[12:13]
	global_load_lds_dwordx4 v[218:219], off
	v_lshl_add_u64 v[218:219], v[224:225], 0, s[12:13]
	s_mov_b32 m0, s61
	s_nop 0
	global_load_lds_dwordx4 v[218:219], off
	s_add_u32 s54, s54, 0x40080
	s_addc_u32 s55, s55, 0
	s_add_i32 s45, s98, s21
	v_lshl_add_u64 v[240:241], s[54:55], 0, v[138:139]
	s_mov_b32 m0, s45
	s_nop 0
	global_load_lds_dwordx4 v[240:241], off
	v_lshl_add_u64 v[240:241], s[54:55], 0, v[142:143]
	s_add_i32 m0, s45, 0x2000
	s_nop 0
	global_load_lds_dwordx4 v[240:241], off
	s_waitcnt vmcnt(8) lgkmcnt(0)
	s_barrier
	v_mfma_f32_16x16x32_bf16 v[60:63], v[150:153], v[170:173], v[60:63]
	v_mfma_f32_16x16x32_bf16 v[56:59], v[158:161], v[170:173], v[56:59]
	v_mfma_f32_16x16x32_bf16 v[52:55], v[150:153], v[178:181], v[52:55]
	v_mfma_f32_16x16x32_bf16 v[44:47], v[158:161], v[178:181], v[44:47]
	v_mfma_f32_16x16x32_bf16 v[36:39], v[150:153], v[186:189], v[36:39]
	v_mfma_f32_16x16x32_bf16 v[28:31], v[158:161], v[186:189], v[28:31]
	v_mfma_f32_16x16x32_bf16 v[20:23], v[150:153], v[194:197], v[20:23]
	v_mfma_f32_16x16x32_bf16 v[12:15], v[158:161], v[194:197], v[12:15]
	v_mfma_f32_16x16x32_bf16 v[60:63], v[154:157], v[174:177], v[60:63]
	v_mfma_f32_16x16x32_bf16 v[56:59], v[166:169], v[174:177], v[56:59]
	v_mfma_f32_16x16x32_bf16 v[52:55], v[154:157], v[182:185], v[52:55]
	v_mfma_f32_16x16x32_bf16 v[44:47], v[166:169], v[182:185], v[44:47]
	v_mfma_f32_16x16x32_bf16 v[36:39], v[154:157], v[190:193], v[36:39]
	v_mfma_f32_16x16x32_bf16 v[28:31], v[166:169], v[190:193], v[28:31]
	v_mfma_f32_16x16x32_bf16 v[20:23], v[154:157], v[198:201], v[20:23]
	v_mfma_f32_16x16x32_bf16 v[12:15], v[166:169], v[198:201], v[12:15]
	v_mfma_f32_16x16x32_bf16 v[48:51], v[202:205], v[170:173], v[48:51]
	v_mfma_f32_16x16x32_bf16 v[40:43], v[210:213], v[170:173], v[40:43]
	v_mfma_f32_16x16x32_bf16 v[32:35], v[202:205], v[178:181], v[32:35]
	v_mfma_f32_16x16x32_bf16 v[24:27], v[210:213], v[178:181], v[24:27]
	v_mfma_f32_16x16x32_bf16 v[16:19], v[202:205], v[186:189], v[16:19]
	v_mfma_f32_16x16x32_bf16 v[8:11], v[210:213], v[186:189], v[8:11]
	v_mfma_f32_16x16x32_bf16 v[4:7], v[202:205], v[194:197], v[4:7]
	v_mfma_f32_16x16x32_bf16 v[0:3], v[210:213], v[194:197], v[0:3]
	v_mfma_f32_16x16x32_bf16 v[48:51], v[206:209], v[174:177], v[48:51]
	v_mfma_f32_16x16x32_bf16 v[40:43], v[214:217], v[174:177], v[40:43]
	v_mfma_f32_16x16x32_bf16 v[32:35], v[206:209], v[182:185], v[32:35]
	v_mfma_f32_16x16x32_bf16 v[24:27], v[214:217], v[182:185], v[24:27]
	v_mfma_f32_16x16x32_bf16 v[16:19], v[206:209], v[190:193], v[16:19]
	v_mfma_f32_16x16x32_bf16 v[8:11], v[214:217], v[190:193], v[8:11]
	v_mfma_f32_16x16x32_bf16 v[4:7], v[206:209], v[198:201], v[4:7]
	v_mfma_f32_16x16x32_bf16 v[0:3], v[214:217], v[198:201], v[0:3]
	s_add_u32 s50, s50, 0x100
	s_addc_u32 s51, s51, 0
	s_add_u32 s41, s41, 0x100
	s_addc_u32 s43, s43, 0
	s_cmp_ge_i32 s77, s76
	s_mov_b32 s45, s77
	s_barrier
	s_cbranch_scc0 .LBB0_1146
	v_lshl_add_u32 v150, s8, 8, v133
	v_lshl_or_b32 v154, s44, 8, v162
	s_cmp_lg_u32 s75, 0
	v_ashrrev_i32_e32 v155, 31, v154
	v_or_b32_e32 v160, 16, v150
	v_or_b32_e32 v158, 32, v150
	v_or_b32_e32 v156, 48, v150
	s_cbranch_scc0 .LBB0_1149
	s_add_i32 s8, s75, -1
	s_lshl_b64 s[44:45], s[8:9], 21
	s_add_u32 s44, s92, s44
	s_addc_u32 s45, s93, s45
	v_lshl_add_u64 v[152:153], v[154:155], 2, s[44:45]
	v_ashrrev_i32_e32 v151, 31, v150
	v_ashrrev_i32_e32 v161, 31, v160
	v_lshl_add_u64 v[152:153], v[152:153], 0, s[22:23]
	v_lshlrev_b64 v[166:167], 12, v[150:151]
	v_lshlrev_b64 v[168:169], 12, v[160:161]
	v_lshl_add_u64 v[166:167], v[152:153], 0, v[166:167]
	v_lshl_add_u64 v[168:169], v[152:153], 0, v[168:169]
	v_ashrrev_i32_e32 v159, 31, v158
	global_store_dwordx4 v[166:167], v[124:127], off
	global_store_dwordx4 v[166:167], v[120:123], off offset:16
	global_store_dwordx4 v[166:167], v[112:115], off offset:512
	global_store_dwordx4 v[166:167], v[104:107], off offset:528
	global_store_dwordx4 v[168:169], v[116:119], off
	global_store_dwordx4 v[168:169], v[108:111], off offset:16
	global_store_dwordx4 v[168:169], v[96:99], off offset:512
	global_store_dwordx4 v[168:169], v[88:91], off offset:528
	v_lshlrev_b64 v[168:169], 12, v[158:159]
	v_lshl_add_u64 v[168:169], v[152:153], 0, v[168:169]
	v_ashrrev_i32_e32 v157, 31, v156
	global_store_dwordx4 v[168:169], v[100:103], off
	global_store_dwordx4 v[168:169], v[92:95], off offset:16
	global_store_dwordx4 v[168:169], v[80:83], off offset:512
	global_store_dwordx4 v[168:169], v[72:75], off offset:528
	v_lshlrev_b64 v[168:169], 12, v[156:157]
	v_lshl_add_u64 v[152:153], v[152:153], 0, v[168:169]
	v_add_co_u32_e32 v168, vcc, s68, v166
	global_store_dwordx4 v[152:153], v[84:87], off
	global_store_dwordx4 v[152:153], v[76:79], off offset:16
	global_store_dwordx4 v[152:153], v[68:71], off offset:512
	global_store_dwordx4 v[152:153], v[64:67], off offset:528
	v_addc_co_u32_e32 v169, vcc, 0, v167, vcc
	v_lshl_add_u64 v[152:153], v[166:167], 0, s[24:25]
	global_store_dwordx4 v[168:169], v[60:63], off
	global_store_dwordx4 v[152:153], v[56:59], off offset:16
	global_store_dwordx4 v[152:153], v[48:51], off offset:512
	global_store_dwordx4 v[152:153], v[40:43], off offset:528
	v_add_co_u32_e32 v168, vcc, s69, v166
	v_lshl_add_u64 v[152:153], v[166:167], 0, s[26:27]
	s_nop 0
	v_addc_co_u32_e32 v169, vcc, 0, v167, vcc
	global_store_dwordx4 v[168:169], v[52:55], off
	global_store_dwordx4 v[152:153], v[44:47], off offset:16
	global_store_dwordx4 v[152:153], v[32:35], off offset:512
	global_store_dwordx4 v[152:153], v[24:27], off offset:528
	v_add_co_u32_e32 v168, vcc, s70, v166
	v_lshl_add_u64 v[152:153], v[166:167], 0, s[28:29]
	s_nop 0
	v_addc_co_u32_e32 v169, vcc, 0, v167, vcc
	global_store_dwordx4 v[168:169], v[36:39], off
	global_store_dwordx4 v[152:153], v[28:31], off offset:16
	global_store_dwordx4 v[152:153], v[16:19], off offset:512
	global_store_dwordx4 v[152:153], v[8:11], off offset:528
	v_lshl_add_u64 v[152:153], v[166:167], 0, s[36:37]
	v_add_co_u32_e32 v166, vcc, 0xb0000, v166
	s_nop 1
	v_addc_co_u32_e32 v167, vcc, 0, v167, vcc
	global_store_dwordx4 v[166:167], v[20:23], off
	global_store_dwordx4 v[152:153], v[12:15], off offset:16
	global_store_dwordx4 v[152:153], v[4:7], off offset:512
	global_store_dwordx4 v[152:153], v[0:3], off offset:528
	s_cbranch_execnz .LBB0_1131
	s_branch .LBB0_1130
